# GEMM K loops: one static s_setprio 1 for waves 4-7 at loop entry, per-cluster priority flips deleted
# speedup vs baseline: 1.0047x; 1.0042x over previous
.LBB0_214:
	s_ashr_i32 s19, s18, 31
	s_lshl_b64 s[20:21], s[18:19], 19
	s_add_u32 s20, s62, s20
	s_addc_u32 s21, s63, s21
	s_and_b64 s[34:35], s[2:3], exec
	s_cselect_b32 s19, s21, s55
	s_cselect_b32 s86, s20, s54
	s_ashr_i32 s15, s14, 31
	s_lshl_b64 s[34:35], s[14:15], 19
	s_add_u32 s34, s26, s34
	s_addc_u32 s35, s27, s35
	s_and_b64 s[60:61], s[2:3], exec
	s_cselect_b32 s15, s35, s59
	s_cselect_b32 s87, s34, s58
	s_add_u32 s54, s54, 0x40080
	s_addc_u32 s55, s55, 0
	s_add_u32 s88, s58, 0x100
	s_addc_u32 s89, s59, 0
	s_mov_b32 s90, -2
	v_mov_b64_e32 v[0:1], 0
	v_mov_b64_e32 v[2:3], 0
	v_mov_b64_e32 v[4:5], 0
	v_mov_b64_e32 v[6:7], 0
	v_mov_b64_e32 v[8:9], 0
	v_mov_b64_e32 v[10:11], 0
	v_mov_b64_e32 v[12:13], 0
	v_mov_b64_e32 v[14:15], 0
	v_mov_b64_e32 v[16:17], 0
	v_mov_b64_e32 v[18:19], 0
	v_mov_b64_e32 v[20:21], 0
	v_mov_b64_e32 v[22:23], 0
	v_mov_b64_e32 v[24:25], 0
	v_mov_b64_e32 v[26:27], 0
	v_mov_b64_e32 v[28:29], 0
	v_mov_b64_e32 v[30:31], 0
	v_mov_b64_e32 v[32:33], 0
	v_mov_b64_e32 v[34:35], 0
	v_mov_b64_e32 v[36:37], 0
	v_mov_b64_e32 v[38:39], 0
	v_mov_b64_e32 v[40:41], 0
	v_mov_b64_e32 v[42:43], 0
	v_mov_b64_e32 v[44:45], 0
	v_mov_b64_e32 v[46:47], 0
	v_mov_b64_e32 v[48:49], 0
	v_mov_b64_e32 v[50:51], 0
	v_mov_b64_e32 v[52:53], 0
	v_mov_b64_e32 v[54:55], 0
	v_mov_b64_e32 v[56:57], 0
	v_mov_b64_e32 v[58:59], 0
	v_mov_b64_e32 v[60:61], 0
	v_mov_b64_e32 v[62:63], 0
	v_mov_b64_e32 v[64:65], 0
	v_mov_b64_e32 v[66:67], 0
	v_mov_b64_e32 v[68:69], 0
	v_mov_b64_e32 v[70:71], 0
	v_mov_b64_e32 v[72:73], 0
	v_mov_b64_e32 v[74:75], 0
	v_mov_b64_e32 v[76:77], 0
	v_mov_b64_e32 v[78:79], 0
	v_mov_b64_e32 v[80:81], 0
	v_mov_b64_e32 v[82:83], 0
	v_mov_b64_e32 v[84:85], 0
	v_mov_b64_e32 v[86:87], 0
	v_mov_b64_e32 v[88:89], 0
	v_mov_b64_e32 v[90:91], 0
	v_mov_b64_e32 v[92:93], 0
	v_mov_b64_e32 v[94:95], 0
	v_mov_b64_e32 v[96:97], 0
	v_mov_b64_e32 v[98:99], 0
	v_mov_b64_e32 v[100:101], 0
	v_mov_b64_e32 v[102:103], 0
	v_mov_b64_e32 v[104:105], 0
	v_mov_b64_e32 v[106:107], 0
	v_mov_b64_e32 v[108:109], 0
	v_mov_b64_e32 v[110:111], 0
	v_mov_b64_e32 v[112:113], 0
	v_mov_b64_e32 v[114:115], 0
	v_mov_b64_e32 v[116:117], 0
	v_mov_b64_e32 v[118:119], 0
	v_mov_b64_e32 v[120:121], 0
	v_mov_b64_e32 v[122:123], 0
	v_mov_b64_e32 v[124:125], 0
	v_mov_b64_e32 v[126:127], 0
	v_lshrrev_b32_e32 v253, 8, v200
	s_nop 0
	v_readfirstlane_b32 s98, v253
	s_cmp_lg_u32 s98, 0
	s_cbranch_scc0 .Lgp_215
	s_setprio 1
.Lgp_215:
.LBB0_215:
	ds_read_b128 v[144:147], v151
	ds_read_b128 v[154:157], v151 offset:1024
	ds_read_b128 v[158:161], v151 offset:2048
	ds_read_b128 v[162:165], v151 offset:3072
	ds_read_b128 v[166:169], v152
	ds_read_b128 v[170:173], v152 offset:1024
	ds_read_b128 v[174:177], v152 offset:2048
	ds_read_b128 v[178:181], v152 offset:3072
	s_add_u32 s58, s54, 0xfffc0080
	s_addc_u32 s59, s55, -1
	s_cmp_eq_u32 s90, 12
	s_cselect_b32 s61, s19, s59
	s_cselect_b32 s60, s86, s58
	s_cselect_b32 s59, s15, s89
	s_cselect_b32 s58, s87, s88
	v_lshl_add_u64 v[198:199], s[54:55], 0, v[136:137]
	s_add_i32 m0, s4, 0xc000
	ds_read_b128 v[182:185], v153
	ds_read_b128 v[186:189], v153 offset:1024
	ds_read_b128 v[190:193], v153 offset:2048
	ds_read_b128 v[194:197], v153 offset:3072
	ds_read_b128 v[202:205], v153 offset:4096
	ds_read_b128 v[206:209], v153 offset:5120
	ds_read_b128 v[210:213], v153 offset:6144
	ds_read_b128 v[214:217], v153 offset:7168
	global_load_lds_dwordx4 v[198:199], off
	v_lshl_add_u64 v[198:199], s[54:55], 0, v[138:139]
	s_add_i32 m0, s4, 0xe000
	s_nop 0
	global_load_lds_dwordx4 v[198:199], off
	s_waitcnt vmcnt(8)
	s_waitcnt lgkmcnt(0)
	s_barrier
	s_waitcnt lgkmcnt(0)
	v_mfma_f32_16x16x32_bf16 v[124:127], v[144:147], v[182:185], v[124:127]
	v_mfma_f32_16x16x32_bf16 v[120:123], v[158:161], v[182:185], v[120:123]
	v_mfma_f32_16x16x32_bf16 v[116:119], v[144:147], v[190:193], v[116:119]
	v_mfma_f32_16x16x32_bf16 v[108:111], v[158:161], v[190:193], v[108:111]
	v_mfma_f32_16x16x32_bf16 v[100:103], v[144:147], v[202:205], v[100:103]
	v_mfma_f32_16x16x32_bf16 v[92:95], v[158:161], v[202:205], v[92:95]
	v_mfma_f32_16x16x32_bf16 v[84:87], v[144:147], v[210:213], v[84:87]
	v_mfma_f32_16x16x32_bf16 v[76:79], v[158:161], v[210:213], v[76:79]
	v_mfma_f32_16x16x32_bf16 v[124:127], v[154:157], v[186:189], v[124:127]
	v_mfma_f32_16x16x32_bf16 v[120:123], v[162:165], v[186:189], v[120:123]
	v_mfma_f32_16x16x32_bf16 v[116:119], v[154:157], v[194:197], v[116:119]
	v_mfma_f32_16x16x32_bf16 v[108:111], v[162:165], v[194:197], v[108:111]
	v_mfma_f32_16x16x32_bf16 v[100:103], v[154:157], v[206:209], v[100:103]
	v_mfma_f32_16x16x32_bf16 v[92:95], v[162:165], v[206:209], v[92:95]
	v_mfma_f32_16x16x32_bf16 v[84:87], v[154:157], v[214:217], v[84:87]
	v_mfma_f32_16x16x32_bf16 v[76:79], v[162:165], v[214:217], v[76:79]
	v_mfma_f32_16x16x32_bf16 v[112:115], v[166:169], v[182:185], v[112:115]
	v_mfma_f32_16x16x32_bf16 v[104:107], v[174:177], v[182:185], v[104:107]
	v_mfma_f32_16x16x32_bf16 v[96:99], v[166:169], v[190:193], v[96:99]
	v_mfma_f32_16x16x32_bf16 v[88:91], v[174:177], v[190:193], v[88:91]
	v_mfma_f32_16x16x32_bf16 v[80:83], v[166:169], v[202:205], v[80:83]
	v_mfma_f32_16x16x32_bf16 v[72:75], v[174:177], v[202:205], v[72:75]
	v_mfma_f32_16x16x32_bf16 v[68:71], v[166:169], v[210:213], v[68:71]
	v_mfma_f32_16x16x32_bf16 v[64:67], v[174:177], v[210:213], v[64:67]
	v_mfma_f32_16x16x32_bf16 v[112:115], v[170:173], v[186:189], v[112:115]
	v_mfma_f32_16x16x32_bf16 v[104:107], v[178:181], v[186:189], v[104:107]
	v_mfma_f32_16x16x32_bf16 v[96:99], v[170:173], v[194:197], v[96:99]
	v_mfma_f32_16x16x32_bf16 v[88:91], v[178:181], v[194:197], v[88:91]
	v_mfma_f32_16x16x32_bf16 v[80:83], v[170:173], v[206:209], v[80:83]
	v_mfma_f32_16x16x32_bf16 v[72:75], v[178:181], v[206:209], v[72:75]
	v_mfma_f32_16x16x32_bf16 v[68:71], v[170:173], v[214:217], v[68:71]
	v_mfma_f32_16x16x32_bf16 v[64:67], v[178:181], v[214:217], v[64:67]
	s_barrier
	s_add_i32 s91, s17, s66
	v_lshl_add_u64 v[198:199], s[58:59], 0, v[132:133]
	s_mov_b32 m0, s91
	ds_read_b128 v[182:185], v153 offset:16384
	ds_read_b128 v[186:189], v153 offset:17408
	ds_read_b128 v[190:193], v153 offset:18432
	ds_read_b128 v[194:197], v153 offset:19456
	ds_read_b128 v[202:205], v153 offset:20480
	ds_read_b128 v[206:209], v153 offset:21504
	ds_read_b128 v[210:213], v153 offset:22528
	ds_read_b128 v[214:217], v153 offset:23552
	global_load_lds_dwordx4 v[198:199], off
	s_add_i32 m0, s91, 0x2000
	s_add_u32 s92, s58, 0x40000
	v_lshl_add_u64 v[218:219], s[58:59], 0, v[128:129]
	s_addc_u32 s93, s59, 0
	s_add_i32 s91, s80, s66
	global_load_lds_dwordx4 v[218:219], off
	v_lshl_add_u64 v[220:221], s[92:93], 0, v[132:133]
	s_mov_b32 m0, s91
	v_lshl_add_u64 v[222:223], s[60:61], 0, v[130:131]
	global_load_lds_dwordx4 v[220:221], off
	v_lshl_add_u64 v[220:221], s[92:93], 0, v[128:129]
	s_add_i32 m0, s91, 0x2000
	s_nop 0
	global_load_lds_dwordx4 v[220:221], off
	v_lshl_add_u64 v[220:221], s[60:61], 0, v[134:135]
	s_mov_b32 m0, s4
	s_nop 0
	global_load_lds_dwordx4 v[220:221], off
	s_mov_b32 m0, s67
	s_nop 0
	global_load_lds_dwordx4 v[222:223], off
	s_waitcnt vmcnt(8)
	s_waitcnt lgkmcnt(0)
	s_barrier
	s_waitcnt lgkmcnt(0)
	v_mfma_f32_16x16x32_bf16 v[60:63], v[144:147], v[182:185], v[60:63]
	v_mfma_f32_16x16x32_bf16 v[56:59], v[158:161], v[182:185], v[56:59]
	v_mfma_f32_16x16x32_bf16 v[52:55], v[144:147], v[190:193], v[52:55]
	v_mfma_f32_16x16x32_bf16 v[44:47], v[158:161], v[190:193], v[44:47]
	v_mfma_f32_16x16x32_bf16 v[36:39], v[144:147], v[202:205], v[36:39]
	v_mfma_f32_16x16x32_bf16 v[28:31], v[158:161], v[202:205], v[28:31]
	v_mfma_f32_16x16x32_bf16 v[20:23], v[144:147], v[210:213], v[20:23]
	v_mfma_f32_16x16x32_bf16 v[12:15], v[158:161], v[210:213], v[12:15]
	v_mfma_f32_16x16x32_bf16 v[60:63], v[154:157], v[186:189], v[60:63]
	v_mfma_f32_16x16x32_bf16 v[56:59], v[162:165], v[186:189], v[56:59]
	v_mfma_f32_16x16x32_bf16 v[52:55], v[154:157], v[194:197], v[52:55]
	v_mfma_f32_16x16x32_bf16 v[44:47], v[162:165], v[194:197], v[44:47]
	v_mfma_f32_16x16x32_bf16 v[36:39], v[154:157], v[206:209], v[36:39]
	v_mfma_f32_16x16x32_bf16 v[28:31], v[162:165], v[206:209], v[28:31]
	v_mfma_f32_16x16x32_bf16 v[20:23], v[154:157], v[214:217], v[20:23]
	v_mfma_f32_16x16x32_bf16 v[12:15], v[162:165], v[214:217], v[12:15]
	v_mfma_f32_16x16x32_bf16 v[48:51], v[166:169], v[182:185], v[48:51]
	v_mfma_f32_16x16x32_bf16 v[40:43], v[174:177], v[182:185], v[40:43]
	v_mfma_f32_16x16x32_bf16 v[32:35], v[166:169], v[190:193], v[32:35]
	v_mfma_f32_16x16x32_bf16 v[24:27], v[174:177], v[190:193], v[24:27]
	v_mfma_f32_16x16x32_bf16 v[16:19], v[166:169], v[202:205], v[16:19]
	v_mfma_f32_16x16x32_bf16 v[8:11], v[174:177], v[202:205], v[8:11]
	v_mfma_f32_16x16x32_bf16 v[4:7], v[166:169], v[210:213], v[4:7]
	v_mfma_f32_16x16x32_bf16 v[0:3], v[174:177], v[210:213], v[0:3]
	v_mfma_f32_16x16x32_bf16 v[48:51], v[170:173], v[186:189], v[48:51]
	v_mfma_f32_16x16x32_bf16 v[40:43], v[178:181], v[186:189], v[40:43]
	v_mfma_f32_16x16x32_bf16 v[32:35], v[170:173], v[194:197], v[32:35]
	v_mfma_f32_16x16x32_bf16 v[24:27], v[178:181], v[194:197], v[24:27]
	v_mfma_f32_16x16x32_bf16 v[16:19], v[170:173], v[206:209], v[16:19]
	v_mfma_f32_16x16x32_bf16 v[8:11], v[178:181], v[206:209], v[8:11]
	v_mfma_f32_16x16x32_bf16 v[4:7], v[170:173], v[214:217], v[4:7]
	v_mfma_f32_16x16x32_bf16 v[0:3], v[178:181], v[214:217], v[0:3]
	s_barrier
	s_add_i32 s91, 0, 0x18000
	s_add_i32 s92, 0, 0x1c000
	v_add_u32_e32 v162, s91, v149
	v_add_u32_e32 v178, s92, v149
	ds_read_b128 v[144:147], v162
	ds_read_b128 v[154:157], v162 offset:1024
	ds_read_b128 v[158:161], v162 offset:2048
	ds_read_b128 v[162:165], v162 offset:3072
	ds_read_b128 v[166:169], v178
	ds_read_b128 v[170:173], v178 offset:1024
	ds_read_b128 v[174:177], v178 offset:2048
	ds_read_b128 v[178:181], v178 offset:3072
	s_add_u32 s60, s60, 0x40000
	s_addc_u32 s61, s61, 0
	s_mov_b32 m0, s68
	v_lshl_add_u64 v[224:225], s[60:61], 0, v[134:135]
	ds_read_b128 v[182:185], v153 offset:32768
	ds_read_b128 v[186:189], v153 offset:33792
	ds_read_b128 v[190:193], v153 offset:34816
	ds_read_b128 v[194:197], v153 offset:35840
	ds_read_b128 v[202:205], v153 offset:36864
	ds_read_b128 v[206:209], v153 offset:37888
	ds_read_b128 v[210:213], v153 offset:38912
	ds_read_b128 v[214:217], v153 offset:39936
	global_load_lds_dwordx4 v[224:225], off
	v_lshl_add_u64 v[224:225], s[60:61], 0, v[130:131]
	s_mov_b32 m0, s69
	s_nop 0
	global_load_lds_dwordx4 v[224:225], off
	s_waitcnt vmcnt(8)
	s_waitcnt lgkmcnt(0)
	s_barrier
	s_waitcnt lgkmcnt(0)
	v_mfma_f32_16x16x32_bf16 v[124:127], v[144:147], v[182:185], v[124:127]
	v_mfma_f32_16x16x32_bf16 v[120:123], v[158:161], v[182:185], v[120:123]
	v_mfma_f32_16x16x32_bf16 v[116:119], v[144:147], v[190:193], v[116:119]
	v_mfma_f32_16x16x32_bf16 v[108:111], v[158:161], v[190:193], v[108:111]
	v_mfma_f32_16x16x32_bf16 v[100:103], v[144:147], v[202:205], v[100:103]
	v_mfma_f32_16x16x32_bf16 v[92:95], v[158:161], v[202:205], v[92:95]
	v_mfma_f32_16x16x32_bf16 v[84:87], v[144:147], v[210:213], v[84:87]
	v_mfma_f32_16x16x32_bf16 v[76:79], v[158:161], v[210:213], v[76:79]
	v_mfma_f32_16x16x32_bf16 v[124:127], v[154:157], v[186:189], v[124:127]
	v_mfma_f32_16x16x32_bf16 v[120:123], v[162:165], v[186:189], v[120:123]
	v_mfma_f32_16x16x32_bf16 v[116:119], v[154:157], v[194:197], v[116:119]
	v_mfma_f32_16x16x32_bf16 v[108:111], v[162:165], v[194:197], v[108:111]
	v_mfma_f32_16x16x32_bf16 v[100:103], v[154:157], v[206:209], v[100:103]
	v_mfma_f32_16x16x32_bf16 v[92:95], v[162:165], v[206:209], v[92:95]
	v_mfma_f32_16x16x32_bf16 v[84:87], v[154:157], v[214:217], v[84:87]
	v_mfma_f32_16x16x32_bf16 v[76:79], v[162:165], v[214:217], v[76:79]
	v_mfma_f32_16x16x32_bf16 v[112:115], v[166:169], v[182:185], v[112:115]
	v_mfma_f32_16x16x32_bf16 v[104:107], v[174:177], v[182:185], v[104:107]
	v_mfma_f32_16x16x32_bf16 v[96:99], v[166:169], v[190:193], v[96:99]
	v_mfma_f32_16x16x32_bf16 v[88:91], v[174:177], v[190:193], v[88:91]
	v_mfma_f32_16x16x32_bf16 v[80:83], v[166:169], v[202:205], v[80:83]
	v_mfma_f32_16x16x32_bf16 v[72:75], v[174:177], v[202:205], v[72:75]
	v_mfma_f32_16x16x32_bf16 v[68:71], v[166:169], v[210:213], v[68:71]
	v_mfma_f32_16x16x32_bf16 v[64:67], v[174:177], v[210:213], v[64:67]
	v_mfma_f32_16x16x32_bf16 v[112:115], v[170:173], v[186:189], v[112:115]
	v_mfma_f32_16x16x32_bf16 v[104:107], v[178:181], v[186:189], v[104:107]
	v_mfma_f32_16x16x32_bf16 v[96:99], v[170:173], v[194:197], v[96:99]
	v_mfma_f32_16x16x32_bf16 v[88:91], v[178:181], v[194:197], v[88:91]
	v_mfma_f32_16x16x32_bf16 v[80:83], v[170:173], v[206:209], v[80:83]
	v_mfma_f32_16x16x32_bf16 v[72:75], v[178:181], v[206:209], v[72:75]
	v_mfma_f32_16x16x32_bf16 v[68:71], v[170:173], v[214:217], v[68:71]
	v_mfma_f32_16x16x32_bf16 v[64:67], v[178:181], v[214:217], v[64:67]
	s_barrier
	s_add_i32 s60, s91, s66
	v_lshl_add_u64 v[198:199], v[198:199], 0, s[10:11]
	s_mov_b32 m0, s60
	ds_read_b128 v[182:185], v153 offset:49152
	ds_read_b128 v[186:189], v153 offset:50176
	ds_read_b128 v[190:193], v153 offset:51200
	ds_read_b128 v[194:197], v153 offset:52224
	ds_read_b128 v[202:205], v153 offset:53248
	ds_read_b128 v[206:209], v153 offset:54272
	ds_read_b128 v[210:213], v153 offset:55296
	ds_read_b128 v[214:217], v153 offset:56320
	global_load_lds_dwordx4 v[198:199], off
	s_add_i32 m0, s60, 0x2000
	s_add_u32 s58, s58, 0x40080
	v_lshl_add_u64 v[198:199], v[218:219], 0, s[10:11]
	s_addc_u32 s59, s59, 0
	s_add_i32 s60, s92, s66
	global_load_lds_dwordx4 v[198:199], off
	v_lshl_add_u64 v[198:199], s[58:59], 0, v[132:133]
	s_mov_b32 m0, s60
	s_nop 0
	global_load_lds_dwordx4 v[198:199], off
	v_lshl_add_u64 v[198:199], s[58:59], 0, v[128:129]
	s_add_i32 m0, s60, 0x2000
	s_nop 0
	global_load_lds_dwordx4 v[198:199], off
	v_lshl_add_u64 v[198:199], v[220:221], 0, s[10:11]
	s_mov_b32 m0, s72
	s_nop 0
	global_load_lds_dwordx4 v[198:199], off
	v_lshl_add_u64 v[198:199], v[222:223], 0, s[10:11]
	s_mov_b32 m0, s73
	s_nop 0
	global_load_lds_dwordx4 v[198:199], off
	s_waitcnt vmcnt(8)
	s_waitcnt lgkmcnt(0)
	s_barrier
	s_waitcnt lgkmcnt(0)
	v_mfma_f32_16x16x32_bf16 v[60:63], v[144:147], v[182:185], v[60:63]
	v_mfma_f32_16x16x32_bf16 v[56:59], v[158:161], v[182:185], v[56:59]
	v_mfma_f32_16x16x32_bf16 v[52:55], v[144:147], v[190:193], v[52:55]
	v_mfma_f32_16x16x32_bf16 v[44:47], v[158:161], v[190:193], v[44:47]
	v_mfma_f32_16x16x32_bf16 v[36:39], v[144:147], v[202:205], v[36:39]
	v_mfma_f32_16x16x32_bf16 v[28:31], v[158:161], v[202:205], v[28:31]
	v_mfma_f32_16x16x32_bf16 v[20:23], v[144:147], v[210:213], v[20:23]
	v_mfma_f32_16x16x32_bf16 v[12:15], v[158:161], v[210:213], v[12:15]
	v_mfma_f32_16x16x32_bf16 v[60:63], v[154:157], v[186:189], v[60:63]
	v_mfma_f32_16x16x32_bf16 v[56:59], v[162:165], v[186:189], v[56:59]
	v_mfma_f32_16x16x32_bf16 v[52:55], v[154:157], v[194:197], v[52:55]
	v_mfma_f32_16x16x32_bf16 v[44:47], v[162:165], v[194:197], v[44:47]
	v_mfma_f32_16x16x32_bf16 v[36:39], v[154:157], v[206:209], v[36:39]
	v_mfma_f32_16x16x32_bf16 v[28:31], v[162:165], v[206:209], v[28:31]
	v_mfma_f32_16x16x32_bf16 v[20:23], v[154:157], v[214:217], v[20:23]
	v_mfma_f32_16x16x32_bf16 v[12:15], v[162:165], v[214:217], v[12:15]
	v_mfma_f32_16x16x32_bf16 v[48:51], v[166:169], v[182:185], v[48:51]
	v_mfma_f32_16x16x32_bf16 v[40:43], v[174:177], v[182:185], v[40:43]
	v_mfma_f32_16x16x32_bf16 v[32:35], v[166:169], v[190:193], v[32:35]
	v_mfma_f32_16x16x32_bf16 v[24:27], v[174:177], v[190:193], v[24:27]
	v_mfma_f32_16x16x32_bf16 v[16:19], v[166:169], v[202:205], v[16:19]
	v_mfma_f32_16x16x32_bf16 v[8:11], v[174:177], v[202:205], v[8:11]
	v_mfma_f32_16x16x32_bf16 v[4:7], v[166:169], v[210:213], v[4:7]
	v_mfma_f32_16x16x32_bf16 v[0:3], v[174:177], v[210:213], v[0:3]
	v_mfma_f32_16x16x32_bf16 v[48:51], v[170:173], v[186:189], v[48:51]
	v_mfma_f32_16x16x32_bf16 v[40:43], v[178:181], v[186:189], v[40:43]
	v_mfma_f32_16x16x32_bf16 v[32:35], v[170:173], v[194:197], v[32:35]
	v_mfma_f32_16x16x32_bf16 v[24:27], v[178:181], v[194:197], v[24:27]
	v_mfma_f32_16x16x32_bf16 v[16:19], v[170:173], v[206:209], v[16:19]
	v_mfma_f32_16x16x32_bf16 v[8:11], v[178:181], v[206:209], v[8:11]
	v_mfma_f32_16x16x32_bf16 v[4:7], v[170:173], v[214:217], v[4:7]
	v_mfma_f32_16x16x32_bf16 v[0:3], v[178:181], v[214:217], v[0:3]
	s_barrier
	s_add_i32 s90, s90, 2
	s_add_u32 s54, s54, 0x100
	s_addc_u32 s55, s55, 0
	s_add_u32 s88, s88, 0x100
	s_addc_u32 s89, s89, 0
	s_cmp_gt_u32 s90, 13
	s_cbranch_scc0 .LBB0_215
	s_setprio 0
	s_and_b64 vcc, exec, s[12:13]
	s_cbranch_vccz .LBB0_218
	s_barrier

.LBB0_383:
	s_ashr_i32 s45, s44, 31
	s_lshl_b64 s[50:51], s[44:45], 19
	s_add_u32 s50, s67, s50
	s_addc_u32 s51, s68, s51
	s_and_b64 s[54:55], s[2:3], exec
	s_cselect_b32 s17, s51, s59
	s_cselect_b32 s45, s50, s58
	s_ashr_i32 s35, s34, 31
	s_lshl_b64 s[54:55], s[34:35], 19
	s_add_u32 s54, s69, s54
	s_addc_u32 s55, s72, s55
	s_and_b64 s[62:63], s[2:3], exec
	s_cselect_b32 s35, s55, s61
	s_cselect_b32 s89, s54, s60
	s_add_u32 s58, s58, 0x40080
	s_addc_u32 s59, s59, 0
	s_add_u32 s90, s60, 0x100
	s_addc_u32 s91, s61, 0
	s_mov_b32 s92, -2
	v_mov_b64_e32 v[0:1], 0
	v_mov_b64_e32 v[2:3], 0
	v_mov_b64_e32 v[4:5], 0
	v_mov_b64_e32 v[6:7], 0
	v_mov_b64_e32 v[8:9], 0
	v_mov_b64_e32 v[10:11], 0
	v_mov_b64_e32 v[12:13], 0
	v_mov_b64_e32 v[14:15], 0
	v_mov_b64_e32 v[16:17], 0
	v_mov_b64_e32 v[18:19], 0
	v_mov_b64_e32 v[20:21], 0
	v_mov_b64_e32 v[22:23], 0
	v_mov_b64_e32 v[24:25], 0
	v_mov_b64_e32 v[26:27], 0
	v_mov_b64_e32 v[28:29], 0
	v_mov_b64_e32 v[30:31], 0
	v_mov_b64_e32 v[32:33], 0
	v_mov_b64_e32 v[34:35], 0
	v_mov_b64_e32 v[36:37], 0
	v_mov_b64_e32 v[38:39], 0
	v_mov_b64_e32 v[40:41], 0
	v_mov_b64_e32 v[42:43], 0
	v_mov_b64_e32 v[44:45], 0
	v_mov_b64_e32 v[46:47], 0
	v_mov_b64_e32 v[48:49], 0
	v_mov_b64_e32 v[50:51], 0
	v_mov_b64_e32 v[52:53], 0
	v_mov_b64_e32 v[54:55], 0
	v_mov_b64_e32 v[56:57], 0
	v_mov_b64_e32 v[58:59], 0
	v_mov_b64_e32 v[60:61], 0
	v_mov_b64_e32 v[62:63], 0
	v_mov_b64_e32 v[64:65], 0
	v_mov_b64_e32 v[66:67], 0
	v_mov_b64_e32 v[68:69], 0
	v_mov_b64_e32 v[70:71], 0
	v_mov_b64_e32 v[72:73], 0
	v_mov_b64_e32 v[74:75], 0
	v_mov_b64_e32 v[76:77], 0
	v_mov_b64_e32 v[78:79], 0
	v_mov_b64_e32 v[80:81], 0
	v_mov_b64_e32 v[82:83], 0
	v_mov_b64_e32 v[84:85], 0
	v_mov_b64_e32 v[86:87], 0
	v_mov_b64_e32 v[88:89], 0
	v_mov_b64_e32 v[90:91], 0
	v_mov_b64_e32 v[92:93], 0
	v_mov_b64_e32 v[94:95], 0
	v_mov_b64_e32 v[96:97], 0
	v_mov_b64_e32 v[98:99], 0
	v_mov_b64_e32 v[100:101], 0
	v_mov_b64_e32 v[102:103], 0
	v_mov_b64_e32 v[104:105], 0
	v_mov_b64_e32 v[106:107], 0
	v_mov_b64_e32 v[108:109], 0
	v_mov_b64_e32 v[110:111], 0
	v_mov_b64_e32 v[112:113], 0
	v_mov_b64_e32 v[114:115], 0
	v_mov_b64_e32 v[116:117], 0
	v_mov_b64_e32 v[118:119], 0
	v_mov_b64_e32 v[120:121], 0
	v_mov_b64_e32 v[122:123], 0
	v_mov_b64_e32 v[124:125], 0
	v_mov_b64_e32 v[126:127], 0
	v_lshrrev_b32_e32 v253, 8, v200
	s_nop 0
	v_readfirstlane_b32 s98, v253
	s_cmp_lg_u32 s98, 0
	s_cbranch_scc0 .Lgp_384
	s_setprio 1
.Lgp_384:
.LBB0_384:
	ds_read_b128 v[152:155], v149
	ds_read_b128 v[156:159], v149 offset:1024
	ds_read_b128 v[160:163], v149 offset:2048
	ds_read_b128 v[164:167], v149 offset:3072
	ds_read_b128 v[168:171], v150
	ds_read_b128 v[172:175], v150 offset:1024
	ds_read_b128 v[176:179], v150 offset:2048
	ds_read_b128 v[180:183], v150 offset:3072
	s_add_u32 s60, s58, 0xfffc0080
	s_addc_u32 s61, s59, -1
	s_cmp_eq_u32 s92, 12
	s_cselect_b32 s63, s17, s61
	s_cselect_b32 s62, s45, s60
	s_cselect_b32 s61, s35, s91
	s_cselect_b32 s60, s89, s90
	v_lshl_add_u64 v[144:145], s[58:59], 0, v[136:137]
	s_add_i32 m0, s74, 0xc000
	ds_read_b128 v[184:187], v151
	ds_read_b128 v[188:191], v151 offset:1024
	ds_read_b128 v[192:195], v151 offset:2048
	ds_read_b128 v[196:199], v151 offset:3072
	ds_read_b128 v[202:205], v151 offset:4096
	ds_read_b128 v[206:209], v151 offset:5120
	ds_read_b128 v[210:213], v151 offset:6144
	ds_read_b128 v[214:217], v151 offset:7168
	global_load_lds_dwordx4 v[144:145], off
	v_lshl_add_u64 v[144:145], s[58:59], 0, v[138:139]
	s_add_i32 m0, s74, 0xe000
	s_nop 0
	global_load_lds_dwordx4 v[144:145], off
	s_waitcnt vmcnt(8)
	s_waitcnt lgkmcnt(0)
	s_barrier
	s_waitcnt lgkmcnt(0)
	v_mfma_f32_16x16x32_bf16 v[124:127], v[152:155], v[184:187], v[124:127]
	v_mfma_f32_16x16x32_bf16 v[120:123], v[160:163], v[184:187], v[120:123]
	v_mfma_f32_16x16x32_bf16 v[116:119], v[152:155], v[192:195], v[116:119]
	v_mfma_f32_16x16x32_bf16 v[108:111], v[160:163], v[192:195], v[108:111]
	v_mfma_f32_16x16x32_bf16 v[100:103], v[152:155], v[202:205], v[100:103]
	v_mfma_f32_16x16x32_bf16 v[92:95], v[160:163], v[202:205], v[92:95]
	v_mfma_f32_16x16x32_bf16 v[84:87], v[152:155], v[210:213], v[84:87]
	v_mfma_f32_16x16x32_bf16 v[76:79], v[160:163], v[210:213], v[76:79]
	v_mfma_f32_16x16x32_bf16 v[124:127], v[156:159], v[188:191], v[124:127]
	v_mfma_f32_16x16x32_bf16 v[120:123], v[164:167], v[188:191], v[120:123]
	v_mfma_f32_16x16x32_bf16 v[116:119], v[156:159], v[196:199], v[116:119]
	v_mfma_f32_16x16x32_bf16 v[108:111], v[164:167], v[196:199], v[108:111]
	v_mfma_f32_16x16x32_bf16 v[100:103], v[156:159], v[206:209], v[100:103]
	v_mfma_f32_16x16x32_bf16 v[92:95], v[164:167], v[206:209], v[92:95]
	v_mfma_f32_16x16x32_bf16 v[84:87], v[156:159], v[214:217], v[84:87]
	v_mfma_f32_16x16x32_bf16 v[76:79], v[164:167], v[214:217], v[76:79]
	v_mfma_f32_16x16x32_bf16 v[112:115], v[168:171], v[184:187], v[112:115]
	v_mfma_f32_16x16x32_bf16 v[104:107], v[176:179], v[184:187], v[104:107]
	v_mfma_f32_16x16x32_bf16 v[96:99], v[168:171], v[192:195], v[96:99]
	v_mfma_f32_16x16x32_bf16 v[88:91], v[176:179], v[192:195], v[88:91]
	v_mfma_f32_16x16x32_bf16 v[80:83], v[168:171], v[202:205], v[80:83]
	v_mfma_f32_16x16x32_bf16 v[72:75], v[176:179], v[202:205], v[72:75]
	v_mfma_f32_16x16x32_bf16 v[68:71], v[168:171], v[210:213], v[68:71]
	v_mfma_f32_16x16x32_bf16 v[64:67], v[176:179], v[210:213], v[64:67]
	v_mfma_f32_16x16x32_bf16 v[112:115], v[172:175], v[188:191], v[112:115]
	v_mfma_f32_16x16x32_bf16 v[104:107], v[180:183], v[188:191], v[104:107]
	v_mfma_f32_16x16x32_bf16 v[96:99], v[172:175], v[196:199], v[96:99]
	v_mfma_f32_16x16x32_bf16 v[88:91], v[180:183], v[196:199], v[88:91]
	v_mfma_f32_16x16x32_bf16 v[80:83], v[172:175], v[206:209], v[80:83]
	v_mfma_f32_16x16x32_bf16 v[72:75], v[180:183], v[206:209], v[72:75]
	v_mfma_f32_16x16x32_bf16 v[68:71], v[172:175], v[214:217], v[68:71]
	v_mfma_f32_16x16x32_bf16 v[64:67], v[180:183], v[214:217], v[64:67]
	s_barrier
	s_add_i32 s93, s83, s73
	v_lshl_add_u64 v[144:145], s[60:61], 0, v[132:133]
	s_mov_b32 m0, s93
	ds_read_b128 v[184:187], v151 offset:16384
	ds_read_b128 v[188:191], v151 offset:17408
	ds_read_b128 v[192:195], v151 offset:18432
	ds_read_b128 v[196:199], v151 offset:19456
	ds_read_b128 v[202:205], v151 offset:20480
	ds_read_b128 v[206:209], v151 offset:21504
	ds_read_b128 v[210:213], v151 offset:22528
	ds_read_b128 v[214:217], v151 offset:23552
	global_load_lds_dwordx4 v[144:145], off
	s_add_i32 m0, s93, 0x2000
	s_add_u32 s94, s60, 0x40000
	v_lshl_add_u64 v[218:219], s[60:61], 0, v[128:129]
	s_addc_u32 s95, s61, 0
	s_add_i32 s93, s84, s73
	global_load_lds_dwordx4 v[218:219], off
	v_lshl_add_u64 v[220:221], s[94:95], 0, v[132:133]
	s_mov_b32 m0, s93
	v_lshl_add_u64 v[222:223], s[62:63], 0, v[130:131]
	global_load_lds_dwordx4 v[220:221], off
	v_lshl_add_u64 v[220:221], s[94:95], 0, v[128:129]
	s_add_i32 m0, s93, 0x2000
	s_nop 0
	global_load_lds_dwordx4 v[220:221], off
	v_lshl_add_u64 v[220:221], s[62:63], 0, v[134:135]
	s_mov_b32 m0, s74
	s_nop 0
	global_load_lds_dwordx4 v[220:221], off
	s_mov_b32 m0, s75
	s_nop 0
	global_load_lds_dwordx4 v[222:223], off
	s_waitcnt vmcnt(8)
	s_waitcnt lgkmcnt(0)
	s_barrier
	s_waitcnt lgkmcnt(0)
	v_mfma_f32_16x16x32_bf16 v[60:63], v[152:155], v[184:187], v[60:63]
	v_mfma_f32_16x16x32_bf16 v[56:59], v[160:163], v[184:187], v[56:59]
	v_mfma_f32_16x16x32_bf16 v[52:55], v[152:155], v[192:195], v[52:55]
	v_mfma_f32_16x16x32_bf16 v[44:47], v[160:163], v[192:195], v[44:47]
	v_mfma_f32_16x16x32_bf16 v[36:39], v[152:155], v[202:205], v[36:39]
	v_mfma_f32_16x16x32_bf16 v[28:31], v[160:163], v[202:205], v[28:31]
	v_mfma_f32_16x16x32_bf16 v[20:23], v[152:155], v[210:213], v[20:23]
	v_mfma_f32_16x16x32_bf16 v[12:15], v[160:163], v[210:213], v[12:15]
	v_mfma_f32_16x16x32_bf16 v[60:63], v[156:159], v[188:191], v[60:63]
	v_mfma_f32_16x16x32_bf16 v[56:59], v[164:167], v[188:191], v[56:59]
	v_mfma_f32_16x16x32_bf16 v[52:55], v[156:159], v[196:199], v[52:55]
	v_mfma_f32_16x16x32_bf16 v[44:47], v[164:167], v[196:199], v[44:47]
	v_mfma_f32_16x16x32_bf16 v[36:39], v[156:159], v[206:209], v[36:39]
	v_mfma_f32_16x16x32_bf16 v[28:31], v[164:167], v[206:209], v[28:31]
	v_mfma_f32_16x16x32_bf16 v[20:23], v[156:159], v[214:217], v[20:23]
	v_mfma_f32_16x16x32_bf16 v[12:15], v[164:167], v[214:217], v[12:15]
	v_mfma_f32_16x16x32_bf16 v[48:51], v[168:171], v[184:187], v[48:51]
	v_mfma_f32_16x16x32_bf16 v[40:43], v[176:179], v[184:187], v[40:43]
	v_mfma_f32_16x16x32_bf16 v[32:35], v[168:171], v[192:195], v[32:35]
	v_mfma_f32_16x16x32_bf16 v[24:27], v[176:179], v[192:195], v[24:27]
	v_mfma_f32_16x16x32_bf16 v[16:19], v[168:171], v[202:205], v[16:19]
	v_mfma_f32_16x16x32_bf16 v[8:11], v[176:179], v[202:205], v[8:11]
	v_mfma_f32_16x16x32_bf16 v[4:7], v[168:171], v[210:213], v[4:7]
	v_mfma_f32_16x16x32_bf16 v[0:3], v[176:179], v[210:213], v[0:3]
	v_mfma_f32_16x16x32_bf16 v[48:51], v[172:175], v[188:191], v[48:51]
	v_mfma_f32_16x16x32_bf16 v[40:43], v[180:183], v[188:191], v[40:43]
	v_mfma_f32_16x16x32_bf16 v[32:35], v[172:175], v[196:199], v[32:35]
	v_mfma_f32_16x16x32_bf16 v[24:27], v[180:183], v[196:199], v[24:27]
	v_mfma_f32_16x16x32_bf16 v[16:19], v[172:175], v[206:209], v[16:19]
	v_mfma_f32_16x16x32_bf16 v[8:11], v[180:183], v[206:209], v[8:11]
	v_mfma_f32_16x16x32_bf16 v[4:7], v[172:175], v[214:217], v[4:7]
	v_mfma_f32_16x16x32_bf16 v[0:3], v[180:183], v[214:217], v[0:3]
	s_barrier
	s_add_i32 s93, 0, 0x18000
	s_add_i32 s94, 0, 0x1c000
	v_add_u32_e32 v164, s93, v147
	v_add_u32_e32 v180, s94, v147
	ds_read_b128 v[152:155], v164
	ds_read_b128 v[156:159], v164 offset:1024
	ds_read_b128 v[160:163], v164 offset:2048
	ds_read_b128 v[164:167], v164 offset:3072
	ds_read_b128 v[168:171], v180
	ds_read_b128 v[172:175], v180 offset:1024
	ds_read_b128 v[176:179], v180 offset:2048
	ds_read_b128 v[180:183], v180 offset:3072
	s_add_u32 s62, s62, 0x40000
	s_addc_u32 s63, s63, 0
	s_mov_b32 m0, s76
	v_lshl_add_u64 v[224:225], s[62:63], 0, v[134:135]
	ds_read_b128 v[184:187], v151 offset:32768
	ds_read_b128 v[188:191], v151 offset:33792
	ds_read_b128 v[192:195], v151 offset:34816
	ds_read_b128 v[196:199], v151 offset:35840
	ds_read_b128 v[202:205], v151 offset:36864
	ds_read_b128 v[206:209], v151 offset:37888
	ds_read_b128 v[210:213], v151 offset:38912
	ds_read_b128 v[214:217], v151 offset:39936
	global_load_lds_dwordx4 v[224:225], off
	v_lshl_add_u64 v[224:225], s[62:63], 0, v[130:131]
	s_mov_b32 m0, s77
	s_nop 0
	global_load_lds_dwordx4 v[224:225], off
	s_waitcnt vmcnt(8)
	s_waitcnt lgkmcnt(0)
	s_barrier
	s_waitcnt lgkmcnt(0)
	v_mfma_f32_16x16x32_bf16 v[124:127], v[152:155], v[184:187], v[124:127]
	v_mfma_f32_16x16x32_bf16 v[120:123], v[160:163], v[184:187], v[120:123]
	v_mfma_f32_16x16x32_bf16 v[116:119], v[152:155], v[192:195], v[116:119]
	v_mfma_f32_16x16x32_bf16 v[108:111], v[160:163], v[192:195], v[108:111]
	v_mfma_f32_16x16x32_bf16 v[100:103], v[152:155], v[202:205], v[100:103]
	v_mfma_f32_16x16x32_bf16 v[92:95], v[160:163], v[202:205], v[92:95]
	v_mfma_f32_16x16x32_bf16 v[84:87], v[152:155], v[210:213], v[84:87]
	v_mfma_f32_16x16x32_bf16 v[76:79], v[160:163], v[210:213], v[76:79]
	v_mfma_f32_16x16x32_bf16 v[124:127], v[156:159], v[188:191], v[124:127]
	v_mfma_f32_16x16x32_bf16 v[120:123], v[164:167], v[188:191], v[120:123]
	v_mfma_f32_16x16x32_bf16 v[116:119], v[156:159], v[196:199], v[116:119]
	v_mfma_f32_16x16x32_bf16 v[108:111], v[164:167], v[196:199], v[108:111]
	v_mfma_f32_16x16x32_bf16 v[100:103], v[156:159], v[206:209], v[100:103]
	v_mfma_f32_16x16x32_bf16 v[92:95], v[164:167], v[206:209], v[92:95]
	v_mfma_f32_16x16x32_bf16 v[84:87], v[156:159], v[214:217], v[84:87]
	v_mfma_f32_16x16x32_bf16 v[76:79], v[164:167], v[214:217], v[76:79]
	v_mfma_f32_16x16x32_bf16 v[112:115], v[168:171], v[184:187], v[112:115]
	v_mfma_f32_16x16x32_bf16 v[104:107], v[176:179], v[184:187], v[104:107]
	v_mfma_f32_16x16x32_bf16 v[96:99], v[168:171], v[192:195], v[96:99]
	v_mfma_f32_16x16x32_bf16 v[88:91], v[176:179], v[192:195], v[88:91]
	v_mfma_f32_16x16x32_bf16 v[80:83], v[168:171], v[202:205], v[80:83]
	v_mfma_f32_16x16x32_bf16 v[72:75], v[176:179], v[202:205], v[72:75]
	v_mfma_f32_16x16x32_bf16 v[68:71], v[168:171], v[210:213], v[68:71]
	v_mfma_f32_16x16x32_bf16 v[64:67], v[176:179], v[210:213], v[64:67]
	v_mfma_f32_16x16x32_bf16 v[112:115], v[172:175], v[188:191], v[112:115]
	v_mfma_f32_16x16x32_bf16 v[104:107], v[180:183], v[188:191], v[104:107]
	v_mfma_f32_16x16x32_bf16 v[96:99], v[172:175], v[196:199], v[96:99]
	v_mfma_f32_16x16x32_bf16 v[88:91], v[180:183], v[196:199], v[88:91]
	v_mfma_f32_16x16x32_bf16 v[80:83], v[172:175], v[206:209], v[80:83]
	v_mfma_f32_16x16x32_bf16 v[72:75], v[180:183], v[206:209], v[72:75]
	v_mfma_f32_16x16x32_bf16 v[68:71], v[172:175], v[214:217], v[68:71]
	v_mfma_f32_16x16x32_bf16 v[64:67], v[180:183], v[214:217], v[64:67]
	s_barrier
	s_add_i32 s62, s93, s73
	v_lshl_add_u64 v[144:145], v[144:145], 0, s[10:11]
	s_mov_b32 m0, s62
	ds_read_b128 v[184:187], v151 offset:49152
	ds_read_b128 v[188:191], v151 offset:50176
	ds_read_b128 v[192:195], v151 offset:51200
	ds_read_b128 v[196:199], v151 offset:52224
	ds_read_b128 v[202:205], v151 offset:53248
	ds_read_b128 v[206:209], v151 offset:54272
	ds_read_b128 v[210:213], v151 offset:55296
	ds_read_b128 v[214:217], v151 offset:56320
	global_load_lds_dwordx4 v[144:145], off
	s_add_i32 m0, s62, 0x2000
	s_add_u32 s60, s60, 0x40080
	v_lshl_add_u64 v[144:145], v[218:219], 0, s[10:11]
	s_addc_u32 s61, s61, 0
	s_add_i32 s62, s94, s73
	global_load_lds_dwordx4 v[144:145], off
	v_lshl_add_u64 v[144:145], s[60:61], 0, v[132:133]
	s_mov_b32 m0, s62
	s_nop 0
	global_load_lds_dwordx4 v[144:145], off
	v_lshl_add_u64 v[144:145], s[60:61], 0, v[128:129]
	s_add_i32 m0, s62, 0x2000
	s_nop 0
	global_load_lds_dwordx4 v[144:145], off
	v_lshl_add_u64 v[144:145], v[220:221], 0, s[10:11]
	s_mov_b32 m0, s79
	s_nop 0
	global_load_lds_dwordx4 v[144:145], off
	v_lshl_add_u64 v[144:145], v[222:223], 0, s[10:11]
	s_mov_b32 m0, s80
	s_nop 0
	global_load_lds_dwordx4 v[144:145], off
	s_waitcnt vmcnt(8)
	s_waitcnt lgkmcnt(0)
	s_barrier
	s_waitcnt lgkmcnt(0)
	v_mfma_f32_16x16x32_bf16 v[60:63], v[152:155], v[184:187], v[60:63]
	v_mfma_f32_16x16x32_bf16 v[56:59], v[160:163], v[184:187], v[56:59]
	v_mfma_f32_16x16x32_bf16 v[52:55], v[152:155], v[192:195], v[52:55]
	v_mfma_f32_16x16x32_bf16 v[44:47], v[160:163], v[192:195], v[44:47]
	v_mfma_f32_16x16x32_bf16 v[36:39], v[152:155], v[202:205], v[36:39]
	v_mfma_f32_16x16x32_bf16 v[28:31], v[160:163], v[202:205], v[28:31]
	v_mfma_f32_16x16x32_bf16 v[20:23], v[152:155], v[210:213], v[20:23]
	v_mfma_f32_16x16x32_bf16 v[12:15], v[160:163], v[210:213], v[12:15]
	v_mfma_f32_16x16x32_bf16 v[60:63], v[156:159], v[188:191], v[60:63]
	v_mfma_f32_16x16x32_bf16 v[56:59], v[164:167], v[188:191], v[56:59]
	v_mfma_f32_16x16x32_bf16 v[52:55], v[156:159], v[196:199], v[52:55]
	v_mfma_f32_16x16x32_bf16 v[44:47], v[164:167], v[196:199], v[44:47]
	v_mfma_f32_16x16x32_bf16 v[36:39], v[156:159], v[206:209], v[36:39]
	v_mfma_f32_16x16x32_bf16 v[28:31], v[164:167], v[206:209], v[28:31]
	v_mfma_f32_16x16x32_bf16 v[20:23], v[156:159], v[214:217], v[20:23]
	v_mfma_f32_16x16x32_bf16 v[12:15], v[164:167], v[214:217], v[12:15]
	v_mfma_f32_16x16x32_bf16 v[48:51], v[168:171], v[184:187], v[48:51]
	v_mfma_f32_16x16x32_bf16 v[40:43], v[176:179], v[184:187], v[40:43]
	v_mfma_f32_16x16x32_bf16 v[32:35], v[168:171], v[192:195], v[32:35]
	v_mfma_f32_16x16x32_bf16 v[24:27], v[176:179], v[192:195], v[24:27]
	v_mfma_f32_16x16x32_bf16 v[16:19], v[168:171], v[202:205], v[16:19]
	v_mfma_f32_16x16x32_bf16 v[8:11], v[176:179], v[202:205], v[8:11]
	v_mfma_f32_16x16x32_bf16 v[4:7], v[168:171], v[210:213], v[4:7]
	v_mfma_f32_16x16x32_bf16 v[0:3], v[176:179], v[210:213], v[0:3]
	v_mfma_f32_16x16x32_bf16 v[48:51], v[172:175], v[188:191], v[48:51]
	v_mfma_f32_16x16x32_bf16 v[40:43], v[180:183], v[188:191], v[40:43]
	v_mfma_f32_16x16x32_bf16 v[32:35], v[172:175], v[196:199], v[32:35]
	v_mfma_f32_16x16x32_bf16 v[24:27], v[180:183], v[196:199], v[24:27]
	v_mfma_f32_16x16x32_bf16 v[16:19], v[172:175], v[206:209], v[16:19]
	v_mfma_f32_16x16x32_bf16 v[8:11], v[180:183], v[206:209], v[8:11]
	v_mfma_f32_16x16x32_bf16 v[4:7], v[172:175], v[214:217], v[4:7]
	v_mfma_f32_16x16x32_bf16 v[0:3], v[180:183], v[214:217], v[0:3]
	s_barrier
	s_add_i32 s92, s92, 2
	s_add_u32 s58, s58, 0x100
	s_addc_u32 s59, s59, 0
	s_add_u32 s90, s90, 0x100
	s_addc_u32 s91, s91, 0
	s_cmp_gt_u32 s92, 13
	s_cbranch_scc0 .LBB0_384
	s_setprio 0
	s_and_b64 vcc, exec, s[12:13]
	s_cbranch_vccz .LBB0_387
	s_barrier

.LBB0_728:
	s_ashr_i32 s45, s44, 31
	s_lshl_b64 s[50:51], s[44:45], 19
	s_add_u32 s50, s11, s50
	s_addc_u32 s51, s17, s51
	s_and_b64 s[54:55], s[2:3], exec
	s_cselect_b32 s45, s51, s59
	s_cselect_b32 s78, s50, s58
	s_ashr_i32 s35, s34, 31
	s_lshl_b64 s[54:55], s[34:35], 19
	s_add_u32 s54, s64, s54
	s_addc_u32 s55, s65, s55
	s_and_b64 s[62:63], s[2:3], exec
	s_cselect_b32 s35, s55, s61
	s_cselect_b32 s79, s54, s60
	s_add_u32 s58, s58, 0x40080
	s_addc_u32 s59, s59, 0
	s_add_u32 s80, s60, 0x100
	s_addc_u32 s81, s61, 0
	s_mov_b32 s82, -2
	v_mov_b64_e32 v[0:1], 0
	v_mov_b64_e32 v[2:3], 0
	v_mov_b64_e32 v[4:5], 0
	v_mov_b64_e32 v[6:7], 0
	v_mov_b64_e32 v[8:9], 0
	v_mov_b64_e32 v[10:11], 0
	v_mov_b64_e32 v[12:13], 0
	v_mov_b64_e32 v[14:15], 0
	v_mov_b64_e32 v[16:17], 0
	v_mov_b64_e32 v[18:19], 0
	v_mov_b64_e32 v[20:21], 0
	v_mov_b64_e32 v[22:23], 0
	v_mov_b64_e32 v[24:25], 0
	v_mov_b64_e32 v[26:27], 0
	v_mov_b64_e32 v[28:29], 0
	v_mov_b64_e32 v[30:31], 0
	v_mov_b64_e32 v[32:33], 0
	v_mov_b64_e32 v[34:35], 0
	v_mov_b64_e32 v[36:37], 0
	v_mov_b64_e32 v[38:39], 0
	v_mov_b64_e32 v[40:41], 0
	v_mov_b64_e32 v[42:43], 0
	v_mov_b64_e32 v[44:45], 0
	v_mov_b64_e32 v[46:47], 0
	v_mov_b64_e32 v[48:49], 0
	v_mov_b64_e32 v[50:51], 0
	v_mov_b64_e32 v[52:53], 0
	v_mov_b64_e32 v[54:55], 0
	v_mov_b64_e32 v[56:57], 0
	v_mov_b64_e32 v[58:59], 0
	v_mov_b64_e32 v[60:61], 0
	v_mov_b64_e32 v[62:63], 0
	v_mov_b64_e32 v[64:65], 0
	v_mov_b64_e32 v[66:67], 0
	v_mov_b64_e32 v[68:69], 0
	v_mov_b64_e32 v[70:71], 0
	v_mov_b64_e32 v[72:73], 0
	v_mov_b64_e32 v[74:75], 0
	v_mov_b64_e32 v[76:77], 0
	v_mov_b64_e32 v[78:79], 0
	v_mov_b64_e32 v[80:81], 0
	v_mov_b64_e32 v[82:83], 0
	v_mov_b64_e32 v[84:85], 0
	v_mov_b64_e32 v[86:87], 0
	v_mov_b64_e32 v[88:89], 0
	v_mov_b64_e32 v[90:91], 0
	v_mov_b64_e32 v[92:93], 0
	v_mov_b64_e32 v[94:95], 0
	v_mov_b64_e32 v[96:97], 0
	v_mov_b64_e32 v[98:99], 0
	v_mov_b64_e32 v[100:101], 0
	v_mov_b64_e32 v[102:103], 0
	v_mov_b64_e32 v[104:105], 0
	v_mov_b64_e32 v[106:107], 0
	v_mov_b64_e32 v[108:109], 0
	v_mov_b64_e32 v[110:111], 0
	v_mov_b64_e32 v[112:113], 0
	v_mov_b64_e32 v[114:115], 0
	v_mov_b64_e32 v[116:117], 0
	v_mov_b64_e32 v[118:119], 0
	v_mov_b64_e32 v[120:121], 0
	v_mov_b64_e32 v[122:123], 0
	v_mov_b64_e32 v[124:125], 0
	v_mov_b64_e32 v[126:127], 0
	v_lshrrev_b32_e32 v253, 8, v200
	s_nop 0
	v_readfirstlane_b32 s98, v253
	s_cmp_lg_u32 s98, 0
	s_cbranch_scc0 .Lgp_729
	s_setprio 1
.Lgp_729:
.LBB0_729:
	ds_read_b128 v[148:151], v145
	ds_read_b128 v[152:155], v145 offset:1024
	ds_read_b128 v[156:159], v145 offset:2048
	ds_read_b128 v[160:163], v145 offset:3072
	ds_read_b128 v[164:167], v146
	ds_read_b128 v[168:171], v146 offset:1024
	ds_read_b128 v[172:175], v146 offset:2048
	ds_read_b128 v[176:179], v146 offset:3072
	s_add_u32 s60, s58, 0xfffc0080
	s_addc_u32 s61, s59, -1
	s_cmp_eq_u32 s82, 12
	s_cselect_b32 s63, s45, s61
	s_cselect_b32 s62, s78, s60
	s_cselect_b32 s61, s35, s81
	s_cselect_b32 s60, s79, s80
	v_lshl_add_u64 v[140:141], s[58:59], 0, v[132:133]
	s_add_i32 m0, s67, 0xc000
	ds_read_b128 v[180:183], v147
	ds_read_b128 v[184:187], v147 offset:1024
	ds_read_b128 v[188:191], v147 offset:2048
	ds_read_b128 v[192:195], v147 offset:3072
	ds_read_b128 v[196:199], v147 offset:4096
	ds_read_b128 v[202:205], v147 offset:5120
	ds_read_b128 v[206:209], v147 offset:6144
	ds_read_b128 v[210:213], v147 offset:7168
	global_load_lds_dwordx4 v[140:141], off
	v_lshl_add_u64 v[140:141], s[58:59], 0, v[134:135]
	s_add_i32 m0, s67, 0xe000
	s_nop 0
	global_load_lds_dwordx4 v[140:141], off
	s_waitcnt vmcnt(8)
	s_waitcnt lgkmcnt(0)
	s_barrier
	s_waitcnt lgkmcnt(0)
	v_mfma_f32_16x16x32_bf16 v[124:127], v[148:151], v[180:183], v[124:127]
	v_mfma_f32_16x16x32_bf16 v[120:123], v[156:159], v[180:183], v[120:123]
	v_mfma_f32_16x16x32_bf16 v[112:115], v[148:151], v[188:191], v[112:115]
	v_mfma_f32_16x16x32_bf16 v[108:111], v[156:159], v[188:191], v[108:111]
	v_mfma_f32_16x16x32_bf16 v[96:99], v[148:151], v[196:199], v[96:99]
	v_mfma_f32_16x16x32_bf16 v[92:95], v[156:159], v[196:199], v[92:95]
	v_mfma_f32_16x16x32_bf16 v[80:83], v[148:151], v[206:209], v[80:83]
	v_mfma_f32_16x16x32_bf16 v[76:79], v[156:159], v[206:209], v[76:79]
	v_mfma_f32_16x16x32_bf16 v[124:127], v[152:155], v[184:187], v[124:127]
	v_mfma_f32_16x16x32_bf16 v[120:123], v[160:163], v[184:187], v[120:123]
	v_mfma_f32_16x16x32_bf16 v[112:115], v[152:155], v[192:195], v[112:115]
	v_mfma_f32_16x16x32_bf16 v[108:111], v[160:163], v[192:195], v[108:111]
	v_mfma_f32_16x16x32_bf16 v[96:99], v[152:155], v[202:205], v[96:99]
	v_mfma_f32_16x16x32_bf16 v[92:95], v[160:163], v[202:205], v[92:95]
	v_mfma_f32_16x16x32_bf16 v[80:83], v[152:155], v[210:213], v[80:83]
	v_mfma_f32_16x16x32_bf16 v[76:79], v[160:163], v[210:213], v[76:79]
	v_mfma_f32_16x16x32_bf16 v[116:119], v[164:167], v[180:183], v[116:119]
	v_mfma_f32_16x16x32_bf16 v[104:107], v[172:175], v[180:183], v[104:107]
	v_mfma_f32_16x16x32_bf16 v[100:103], v[164:167], v[188:191], v[100:103]
	v_mfma_f32_16x16x32_bf16 v[88:91], v[172:175], v[188:191], v[88:91]
	v_mfma_f32_16x16x32_bf16 v[84:87], v[164:167], v[196:199], v[84:87]
	v_mfma_f32_16x16x32_bf16 v[72:75], v[172:175], v[196:199], v[72:75]
	v_mfma_f32_16x16x32_bf16 v[68:71], v[164:167], v[206:209], v[68:71]
	v_mfma_f32_16x16x32_bf16 v[64:67], v[172:175], v[206:209], v[64:67]
	v_mfma_f32_16x16x32_bf16 v[116:119], v[168:171], v[184:187], v[116:119]
	v_mfma_f32_16x16x32_bf16 v[104:107], v[176:179], v[184:187], v[104:107]
	v_mfma_f32_16x16x32_bf16 v[100:103], v[168:171], v[192:195], v[100:103]
	v_mfma_f32_16x16x32_bf16 v[88:91], v[176:179], v[192:195], v[88:91]
	v_mfma_f32_16x16x32_bf16 v[84:87], v[168:171], v[202:205], v[84:87]
	v_mfma_f32_16x16x32_bf16 v[72:75], v[176:179], v[202:205], v[72:75]
	v_mfma_f32_16x16x32_bf16 v[68:71], v[168:171], v[210:213], v[68:71]
	v_mfma_f32_16x16x32_bf16 v[64:67], v[176:179], v[210:213], v[64:67]
	s_barrier
	s_add_i32 s83, s76, s66
	v_lshl_add_u64 v[140:141], s[60:61], 0, v[130:131]
	s_mov_b32 m0, s83
	ds_read_b128 v[180:183], v147 offset:16384
	ds_read_b128 v[184:187], v147 offset:17408
	ds_read_b128 v[188:191], v147 offset:18432
	ds_read_b128 v[192:195], v147 offset:19456
	ds_read_b128 v[196:199], v147 offset:20480
	ds_read_b128 v[202:205], v147 offset:21504
	ds_read_b128 v[206:209], v147 offset:22528
	ds_read_b128 v[210:213], v147 offset:23552
	global_load_lds_dwordx4 v[140:141], off
	s_add_i32 m0, s83, 0x2000
	s_add_u32 s84, s60, 0x40000
	v_lshl_add_u64 v[214:215], s[60:61], 0, v[128:129]
	s_addc_u32 s85, s61, 0
	s_add_i32 s83, s77, s66
	global_load_lds_dwordx4 v[214:215], off
	v_lshl_add_u64 v[216:217], s[84:85], 0, v[130:131]
	s_mov_b32 m0, s83
	v_lshl_add_u64 v[218:219], s[62:63], 0, v[128:129]
	global_load_lds_dwordx4 v[216:217], off
	v_lshl_add_u64 v[216:217], s[84:85], 0, v[128:129]
	s_add_i32 m0, s83, 0x2000
	s_nop 0
	global_load_lds_dwordx4 v[216:217], off
	v_lshl_add_u64 v[216:217], s[62:63], 0, v[130:131]
	s_mov_b32 m0, s67
	s_nop 0
	global_load_lds_dwordx4 v[216:217], off
	s_mov_b32 m0, s68
	s_nop 0
	global_load_lds_dwordx4 v[218:219], off
	s_waitcnt vmcnt(8)
	s_waitcnt lgkmcnt(0)
	s_barrier
	s_waitcnt lgkmcnt(0)
	v_mfma_f32_16x16x32_bf16 v[60:63], v[148:151], v[180:183], v[60:63]
	v_mfma_f32_16x16x32_bf16 v[56:59], v[156:159], v[180:183], v[56:59]
	v_mfma_f32_16x16x32_bf16 v[48:51], v[148:151], v[188:191], v[48:51]
	v_mfma_f32_16x16x32_bf16 v[44:47], v[156:159], v[188:191], v[44:47]
	v_mfma_f32_16x16x32_bf16 v[32:35], v[148:151], v[196:199], v[32:35]
	v_mfma_f32_16x16x32_bf16 v[28:31], v[156:159], v[196:199], v[28:31]
	v_mfma_f32_16x16x32_bf16 v[16:19], v[148:151], v[206:209], v[16:19]
	v_mfma_f32_16x16x32_bf16 v[12:15], v[156:159], v[206:209], v[12:15]
	v_mfma_f32_16x16x32_bf16 v[60:63], v[152:155], v[184:187], v[60:63]
	v_mfma_f32_16x16x32_bf16 v[56:59], v[160:163], v[184:187], v[56:59]
	v_mfma_f32_16x16x32_bf16 v[48:51], v[152:155], v[192:195], v[48:51]
	v_mfma_f32_16x16x32_bf16 v[44:47], v[160:163], v[192:195], v[44:47]
	v_mfma_f32_16x16x32_bf16 v[32:35], v[152:155], v[202:205], v[32:35]
	v_mfma_f32_16x16x32_bf16 v[28:31], v[160:163], v[202:205], v[28:31]
	v_mfma_f32_16x16x32_bf16 v[16:19], v[152:155], v[210:213], v[16:19]
	v_mfma_f32_16x16x32_bf16 v[12:15], v[160:163], v[210:213], v[12:15]
	v_mfma_f32_16x16x32_bf16 v[52:55], v[164:167], v[180:183], v[52:55]
	v_mfma_f32_16x16x32_bf16 v[40:43], v[172:175], v[180:183], v[40:43]
	v_mfma_f32_16x16x32_bf16 v[36:39], v[164:167], v[188:191], v[36:39]
	v_mfma_f32_16x16x32_bf16 v[24:27], v[172:175], v[188:191], v[24:27]
	v_mfma_f32_16x16x32_bf16 v[20:23], v[164:167], v[196:199], v[20:23]
	v_mfma_f32_16x16x32_bf16 v[8:11], v[172:175], v[196:199], v[8:11]
	v_mfma_f32_16x16x32_bf16 v[4:7], v[164:167], v[206:209], v[4:7]
	v_mfma_f32_16x16x32_bf16 v[0:3], v[172:175], v[206:209], v[0:3]
	v_mfma_f32_16x16x32_bf16 v[52:55], v[168:171], v[184:187], v[52:55]
	v_mfma_f32_16x16x32_bf16 v[40:43], v[176:179], v[184:187], v[40:43]
	v_mfma_f32_16x16x32_bf16 v[36:39], v[168:171], v[192:195], v[36:39]
	v_mfma_f32_16x16x32_bf16 v[24:27], v[176:179], v[192:195], v[24:27]
	v_mfma_f32_16x16x32_bf16 v[20:23], v[168:171], v[202:205], v[20:23]
	v_mfma_f32_16x16x32_bf16 v[8:11], v[176:179], v[202:205], v[8:11]
	v_mfma_f32_16x16x32_bf16 v[4:7], v[168:171], v[210:213], v[4:7]
	v_mfma_f32_16x16x32_bf16 v[0:3], v[176:179], v[210:213], v[0:3]
	s_barrier
	s_add_i32 s83, 0, 0x18000
	s_add_i32 s84, 0, 0x1c000
	v_add_u32_e32 v160, s83, v143
	v_add_u32_e32 v176, s84, v143
	ds_read_b128 v[148:151], v160
	ds_read_b128 v[152:155], v160 offset:1024
	ds_read_b128 v[156:159], v160 offset:2048
	ds_read_b128 v[160:163], v160 offset:3072
	ds_read_b128 v[164:167], v176
	ds_read_b128 v[168:171], v176 offset:1024
	ds_read_b128 v[172:175], v176 offset:2048
	ds_read_b128 v[176:179], v176 offset:3072
	s_add_u32 s62, s62, 0x40000
	s_addc_u32 s63, s63, 0
	s_mov_b32 m0, s69
	v_lshl_add_u64 v[220:221], s[62:63], 0, v[130:131]
	ds_read_b128 v[180:183], v147 offset:32768
	ds_read_b128 v[184:187], v147 offset:33792
	ds_read_b128 v[188:191], v147 offset:34816
	ds_read_b128 v[192:195], v147 offset:35840
	ds_read_b128 v[196:199], v147 offset:36864
	ds_read_b128 v[202:205], v147 offset:37888
	ds_read_b128 v[206:209], v147 offset:38912
	ds_read_b128 v[210:213], v147 offset:39936
	global_load_lds_dwordx4 v[220:221], off
	v_lshl_add_u64 v[220:221], s[62:63], 0, v[128:129]
	s_mov_b32 m0, s70
	s_nop 0
	global_load_lds_dwordx4 v[220:221], off
	s_waitcnt vmcnt(8)
	s_waitcnt lgkmcnt(0)
	s_barrier
	s_waitcnt lgkmcnt(0)
	v_mfma_f32_16x16x32_bf16 v[124:127], v[148:151], v[180:183], v[124:127]
	v_mfma_f32_16x16x32_bf16 v[120:123], v[156:159], v[180:183], v[120:123]
	v_mfma_f32_16x16x32_bf16 v[112:115], v[148:151], v[188:191], v[112:115]
	v_mfma_f32_16x16x32_bf16 v[108:111], v[156:159], v[188:191], v[108:111]
	v_mfma_f32_16x16x32_bf16 v[96:99], v[148:151], v[196:199], v[96:99]
	v_mfma_f32_16x16x32_bf16 v[92:95], v[156:159], v[196:199], v[92:95]
	v_mfma_f32_16x16x32_bf16 v[80:83], v[148:151], v[206:209], v[80:83]
	v_mfma_f32_16x16x32_bf16 v[76:79], v[156:159], v[206:209], v[76:79]
	v_mfma_f32_16x16x32_bf16 v[124:127], v[152:155], v[184:187], v[124:127]
	v_mfma_f32_16x16x32_bf16 v[120:123], v[160:163], v[184:187], v[120:123]
	v_mfma_f32_16x16x32_bf16 v[112:115], v[152:155], v[192:195], v[112:115]
	v_mfma_f32_16x16x32_bf16 v[108:111], v[160:163], v[192:195], v[108:111]
	v_mfma_f32_16x16x32_bf16 v[96:99], v[152:155], v[202:205], v[96:99]
	v_mfma_f32_16x16x32_bf16 v[92:95], v[160:163], v[202:205], v[92:95]
	v_mfma_f32_16x16x32_bf16 v[80:83], v[152:155], v[210:213], v[80:83]
	v_mfma_f32_16x16x32_bf16 v[76:79], v[160:163], v[210:213], v[76:79]
	v_mfma_f32_16x16x32_bf16 v[116:119], v[164:167], v[180:183], v[116:119]
	v_mfma_f32_16x16x32_bf16 v[104:107], v[172:175], v[180:183], v[104:107]
	v_mfma_f32_16x16x32_bf16 v[100:103], v[164:167], v[188:191], v[100:103]
	v_mfma_f32_16x16x32_bf16 v[88:91], v[172:175], v[188:191], v[88:91]
	v_mfma_f32_16x16x32_bf16 v[84:87], v[164:167], v[196:199], v[84:87]
	v_mfma_f32_16x16x32_bf16 v[72:75], v[172:175], v[196:199], v[72:75]
	v_mfma_f32_16x16x32_bf16 v[68:71], v[164:167], v[206:209], v[68:71]
	v_mfma_f32_16x16x32_bf16 v[64:67], v[172:175], v[206:209], v[64:67]
	v_mfma_f32_16x16x32_bf16 v[116:119], v[168:171], v[184:187], v[116:119]
	v_mfma_f32_16x16x32_bf16 v[104:107], v[176:179], v[184:187], v[104:107]
	v_mfma_f32_16x16x32_bf16 v[100:103], v[168:171], v[192:195], v[100:103]
	v_mfma_f32_16x16x32_bf16 v[88:91], v[176:179], v[192:195], v[88:91]
	v_mfma_f32_16x16x32_bf16 v[84:87], v[168:171], v[202:205], v[84:87]
	v_mfma_f32_16x16x32_bf16 v[72:75], v[176:179], v[202:205], v[72:75]
	v_mfma_f32_16x16x32_bf16 v[68:71], v[168:171], v[210:213], v[68:71]
	v_mfma_f32_16x16x32_bf16 v[64:67], v[176:179], v[210:213], v[64:67]
	s_barrier
	s_add_i32 s62, s83, s66
	v_lshl_add_u64 v[140:141], v[140:141], 0, s[6:7]
	s_mov_b32 m0, s62
	ds_read_b128 v[180:183], v147 offset:49152
	ds_read_b128 v[184:187], v147 offset:50176
	ds_read_b128 v[188:191], v147 offset:51200
	ds_read_b128 v[192:195], v147 offset:52224
	ds_read_b128 v[196:199], v147 offset:53248
	ds_read_b128 v[202:205], v147 offset:54272
	ds_read_b128 v[206:209], v147 offset:55296
	ds_read_b128 v[210:213], v147 offset:56320
	global_load_lds_dwordx4 v[140:141], off
	s_add_i32 m0, s62, 0x2000
	s_add_u32 s60, s60, 0x40080
	v_lshl_add_u64 v[140:141], v[214:215], 0, s[6:7]
	s_addc_u32 s61, s61, 0
	s_add_i32 s62, s84, s66
	global_load_lds_dwordx4 v[140:141], off
	v_lshl_add_u64 v[140:141], s[60:61], 0, v[130:131]
	s_mov_b32 m0, s62
	s_nop 0
	global_load_lds_dwordx4 v[140:141], off
	v_lshl_add_u64 v[140:141], s[60:61], 0, v[128:129]
	s_add_i32 m0, s62, 0x2000
	s_nop 0
	global_load_lds_dwordx4 v[140:141], off
	v_lshl_add_u64 v[140:141], v[216:217], 0, s[6:7]
	s_mov_b32 m0, s72
	s_nop 0
	global_load_lds_dwordx4 v[140:141], off
	v_lshl_add_u64 v[140:141], v[218:219], 0, s[6:7]
	s_mov_b32 m0, s73
	s_nop 0
	global_load_lds_dwordx4 v[140:141], off
	s_waitcnt vmcnt(8)
	s_waitcnt lgkmcnt(0)
	s_barrier
	s_waitcnt lgkmcnt(0)
	v_mfma_f32_16x16x32_bf16 v[60:63], v[148:151], v[180:183], v[60:63]
	v_mfma_f32_16x16x32_bf16 v[56:59], v[156:159], v[180:183], v[56:59]
	v_mfma_f32_16x16x32_bf16 v[48:51], v[148:151], v[188:191], v[48:51]
	v_mfma_f32_16x16x32_bf16 v[44:47], v[156:159], v[188:191], v[44:47]
	v_mfma_f32_16x16x32_bf16 v[32:35], v[148:151], v[196:199], v[32:35]
	v_mfma_f32_16x16x32_bf16 v[28:31], v[156:159], v[196:199], v[28:31]
	v_mfma_f32_16x16x32_bf16 v[16:19], v[148:151], v[206:209], v[16:19]
	v_mfma_f32_16x16x32_bf16 v[12:15], v[156:159], v[206:209], v[12:15]
	v_mfma_f32_16x16x32_bf16 v[60:63], v[152:155], v[184:187], v[60:63]
	v_mfma_f32_16x16x32_bf16 v[56:59], v[160:163], v[184:187], v[56:59]
	v_mfma_f32_16x16x32_bf16 v[48:51], v[152:155], v[192:195], v[48:51]
	v_mfma_f32_16x16x32_bf16 v[44:47], v[160:163], v[192:195], v[44:47]
	v_mfma_f32_16x16x32_bf16 v[32:35], v[152:155], v[202:205], v[32:35]
	v_mfma_f32_16x16x32_bf16 v[28:31], v[160:163], v[202:205], v[28:31]
	v_mfma_f32_16x16x32_bf16 v[16:19], v[152:155], v[210:213], v[16:19]
	v_mfma_f32_16x16x32_bf16 v[12:15], v[160:163], v[210:213], v[12:15]
	v_mfma_f32_16x16x32_bf16 v[52:55], v[164:167], v[180:183], v[52:55]
	v_mfma_f32_16x16x32_bf16 v[40:43], v[172:175], v[180:183], v[40:43]
	v_mfma_f32_16x16x32_bf16 v[36:39], v[164:167], v[188:191], v[36:39]
	v_mfma_f32_16x16x32_bf16 v[24:27], v[172:175], v[188:191], v[24:27]
	v_mfma_f32_16x16x32_bf16 v[20:23], v[164:167], v[196:199], v[20:23]
	v_mfma_f32_16x16x32_bf16 v[8:11], v[172:175], v[196:199], v[8:11]
	v_mfma_f32_16x16x32_bf16 v[4:7], v[164:167], v[206:209], v[4:7]
	v_mfma_f32_16x16x32_bf16 v[0:3], v[172:175], v[206:209], v[0:3]
	v_mfma_f32_16x16x32_bf16 v[52:55], v[168:171], v[184:187], v[52:55]
	v_mfma_f32_16x16x32_bf16 v[40:43], v[176:179], v[184:187], v[40:43]
	v_mfma_f32_16x16x32_bf16 v[36:39], v[168:171], v[192:195], v[36:39]
	v_mfma_f32_16x16x32_bf16 v[24:27], v[176:179], v[192:195], v[24:27]
	v_mfma_f32_16x16x32_bf16 v[20:23], v[168:171], v[202:205], v[20:23]
	v_mfma_f32_16x16x32_bf16 v[8:11], v[176:179], v[202:205], v[8:11]
	v_mfma_f32_16x16x32_bf16 v[4:7], v[168:171], v[210:213], v[4:7]
	v_mfma_f32_16x16x32_bf16 v[0:3], v[176:179], v[210:213], v[0:3]
	s_barrier
	s_add_i32 s82, s82, 2
	s_add_u32 s58, s58, 0x100
	s_addc_u32 s59, s59, 0
	s_add_u32 s80, s80, 0x100
	s_addc_u32 s81, s81, 0
	s_cmp_gt_u32 s82, 13
	s_cbranch_scc0 .LBB0_729
	s_setprio 0
	s_and_b64 vcc, exec, s[8:9]
	s_cbranch_vccz .LBB0_732
	s_barrier

.LBB0_865:
	s_ashr_i32 s55, s54, 31
	s_lshl_b64 s[58:59], s[54:55], 19
	s_add_u32 s58, s17, s58
	s_addc_u32 s59, s68, s59
	s_and_b64 s[60:61], s[6:7], exec
	s_cselect_b32 s55, s59, s63
	s_cselect_b32 s86, s58, s62
	s_ashr_i32 s53, s52, 31
	s_lshl_b64 s[60:61], s[52:53], 19
	s_add_u32 s60, s69, s60
	s_addc_u32 s61, s70, s61
	s_and_b64 s[66:67], s[6:7], exec
	s_cselect_b32 s53, s61, s65
	s_cselect_b32 s87, s60, s64
	s_add_u32 s62, s62, 0x40080
	s_addc_u32 s63, s63, 0
	s_add_u32 s88, s64, 0x100
	s_addc_u32 s89, s65, 0
	s_mov_b32 s90, -2
	v_mov_b64_e32 v[0:1], 0
	v_mov_b64_e32 v[2:3], 0
	v_mov_b64_e32 v[4:5], 0
	v_mov_b64_e32 v[6:7], 0
	v_mov_b64_e32 v[8:9], 0
	v_mov_b64_e32 v[10:11], 0
	v_mov_b64_e32 v[12:13], 0
	v_mov_b64_e32 v[14:15], 0
	v_mov_b64_e32 v[16:17], 0
	v_mov_b64_e32 v[18:19], 0
	v_mov_b64_e32 v[20:21], 0
	v_mov_b64_e32 v[22:23], 0
	v_mov_b64_e32 v[24:25], 0
	v_mov_b64_e32 v[26:27], 0
	v_mov_b64_e32 v[28:29], 0
	v_mov_b64_e32 v[30:31], 0
	v_mov_b64_e32 v[32:33], 0
	v_mov_b64_e32 v[34:35], 0
	v_mov_b64_e32 v[36:37], 0
	v_mov_b64_e32 v[38:39], 0
	v_mov_b64_e32 v[40:41], 0
	v_mov_b64_e32 v[42:43], 0
	v_mov_b64_e32 v[44:45], 0
	v_mov_b64_e32 v[46:47], 0
	v_mov_b64_e32 v[48:49], 0
	v_mov_b64_e32 v[50:51], 0
	v_mov_b64_e32 v[52:53], 0
	v_mov_b64_e32 v[54:55], 0
	v_mov_b64_e32 v[56:57], 0
	v_mov_b64_e32 v[58:59], 0
	v_mov_b64_e32 v[60:61], 0
	v_mov_b64_e32 v[62:63], 0
	v_mov_b64_e32 v[96:97], 0
	v_mov_b64_e32 v[98:99], 0
	v_mov_b64_e32 v[100:101], 0
	v_mov_b64_e32 v[102:103], 0
	v_mov_b64_e32 v[104:105], 0
	v_mov_b64_e32 v[106:107], 0
	v_mov_b64_e32 v[108:109], 0
	v_mov_b64_e32 v[110:111], 0
	v_mov_b64_e32 v[112:113], 0
	v_mov_b64_e32 v[114:115], 0
	v_mov_b64_e32 v[116:117], 0
	v_mov_b64_e32 v[118:119], 0
	v_mov_b64_e32 v[120:121], 0
	v_mov_b64_e32 v[122:123], 0
	v_mov_b64_e32 v[124:125], 0
	v_mov_b64_e32 v[126:127], 0
	v_mov_b64_e32 v[128:129], 0
	v_mov_b64_e32 v[130:131], 0
	v_mov_b64_e32 v[132:133], 0
	v_mov_b64_e32 v[134:135], 0
	v_mov_b64_e32 v[136:137], 0
	v_mov_b64_e32 v[138:139], 0
	v_mov_b64_e32 v[140:141], 0
	v_mov_b64_e32 v[142:143], 0
	v_mov_b64_e32 v[144:145], 0
	v_mov_b64_e32 v[146:147], 0
	v_mov_b64_e32 v[148:149], 0
	v_mov_b64_e32 v[150:151], 0
	v_mov_b64_e32 v[152:153], 0
	v_mov_b64_e32 v[154:155], 0
	v_mov_b64_e32 v[156:157], 0
	v_mov_b64_e32 v[158:159], 0
	v_lshrrev_b32_e32 v253, 8, v200
	s_nop 0
	v_readfirstlane_b32 s98, v253
	s_cmp_lg_u32 s98, 0
	s_cbranch_scc0 .Lgp_866
	s_setprio 1
.Lgp_866:
.LBB0_866:
	ds_read_b128 v[64:67], v203
	ds_read_b128 v[68:71], v203 offset:1024
	ds_read_b128 v[72:75], v203 offset:2048
	ds_read_b128 v[76:79], v203 offset:3072
	ds_read_b128 v[80:83], v204
	ds_read_b128 v[84:87], v204 offset:1024
	ds_read_b128 v[88:91], v204 offset:2048
	ds_read_b128 v[92:95], v204 offset:3072
	s_add_u32 s64, s62, 0xfffc0080
	s_addc_u32 s65, s63, -1
	s_cmp_eq_u32 s90, 12
	s_cselect_b32 s67, s55, s65
	s_cselect_b32 s66, s86, s64
	s_cselect_b32 s65, s53, s89
	s_cselect_b32 s64, s87, s88
	v_lshl_add_u64 v[220:221], s[62:63], 0, v[172:173]
	s_add_i32 m0, s73, 0xc000
	ds_read_b128 v[180:183], v205
	ds_read_b128 v[184:187], v205 offset:1024
	ds_read_b128 v[188:191], v205 offset:2048
	ds_read_b128 v[192:195], v205 offset:3072
	ds_read_b128 v[196:199], v205 offset:4096
	ds_read_b128 v[208:211], v205 offset:5120
	ds_read_b128 v[212:215], v205 offset:6144
	ds_read_b128 v[216:219], v205 offset:7168
	global_load_lds_dwordx4 v[220:221], off
	v_lshl_add_u64 v[220:221], s[62:63], 0, v[174:175]
	s_add_i32 m0, s73, 0xe000
	s_nop 0
	global_load_lds_dwordx4 v[220:221], off
	s_waitcnt vmcnt(8)
	s_waitcnt lgkmcnt(0)
	s_barrier
	s_waitcnt lgkmcnt(0)
	v_mfma_f32_16x16x32_bf16 v[148:151], v[64:67], v[180:183], v[148:151]
	v_mfma_f32_16x16x32_bf16 v[144:147], v[72:75], v[180:183], v[144:147]
	v_mfma_f32_16x16x32_bf16 v[132:135], v[64:67], v[188:191], v[132:135]
	v_mfma_f32_16x16x32_bf16 v[128:131], v[72:75], v[188:191], v[128:131]
	v_mfma_f32_16x16x32_bf16 v[116:119], v[64:67], v[196:199], v[116:119]
	v_mfma_f32_16x16x32_bf16 v[112:115], v[72:75], v[196:199], v[112:115]
	v_mfma_f32_16x16x32_bf16 v[104:107], v[64:67], v[212:215], v[104:107]
	v_mfma_f32_16x16x32_bf16 v[100:103], v[72:75], v[212:215], v[100:103]
	v_mfma_f32_16x16x32_bf16 v[148:151], v[68:71], v[184:187], v[148:151]
	v_mfma_f32_16x16x32_bf16 v[144:147], v[76:79], v[184:187], v[144:147]
	v_mfma_f32_16x16x32_bf16 v[132:135], v[68:71], v[192:195], v[132:135]
	v_mfma_f32_16x16x32_bf16 v[128:131], v[76:79], v[192:195], v[128:131]
	v_mfma_f32_16x16x32_bf16 v[116:119], v[68:71], v[208:211], v[116:119]
	v_mfma_f32_16x16x32_bf16 v[112:115], v[76:79], v[208:211], v[112:115]
	v_mfma_f32_16x16x32_bf16 v[104:107], v[68:71], v[216:219], v[104:107]
	v_mfma_f32_16x16x32_bf16 v[100:103], v[76:79], v[216:219], v[100:103]
	v_mfma_f32_16x16x32_bf16 v[152:155], v[80:83], v[180:183], v[152:155]
	v_mfma_f32_16x16x32_bf16 v[156:159], v[88:91], v[180:183], v[156:159]
	v_mfma_f32_16x16x32_bf16 v[136:139], v[80:83], v[188:191], v[136:139]
	v_mfma_f32_16x16x32_bf16 v[140:143], v[88:91], v[188:191], v[140:143]
	v_mfma_f32_16x16x32_bf16 v[120:123], v[80:83], v[196:199], v[120:123]
	v_mfma_f32_16x16x32_bf16 v[124:127], v[88:91], v[196:199], v[124:127]
	v_mfma_f32_16x16x32_bf16 v[96:99], v[80:83], v[212:215], v[96:99]
	v_mfma_f32_16x16x32_bf16 v[108:111], v[88:91], v[212:215], v[108:111]
	v_mfma_f32_16x16x32_bf16 v[152:155], v[84:87], v[184:187], v[152:155]
	v_mfma_f32_16x16x32_bf16 v[156:159], v[92:95], v[184:187], v[156:159]
	v_mfma_f32_16x16x32_bf16 v[136:139], v[84:87], v[192:195], v[136:139]
	v_mfma_f32_16x16x32_bf16 v[140:143], v[92:95], v[192:195], v[140:143]
	v_mfma_f32_16x16x32_bf16 v[120:123], v[84:87], v[208:211], v[120:123]
	v_mfma_f32_16x16x32_bf16 v[124:127], v[92:95], v[208:211], v[124:127]
	v_mfma_f32_16x16x32_bf16 v[96:99], v[84:87], v[216:219], v[96:99]
	v_mfma_f32_16x16x32_bf16 v[108:111], v[92:95], v[216:219], v[108:111]
	s_barrier
	s_add_i32 s91, s82, s72
	v_lshl_add_u64 v[220:221], s[64:65], 0, v[164:165]
	s_mov_b32 m0, s91
	ds_read_b128 v[180:183], v205 offset:16384
	ds_read_b128 v[184:187], v205 offset:17408
	ds_read_b128 v[188:191], v205 offset:18432
	ds_read_b128 v[192:195], v205 offset:19456
	ds_read_b128 v[196:199], v205 offset:20480
	ds_read_b128 v[208:211], v205 offset:21504
	ds_read_b128 v[212:215], v205 offset:22528
	ds_read_b128 v[216:219], v205 offset:23552
	global_load_lds_dwordx4 v[220:221], off
	s_add_i32 m0, s91, 0x2000
	s_add_u32 s92, s64, 0x40000
	v_lshl_add_u64 v[222:223], s[64:65], 0, v[160:161]
	s_addc_u32 s93, s65, 0
	s_add_i32 s91, s83, s72
	global_load_lds_dwordx4 v[222:223], off
	v_lshl_add_u64 v[224:225], s[92:93], 0, v[164:165]
	s_mov_b32 m0, s91
	v_lshl_add_u64 v[226:227], s[66:67], 0, v[162:163]
	global_load_lds_dwordx4 v[224:225], off
	v_lshl_add_u64 v[224:225], s[92:93], 0, v[160:161]
	s_add_i32 m0, s91, 0x2000
	s_nop 0
	global_load_lds_dwordx4 v[224:225], off
	v_lshl_add_u64 v[224:225], s[66:67], 0, v[166:167]
	s_mov_b32 m0, s73
	s_nop 0
	global_load_lds_dwordx4 v[224:225], off
	s_mov_b32 m0, s74
	s_nop 0
	global_load_lds_dwordx4 v[226:227], off
	s_waitcnt vmcnt(8)
	s_waitcnt lgkmcnt(0)
	s_barrier
	s_waitcnt lgkmcnt(0)
	v_mfma_f32_16x16x32_bf16 v[52:55], v[64:67], v[180:183], v[52:55]
	v_mfma_f32_16x16x32_bf16 v[48:51], v[72:75], v[180:183], v[48:51]
	v_mfma_f32_16x16x32_bf16 v[36:39], v[64:67], v[188:191], v[36:39]
	v_mfma_f32_16x16x32_bf16 v[32:35], v[72:75], v[188:191], v[32:35]
	v_mfma_f32_16x16x32_bf16 v[20:23], v[64:67], v[196:199], v[20:23]
	v_mfma_f32_16x16x32_bf16 v[16:19], v[72:75], v[196:199], v[16:19]
	v_mfma_f32_16x16x32_bf16 v[8:11], v[64:67], v[212:215], v[8:11]
	v_mfma_f32_16x16x32_bf16 v[4:7], v[72:75], v[212:215], v[4:7]
	v_mfma_f32_16x16x32_bf16 v[52:55], v[68:71], v[184:187], v[52:55]
	v_mfma_f32_16x16x32_bf16 v[48:51], v[76:79], v[184:187], v[48:51]
	v_mfma_f32_16x16x32_bf16 v[36:39], v[68:71], v[192:195], v[36:39]
	v_mfma_f32_16x16x32_bf16 v[32:35], v[76:79], v[192:195], v[32:35]
	v_mfma_f32_16x16x32_bf16 v[20:23], v[68:71], v[208:211], v[20:23]
	v_mfma_f32_16x16x32_bf16 v[16:19], v[76:79], v[208:211], v[16:19]
	v_mfma_f32_16x16x32_bf16 v[8:11], v[68:71], v[216:219], v[8:11]
	v_mfma_f32_16x16x32_bf16 v[4:7], v[76:79], v[216:219], v[4:7]
	v_mfma_f32_16x16x32_bf16 v[56:59], v[80:83], v[180:183], v[56:59]
	v_mfma_f32_16x16x32_bf16 v[60:63], v[88:91], v[180:183], v[60:63]
	v_mfma_f32_16x16x32_bf16 v[40:43], v[80:83], v[188:191], v[40:43]
	v_mfma_f32_16x16x32_bf16 v[44:47], v[88:91], v[188:191], v[44:47]
	v_mfma_f32_16x16x32_bf16 v[24:27], v[80:83], v[196:199], v[24:27]
	v_mfma_f32_16x16x32_bf16 v[28:31], v[88:91], v[196:199], v[28:31]
	v_mfma_f32_16x16x32_bf16 v[0:3], v[80:83], v[212:215], v[0:3]
	v_mfma_f32_16x16x32_bf16 v[12:15], v[88:91], v[212:215], v[12:15]
	v_mfma_f32_16x16x32_bf16 v[56:59], v[84:87], v[184:187], v[56:59]
	v_mfma_f32_16x16x32_bf16 v[60:63], v[92:95], v[184:187], v[60:63]
	v_mfma_f32_16x16x32_bf16 v[40:43], v[84:87], v[192:195], v[40:43]
	v_mfma_f32_16x16x32_bf16 v[44:47], v[92:95], v[192:195], v[44:47]
	v_mfma_f32_16x16x32_bf16 v[24:27], v[84:87], v[208:211], v[24:27]
	v_mfma_f32_16x16x32_bf16 v[28:31], v[92:95], v[208:211], v[28:31]
	v_mfma_f32_16x16x32_bf16 v[0:3], v[84:87], v[216:219], v[0:3]
	v_mfma_f32_16x16x32_bf16 v[12:15], v[92:95], v[216:219], v[12:15]
	s_barrier
	s_add_i32 s91, 0, 0x18000
	s_add_i32 s92, 0, 0x1c000
	v_add_u32_e32 v76, s91, v201
	v_add_u32_e32 v92, s92, v201
	ds_read_b128 v[64:67], v76
	ds_read_b128 v[68:71], v76 offset:1024
	ds_read_b128 v[72:75], v76 offset:2048
	ds_read_b128 v[76:79], v76 offset:3072
	ds_read_b128 v[80:83], v92
	ds_read_b128 v[84:87], v92 offset:1024
	ds_read_b128 v[88:91], v92 offset:2048
	ds_read_b128 v[92:95], v92 offset:3072
	s_add_u32 s66, s66, 0x40000
	s_addc_u32 s67, s67, 0
	s_mov_b32 m0, s75
	v_lshl_add_u64 v[228:229], s[66:67], 0, v[166:167]
	ds_read_b128 v[180:183], v205 offset:32768
	ds_read_b128 v[184:187], v205 offset:33792
	ds_read_b128 v[188:191], v205 offset:34816
	ds_read_b128 v[192:195], v205 offset:35840
	ds_read_b128 v[196:199], v205 offset:36864
	ds_read_b128 v[208:211], v205 offset:37888
	ds_read_b128 v[212:215], v205 offset:38912
	ds_read_b128 v[216:219], v205 offset:39936
	global_load_lds_dwordx4 v[228:229], off
	v_lshl_add_u64 v[228:229], s[66:67], 0, v[162:163]
	s_mov_b32 m0, s76
	s_nop 0
	global_load_lds_dwordx4 v[228:229], off
	s_waitcnt vmcnt(8)
	s_waitcnt lgkmcnt(0)
	s_barrier
	s_waitcnt lgkmcnt(0)
	v_mfma_f32_16x16x32_bf16 v[148:151], v[64:67], v[180:183], v[148:151]
	v_mfma_f32_16x16x32_bf16 v[144:147], v[72:75], v[180:183], v[144:147]
	v_mfma_f32_16x16x32_bf16 v[132:135], v[64:67], v[188:191], v[132:135]
	v_mfma_f32_16x16x32_bf16 v[128:131], v[72:75], v[188:191], v[128:131]
	v_mfma_f32_16x16x32_bf16 v[116:119], v[64:67], v[196:199], v[116:119]
	v_mfma_f32_16x16x32_bf16 v[112:115], v[72:75], v[196:199], v[112:115]
	v_mfma_f32_16x16x32_bf16 v[104:107], v[64:67], v[212:215], v[104:107]
	v_mfma_f32_16x16x32_bf16 v[100:103], v[72:75], v[212:215], v[100:103]
	v_mfma_f32_16x16x32_bf16 v[148:151], v[68:71], v[184:187], v[148:151]
	v_mfma_f32_16x16x32_bf16 v[144:147], v[76:79], v[184:187], v[144:147]
	v_mfma_f32_16x16x32_bf16 v[132:135], v[68:71], v[192:195], v[132:135]
	v_mfma_f32_16x16x32_bf16 v[128:131], v[76:79], v[192:195], v[128:131]
	v_mfma_f32_16x16x32_bf16 v[116:119], v[68:71], v[208:211], v[116:119]
	v_mfma_f32_16x16x32_bf16 v[112:115], v[76:79], v[208:211], v[112:115]
	v_mfma_f32_16x16x32_bf16 v[104:107], v[68:71], v[216:219], v[104:107]
	v_mfma_f32_16x16x32_bf16 v[100:103], v[76:79], v[216:219], v[100:103]
	v_mfma_f32_16x16x32_bf16 v[152:155], v[80:83], v[180:183], v[152:155]
	v_mfma_f32_16x16x32_bf16 v[156:159], v[88:91], v[180:183], v[156:159]
	v_mfma_f32_16x16x32_bf16 v[136:139], v[80:83], v[188:191], v[136:139]
	v_mfma_f32_16x16x32_bf16 v[140:143], v[88:91], v[188:191], v[140:143]
	v_mfma_f32_16x16x32_bf16 v[120:123], v[80:83], v[196:199], v[120:123]
	v_mfma_f32_16x16x32_bf16 v[124:127], v[88:91], v[196:199], v[124:127]
	v_mfma_f32_16x16x32_bf16 v[96:99], v[80:83], v[212:215], v[96:99]
	v_mfma_f32_16x16x32_bf16 v[108:111], v[88:91], v[212:215], v[108:111]
	v_mfma_f32_16x16x32_bf16 v[152:155], v[84:87], v[184:187], v[152:155]
	v_mfma_f32_16x16x32_bf16 v[156:159], v[92:95], v[184:187], v[156:159]
	v_mfma_f32_16x16x32_bf16 v[136:139], v[84:87], v[192:195], v[136:139]
	v_mfma_f32_16x16x32_bf16 v[140:143], v[92:95], v[192:195], v[140:143]
	v_mfma_f32_16x16x32_bf16 v[120:123], v[84:87], v[208:211], v[120:123]
	v_mfma_f32_16x16x32_bf16 v[124:127], v[92:95], v[208:211], v[124:127]
	v_mfma_f32_16x16x32_bf16 v[96:99], v[84:87], v[216:219], v[96:99]
	v_mfma_f32_16x16x32_bf16 v[108:111], v[92:95], v[216:219], v[108:111]
	s_barrier
	s_add_i32 s66, s91, s72
	v_lshl_add_u64 v[220:221], v[220:221], 0, s[20:21]
	s_mov_b32 m0, s66
	ds_read_b128 v[180:183], v205 offset:49152
	ds_read_b128 v[184:187], v205 offset:50176
	ds_read_b128 v[188:191], v205 offset:51200
	ds_read_b128 v[192:195], v205 offset:52224
	ds_read_b128 v[196:199], v205 offset:53248
	ds_read_b128 v[208:211], v205 offset:54272
	ds_read_b128 v[212:215], v205 offset:55296
	ds_read_b128 v[216:219], v205 offset:56320
	global_load_lds_dwordx4 v[220:221], off
	s_add_i32 m0, s66, 0x2000
	s_add_u32 s64, s64, 0x40080
	v_lshl_add_u64 v[220:221], v[222:223], 0, s[20:21]
	s_addc_u32 s65, s65, 0
	s_add_i32 s66, s92, s72
	global_load_lds_dwordx4 v[220:221], off
	v_lshl_add_u64 v[220:221], s[64:65], 0, v[164:165]
	s_mov_b32 m0, s66
	s_nop 0
	global_load_lds_dwordx4 v[220:221], off
	v_lshl_add_u64 v[220:221], s[64:65], 0, v[160:161]
	s_add_i32 m0, s66, 0x2000
	s_nop 0
	global_load_lds_dwordx4 v[220:221], off
	v_lshl_add_u64 v[220:221], v[224:225], 0, s[20:21]
	s_mov_b32 m0, s78
	s_nop 0
	global_load_lds_dwordx4 v[220:221], off
	v_lshl_add_u64 v[220:221], v[226:227], 0, s[20:21]
	s_mov_b32 m0, s79
	s_nop 0
	global_load_lds_dwordx4 v[220:221], off
	s_waitcnt vmcnt(8)
	s_waitcnt lgkmcnt(0)
	s_barrier
	s_waitcnt lgkmcnt(0)
	v_mfma_f32_16x16x32_bf16 v[52:55], v[64:67], v[180:183], v[52:55]
	v_mfma_f32_16x16x32_bf16 v[48:51], v[72:75], v[180:183], v[48:51]
	v_mfma_f32_16x16x32_bf16 v[36:39], v[64:67], v[188:191], v[36:39]
	v_mfma_f32_16x16x32_bf16 v[32:35], v[72:75], v[188:191], v[32:35]
	v_mfma_f32_16x16x32_bf16 v[20:23], v[64:67], v[196:199], v[20:23]
	v_mfma_f32_16x16x32_bf16 v[16:19], v[72:75], v[196:199], v[16:19]
	v_mfma_f32_16x16x32_bf16 v[8:11], v[64:67], v[212:215], v[8:11]
	v_mfma_f32_16x16x32_bf16 v[4:7], v[72:75], v[212:215], v[4:7]
	v_mfma_f32_16x16x32_bf16 v[52:55], v[68:71], v[184:187], v[52:55]
	v_mfma_f32_16x16x32_bf16 v[48:51], v[76:79], v[184:187], v[48:51]
	v_mfma_f32_16x16x32_bf16 v[36:39], v[68:71], v[192:195], v[36:39]
	v_mfma_f32_16x16x32_bf16 v[32:35], v[76:79], v[192:195], v[32:35]
	v_mfma_f32_16x16x32_bf16 v[20:23], v[68:71], v[208:211], v[20:23]
	v_mfma_f32_16x16x32_bf16 v[16:19], v[76:79], v[208:211], v[16:19]
	v_mfma_f32_16x16x32_bf16 v[8:11], v[68:71], v[216:219], v[8:11]
	v_mfma_f32_16x16x32_bf16 v[4:7], v[76:79], v[216:219], v[4:7]
	v_mfma_f32_16x16x32_bf16 v[56:59], v[80:83], v[180:183], v[56:59]
	v_mfma_f32_16x16x32_bf16 v[60:63], v[88:91], v[180:183], v[60:63]
	v_mfma_f32_16x16x32_bf16 v[40:43], v[80:83], v[188:191], v[40:43]
	v_mfma_f32_16x16x32_bf16 v[44:47], v[88:91], v[188:191], v[44:47]
	v_mfma_f32_16x16x32_bf16 v[24:27], v[80:83], v[196:199], v[24:27]
	v_mfma_f32_16x16x32_bf16 v[28:31], v[88:91], v[196:199], v[28:31]
	v_mfma_f32_16x16x32_bf16 v[0:3], v[80:83], v[212:215], v[0:3]
	v_mfma_f32_16x16x32_bf16 v[12:15], v[88:91], v[212:215], v[12:15]
	v_mfma_f32_16x16x32_bf16 v[56:59], v[84:87], v[184:187], v[56:59]
	v_mfma_f32_16x16x32_bf16 v[60:63], v[92:95], v[184:187], v[60:63]
	v_mfma_f32_16x16x32_bf16 v[40:43], v[84:87], v[192:195], v[40:43]
	v_mfma_f32_16x16x32_bf16 v[44:47], v[92:95], v[192:195], v[44:47]
	v_mfma_f32_16x16x32_bf16 v[24:27], v[84:87], v[208:211], v[24:27]
	v_mfma_f32_16x16x32_bf16 v[28:31], v[92:95], v[208:211], v[28:31]
	v_mfma_f32_16x16x32_bf16 v[0:3], v[84:87], v[216:219], v[0:3]
	v_mfma_f32_16x16x32_bf16 v[12:15], v[92:95], v[216:219], v[12:15]
	s_barrier
	s_add_i32 s90, s90, 2
	s_add_u32 s62, s62, 0x100
	s_addc_u32 s63, s63, 0
	s_add_u32 s88, s88, 0x100
	s_addc_u32 s89, s89, 0
	s_cmp_gt_u32 s90, 13
	s_cbranch_scc0 .LBB0_866
	s_setprio 0
	s_and_b64 vcc, exec, s[34:35]
	s_cbranch_vccz .LBB0_869
	s_barrier

.LBB0_1017:
	s_add_u32 s52, s52, 0xb0080
	s_addc_u32 s53, s53, 0
	s_add_u32 s76, s54, 0x100
	s_addc_u32 s77, s55, 0
	s_mov_b32 s78, -2
	v_mov_b64_e32 v[0:1], 0
	v_mov_b64_e32 v[2:3], 0
	v_mov_b64_e32 v[4:5], 0
	v_mov_b64_e32 v[6:7], 0
	v_mov_b64_e32 v[8:9], 0
	v_mov_b64_e32 v[10:11], 0
	v_mov_b64_e32 v[12:13], 0
	v_mov_b64_e32 v[14:15], 0
	v_mov_b64_e32 v[16:17], 0
	v_mov_b64_e32 v[18:19], 0
	v_mov_b64_e32 v[20:21], 0
	v_mov_b64_e32 v[22:23], 0
	v_mov_b64_e32 v[24:25], 0
	v_mov_b64_e32 v[26:27], 0
	v_mov_b64_e32 v[28:29], 0
	v_mov_b64_e32 v[30:31], 0
	v_mov_b64_e32 v[32:33], 0
	v_mov_b64_e32 v[34:35], 0
	v_mov_b64_e32 v[36:37], 0
	v_mov_b64_e32 v[38:39], 0
	v_mov_b64_e32 v[40:41], 0
	v_mov_b64_e32 v[42:43], 0
	v_mov_b64_e32 v[44:45], 0
	v_mov_b64_e32 v[46:47], 0
	v_mov_b64_e32 v[48:49], 0
	v_mov_b64_e32 v[50:51], 0
	v_mov_b64_e32 v[52:53], 0
	v_mov_b64_e32 v[54:55], 0
	v_mov_b64_e32 v[56:57], 0
	v_mov_b64_e32 v[58:59], 0
	v_mov_b64_e32 v[60:61], 0
	v_mov_b64_e32 v[62:63], 0
	v_mov_b64_e32 v[64:65], 0
	v_mov_b64_e32 v[66:67], 0
	v_mov_b64_e32 v[68:69], 0
	v_mov_b64_e32 v[70:71], 0
	v_mov_b64_e32 v[72:73], 0
	v_mov_b64_e32 v[74:75], 0
	v_mov_b64_e32 v[76:77], 0
	v_mov_b64_e32 v[78:79], 0
	v_mov_b64_e32 v[80:81], 0
	v_mov_b64_e32 v[82:83], 0
	v_mov_b64_e32 v[84:85], 0
	v_mov_b64_e32 v[86:87], 0
	v_mov_b64_e32 v[88:89], 0
	v_mov_b64_e32 v[90:91], 0
	v_mov_b64_e32 v[92:93], 0
	v_mov_b64_e32 v[94:95], 0
	v_mov_b64_e32 v[96:97], 0
	v_mov_b64_e32 v[98:99], 0
	v_mov_b64_e32 v[100:101], 0
	v_mov_b64_e32 v[102:103], 0
	v_mov_b64_e32 v[104:105], 0
	v_mov_b64_e32 v[106:107], 0
	v_mov_b64_e32 v[108:109], 0
	v_mov_b64_e32 v[110:111], 0
	v_mov_b64_e32 v[112:113], 0
	v_mov_b64_e32 v[114:115], 0
	v_mov_b64_e32 v[116:117], 0
	v_mov_b64_e32 v[118:119], 0
	v_mov_b64_e32 v[120:121], 0
	v_mov_b64_e32 v[122:123], 0
	v_mov_b64_e32 v[124:125], 0
	v_mov_b64_e32 v[126:127], 0
	v_lshrrev_b32_e32 v253, 8, v200
	s_nop 0
	v_readfirstlane_b32 s98, v253
	s_cmp_lg_u32 s98, 0
	s_cbranch_scc0 .Lgp_1018
	s_setprio 1
.Lgp_1018:
.LBB0_1018:
	ds_read_b128 v[140:143], v149
	ds_read_b128 v[152:155], v149 offset:1024
	ds_read_b128 v[156:159], v149 offset:2048
	ds_read_b128 v[160:163], v149 offset:3072
	ds_read_b128 v[164:167], v150
	ds_read_b128 v[168:171], v150 offset:1024
	ds_read_b128 v[172:175], v150 offset:2048
	ds_read_b128 v[176:179], v150 offset:3072
	s_add_u32 s54, s52, 0xfff50080
	s_addc_u32 s55, s53, -1
	s_cmp_eq_u32 s78, 40
	s_cselect_b32 s59, s5, s55
	s_cselect_b32 s58, s4, s54
	s_cselect_b32 s55, s51, s77
	s_cselect_b32 s54, s50, s76
	v_lshl_add_u64 v[144:145], s[52:53], 0, v[132:133]
	s_add_i32 m0, s63, 0xc000
	ds_read_b128 v[180:183], v151
	ds_read_b128 v[184:187], v151 offset:1024
	ds_read_b128 v[188:191], v151 offset:2048
	ds_read_b128 v[192:195], v151 offset:3072
	ds_read_b128 v[196:199], v151 offset:4096
	ds_read_b128 v[202:205], v151 offset:5120
	ds_read_b128 v[206:209], v151 offset:6144
	ds_read_b128 v[210:213], v151 offset:7168
	global_load_lds_dwordx4 v[144:145], off
	v_lshl_add_u64 v[144:145], s[52:53], 0, v[134:135]
	s_add_i32 m0, s63, 0xe000
	s_nop 0
	global_load_lds_dwordx4 v[144:145], off
	s_waitcnt vmcnt(8)
	s_waitcnt lgkmcnt(0)
	s_barrier
	s_waitcnt lgkmcnt(0)
	v_mfma_f32_16x16x32_bf16 v[124:127], v[140:143], v[180:183], v[124:127]
	v_mfma_f32_16x16x32_bf16 v[120:123], v[156:159], v[180:183], v[120:123]
	v_mfma_f32_16x16x32_bf16 v[112:115], v[140:143], v[188:191], v[112:115]
	v_mfma_f32_16x16x32_bf16 v[104:107], v[156:159], v[188:191], v[104:107]
	v_mfma_f32_16x16x32_bf16 v[96:99], v[140:143], v[196:199], v[96:99]
	v_mfma_f32_16x16x32_bf16 v[88:91], v[156:159], v[196:199], v[88:91]
	v_mfma_f32_16x16x32_bf16 v[80:83], v[140:143], v[206:209], v[80:83]
	v_mfma_f32_16x16x32_bf16 v[72:75], v[156:159], v[206:209], v[72:75]
	v_mfma_f32_16x16x32_bf16 v[124:127], v[152:155], v[184:187], v[124:127]
	v_mfma_f32_16x16x32_bf16 v[120:123], v[160:163], v[184:187], v[120:123]
	v_mfma_f32_16x16x32_bf16 v[112:115], v[152:155], v[192:195], v[112:115]
	v_mfma_f32_16x16x32_bf16 v[104:107], v[160:163], v[192:195], v[104:107]
	v_mfma_f32_16x16x32_bf16 v[96:99], v[152:155], v[202:205], v[96:99]
	v_mfma_f32_16x16x32_bf16 v[88:91], v[160:163], v[202:205], v[88:91]
	v_mfma_f32_16x16x32_bf16 v[80:83], v[152:155], v[210:213], v[80:83]
	v_mfma_f32_16x16x32_bf16 v[72:75], v[160:163], v[210:213], v[72:75]
	v_mfma_f32_16x16x32_bf16 v[116:119], v[164:167], v[180:183], v[116:119]
	v_mfma_f32_16x16x32_bf16 v[108:111], v[172:175], v[180:183], v[108:111]
	v_mfma_f32_16x16x32_bf16 v[100:103], v[164:167], v[188:191], v[100:103]
	v_mfma_f32_16x16x32_bf16 v[92:95], v[172:175], v[188:191], v[92:95]
	v_mfma_f32_16x16x32_bf16 v[84:87], v[164:167], v[196:199], v[84:87]
	v_mfma_f32_16x16x32_bf16 v[76:79], v[172:175], v[196:199], v[76:79]
	v_mfma_f32_16x16x32_bf16 v[68:71], v[164:167], v[206:209], v[68:71]
	v_mfma_f32_16x16x32_bf16 v[64:67], v[172:175], v[206:209], v[64:67]
	v_mfma_f32_16x16x32_bf16 v[116:119], v[168:171], v[184:187], v[116:119]
	v_mfma_f32_16x16x32_bf16 v[108:111], v[176:179], v[184:187], v[108:111]
	v_mfma_f32_16x16x32_bf16 v[100:103], v[168:171], v[192:195], v[100:103]
	v_mfma_f32_16x16x32_bf16 v[92:95], v[176:179], v[192:195], v[92:95]
	v_mfma_f32_16x16x32_bf16 v[84:87], v[168:171], v[202:205], v[84:87]
	v_mfma_f32_16x16x32_bf16 v[76:79], v[176:179], v[202:205], v[76:79]
	v_mfma_f32_16x16x32_bf16 v[68:71], v[168:171], v[210:213], v[68:71]
	v_mfma_f32_16x16x32_bf16 v[64:67], v[176:179], v[210:213], v[64:67]
	s_barrier
	s_add_i32 s79, s72, s62
	v_lshl_add_u64 v[144:145], s[54:55], 0, v[130:131]
	s_mov_b32 m0, s79
	ds_read_b128 v[180:183], v151 offset:16384
	ds_read_b128 v[184:187], v151 offset:17408
	ds_read_b128 v[188:191], v151 offset:18432
	ds_read_b128 v[192:195], v151 offset:19456
	ds_read_b128 v[196:199], v151 offset:20480
	ds_read_b128 v[202:205], v151 offset:21504
	ds_read_b128 v[206:209], v151 offset:22528
	ds_read_b128 v[210:213], v151 offset:23552
	global_load_lds_dwordx4 v[144:145], off
	s_add_i32 m0, s79, 0x2000
	s_add_u32 s80, s54, 0xb0000
	v_lshl_add_u64 v[214:215], s[54:55], 0, v[128:129]
	s_addc_u32 s81, s55, 0
	s_add_i32 s79, s73, s62
	global_load_lds_dwordx4 v[214:215], off
	v_lshl_add_u64 v[216:217], s[80:81], 0, v[130:131]
	s_mov_b32 m0, s79
	v_lshl_add_u64 v[218:219], s[58:59], 0, v[128:129]
	global_load_lds_dwordx4 v[216:217], off
	v_lshl_add_u64 v[216:217], s[80:81], 0, v[128:129]
	s_add_i32 m0, s79, 0x2000
	s_nop 0
	global_load_lds_dwordx4 v[216:217], off
	v_lshl_add_u64 v[216:217], s[58:59], 0, v[130:131]
	s_mov_b32 m0, s63
	s_nop 0
	global_load_lds_dwordx4 v[216:217], off
	s_mov_b32 m0, s64
	s_nop 0
	global_load_lds_dwordx4 v[218:219], off
	s_waitcnt vmcnt(8)
	s_waitcnt lgkmcnt(0)
	s_barrier
	s_waitcnt lgkmcnt(0)
	v_mfma_f32_16x16x32_bf16 v[60:63], v[140:143], v[180:183], v[60:63]
	v_mfma_f32_16x16x32_bf16 v[56:59], v[156:159], v[180:183], v[56:59]
	v_mfma_f32_16x16x32_bf16 v[48:51], v[140:143], v[188:191], v[48:51]
	v_mfma_f32_16x16x32_bf16 v[40:43], v[156:159], v[188:191], v[40:43]
	v_mfma_f32_16x16x32_bf16 v[32:35], v[140:143], v[196:199], v[32:35]
	v_mfma_f32_16x16x32_bf16 v[24:27], v[156:159], v[196:199], v[24:27]
	v_mfma_f32_16x16x32_bf16 v[16:19], v[140:143], v[206:209], v[16:19]
	v_mfma_f32_16x16x32_bf16 v[8:11], v[156:159], v[206:209], v[8:11]
	v_mfma_f32_16x16x32_bf16 v[60:63], v[152:155], v[184:187], v[60:63]
	v_mfma_f32_16x16x32_bf16 v[56:59], v[160:163], v[184:187], v[56:59]
	v_mfma_f32_16x16x32_bf16 v[48:51], v[152:155], v[192:195], v[48:51]
	v_mfma_f32_16x16x32_bf16 v[40:43], v[160:163], v[192:195], v[40:43]
	v_mfma_f32_16x16x32_bf16 v[32:35], v[152:155], v[202:205], v[32:35]
	v_mfma_f32_16x16x32_bf16 v[24:27], v[160:163], v[202:205], v[24:27]
	v_mfma_f32_16x16x32_bf16 v[16:19], v[152:155], v[210:213], v[16:19]
	v_mfma_f32_16x16x32_bf16 v[8:11], v[160:163], v[210:213], v[8:11]
	v_mfma_f32_16x16x32_bf16 v[52:55], v[164:167], v[180:183], v[52:55]
	v_mfma_f32_16x16x32_bf16 v[44:47], v[172:175], v[180:183], v[44:47]
	v_mfma_f32_16x16x32_bf16 v[36:39], v[164:167], v[188:191], v[36:39]
	v_mfma_f32_16x16x32_bf16 v[28:31], v[172:175], v[188:191], v[28:31]
	v_mfma_f32_16x16x32_bf16 v[20:23], v[164:167], v[196:199], v[20:23]
	v_mfma_f32_16x16x32_bf16 v[12:15], v[172:175], v[196:199], v[12:15]
	v_mfma_f32_16x16x32_bf16 v[4:7], v[164:167], v[206:209], v[4:7]
	v_mfma_f32_16x16x32_bf16 v[0:3], v[172:175], v[206:209], v[0:3]
	v_mfma_f32_16x16x32_bf16 v[52:55], v[168:171], v[184:187], v[52:55]
	v_mfma_f32_16x16x32_bf16 v[44:47], v[176:179], v[184:187], v[44:47]
	v_mfma_f32_16x16x32_bf16 v[36:39], v[168:171], v[192:195], v[36:39]
	v_mfma_f32_16x16x32_bf16 v[28:31], v[176:179], v[192:195], v[28:31]
	v_mfma_f32_16x16x32_bf16 v[20:23], v[168:171], v[202:205], v[20:23]
	v_mfma_f32_16x16x32_bf16 v[12:15], v[176:179], v[202:205], v[12:15]
	v_mfma_f32_16x16x32_bf16 v[4:7], v[168:171], v[210:213], v[4:7]
	v_mfma_f32_16x16x32_bf16 v[0:3], v[176:179], v[210:213], v[0:3]
	s_barrier
	s_add_i32 s79, 0, 0x18000
	s_add_i32 s80, 0, 0x1c000
	v_add_u32_e32 v160, s79, v147
	v_add_u32_e32 v176, s80, v147
	ds_read_b128 v[140:143], v160
	ds_read_b128 v[152:155], v160 offset:1024
	ds_read_b128 v[156:159], v160 offset:2048
	ds_read_b128 v[160:163], v160 offset:3072
	ds_read_b128 v[164:167], v176
	ds_read_b128 v[168:171], v176 offset:1024
	ds_read_b128 v[172:175], v176 offset:2048
	ds_read_b128 v[176:179], v176 offset:3072
	s_add_u32 s58, s58, 0xb0000
	s_addc_u32 s59, s59, 0
	s_mov_b32 m0, s65
	v_lshl_add_u64 v[220:221], s[58:59], 0, v[130:131]
	ds_read_b128 v[180:183], v151 offset:32768
	ds_read_b128 v[184:187], v151 offset:33792
	ds_read_b128 v[188:191], v151 offset:34816
	ds_read_b128 v[192:195], v151 offset:35840
	ds_read_b128 v[196:199], v151 offset:36864
	ds_read_b128 v[202:205], v151 offset:37888
	ds_read_b128 v[206:209], v151 offset:38912
	ds_read_b128 v[210:213], v151 offset:39936
	global_load_lds_dwordx4 v[220:221], off
	v_lshl_add_u64 v[220:221], s[58:59], 0, v[128:129]
	s_mov_b32 m0, s66
	s_nop 0
	global_load_lds_dwordx4 v[220:221], off
	s_waitcnt vmcnt(8)
	s_waitcnt lgkmcnt(0)
	s_barrier
	s_waitcnt lgkmcnt(0)
	v_mfma_f32_16x16x32_bf16 v[124:127], v[140:143], v[180:183], v[124:127]
	v_mfma_f32_16x16x32_bf16 v[120:123], v[156:159], v[180:183], v[120:123]
	v_mfma_f32_16x16x32_bf16 v[112:115], v[140:143], v[188:191], v[112:115]
	v_mfma_f32_16x16x32_bf16 v[104:107], v[156:159], v[188:191], v[104:107]
	v_mfma_f32_16x16x32_bf16 v[96:99], v[140:143], v[196:199], v[96:99]
	v_mfma_f32_16x16x32_bf16 v[88:91], v[156:159], v[196:199], v[88:91]
	v_mfma_f32_16x16x32_bf16 v[80:83], v[140:143], v[206:209], v[80:83]
	v_mfma_f32_16x16x32_bf16 v[72:75], v[156:159], v[206:209], v[72:75]
	v_mfma_f32_16x16x32_bf16 v[124:127], v[152:155], v[184:187], v[124:127]
	v_mfma_f32_16x16x32_bf16 v[120:123], v[160:163], v[184:187], v[120:123]
	v_mfma_f32_16x16x32_bf16 v[112:115], v[152:155], v[192:195], v[112:115]
	v_mfma_f32_16x16x32_bf16 v[104:107], v[160:163], v[192:195], v[104:107]
	v_mfma_f32_16x16x32_bf16 v[96:99], v[152:155], v[202:205], v[96:99]
	v_mfma_f32_16x16x32_bf16 v[88:91], v[160:163], v[202:205], v[88:91]
	v_mfma_f32_16x16x32_bf16 v[80:83], v[152:155], v[210:213], v[80:83]
	v_mfma_f32_16x16x32_bf16 v[72:75], v[160:163], v[210:213], v[72:75]
	v_mfma_f32_16x16x32_bf16 v[116:119], v[164:167], v[180:183], v[116:119]
	v_mfma_f32_16x16x32_bf16 v[108:111], v[172:175], v[180:183], v[108:111]
	v_mfma_f32_16x16x32_bf16 v[100:103], v[164:167], v[188:191], v[100:103]
	v_mfma_f32_16x16x32_bf16 v[92:95], v[172:175], v[188:191], v[92:95]
	v_mfma_f32_16x16x32_bf16 v[84:87], v[164:167], v[196:199], v[84:87]
	v_mfma_f32_16x16x32_bf16 v[76:79], v[172:175], v[196:199], v[76:79]
	v_mfma_f32_16x16x32_bf16 v[68:71], v[164:167], v[206:209], v[68:71]
	v_mfma_f32_16x16x32_bf16 v[64:67], v[172:175], v[206:209], v[64:67]
	v_mfma_f32_16x16x32_bf16 v[116:119], v[168:171], v[184:187], v[116:119]
	v_mfma_f32_16x16x32_bf16 v[108:111], v[176:179], v[184:187], v[108:111]
	v_mfma_f32_16x16x32_bf16 v[100:103], v[168:171], v[192:195], v[100:103]
	v_mfma_f32_16x16x32_bf16 v[92:95], v[176:179], v[192:195], v[92:95]
	v_mfma_f32_16x16x32_bf16 v[84:87], v[168:171], v[202:205], v[84:87]
	v_mfma_f32_16x16x32_bf16 v[76:79], v[176:179], v[202:205], v[76:79]
	v_mfma_f32_16x16x32_bf16 v[68:71], v[168:171], v[210:213], v[68:71]
	v_mfma_f32_16x16x32_bf16 v[64:67], v[176:179], v[210:213], v[64:67]
	s_barrier
	s_add_i32 s58, s79, s62
	v_lshl_add_u64 v[144:145], v[144:145], 0, s[10:11]
	s_mov_b32 m0, s58
	ds_read_b128 v[180:183], v151 offset:49152
	ds_read_b128 v[184:187], v151 offset:50176
	ds_read_b128 v[188:191], v151 offset:51200
	ds_read_b128 v[192:195], v151 offset:52224
	ds_read_b128 v[196:199], v151 offset:53248
	ds_read_b128 v[202:205], v151 offset:54272
	ds_read_b128 v[206:209], v151 offset:55296
	ds_read_b128 v[210:213], v151 offset:56320
	global_load_lds_dwordx4 v[144:145], off
	s_add_i32 m0, s58, 0x2000
	s_add_u32 s54, s54, 0xb0080
	v_lshl_add_u64 v[144:145], v[214:215], 0, s[10:11]
	s_addc_u32 s55, s55, 0
	s_add_i32 s58, s80, s62
	global_load_lds_dwordx4 v[144:145], off
	v_lshl_add_u64 v[144:145], s[54:55], 0, v[130:131]
	s_mov_b32 m0, s58
	s_nop 0
	global_load_lds_dwordx4 v[144:145], off
	v_lshl_add_u64 v[144:145], s[54:55], 0, v[128:129]
	s_add_i32 m0, s58, 0x2000
	s_nop 0
	global_load_lds_dwordx4 v[144:145], off
	v_lshl_add_u64 v[144:145], v[216:217], 0, s[10:11]
	s_mov_b32 m0, s68
	s_nop 0
	global_load_lds_dwordx4 v[144:145], off
	v_lshl_add_u64 v[144:145], v[218:219], 0, s[10:11]
	s_mov_b32 m0, s69
	s_nop 0
	global_load_lds_dwordx4 v[144:145], off
	s_waitcnt vmcnt(8)
	s_waitcnt lgkmcnt(0)
	s_barrier
	s_waitcnt lgkmcnt(0)
	v_mfma_f32_16x16x32_bf16 v[60:63], v[140:143], v[180:183], v[60:63]
	v_mfma_f32_16x16x32_bf16 v[56:59], v[156:159], v[180:183], v[56:59]
	v_mfma_f32_16x16x32_bf16 v[48:51], v[140:143], v[188:191], v[48:51]
	v_mfma_f32_16x16x32_bf16 v[40:43], v[156:159], v[188:191], v[40:43]
	v_mfma_f32_16x16x32_bf16 v[32:35], v[140:143], v[196:199], v[32:35]
	v_mfma_f32_16x16x32_bf16 v[24:27], v[156:159], v[196:199], v[24:27]
	v_mfma_f32_16x16x32_bf16 v[16:19], v[140:143], v[206:209], v[16:19]
	v_mfma_f32_16x16x32_bf16 v[8:11], v[156:159], v[206:209], v[8:11]
	v_mfma_f32_16x16x32_bf16 v[60:63], v[152:155], v[184:187], v[60:63]
	v_mfma_f32_16x16x32_bf16 v[56:59], v[160:163], v[184:187], v[56:59]
	v_mfma_f32_16x16x32_bf16 v[48:51], v[152:155], v[192:195], v[48:51]
	v_mfma_f32_16x16x32_bf16 v[40:43], v[160:163], v[192:195], v[40:43]
	v_mfma_f32_16x16x32_bf16 v[32:35], v[152:155], v[202:205], v[32:35]
	v_mfma_f32_16x16x32_bf16 v[24:27], v[160:163], v[202:205], v[24:27]
	v_mfma_f32_16x16x32_bf16 v[16:19], v[152:155], v[210:213], v[16:19]
	v_mfma_f32_16x16x32_bf16 v[8:11], v[160:163], v[210:213], v[8:11]
	v_mfma_f32_16x16x32_bf16 v[52:55], v[164:167], v[180:183], v[52:55]
	v_mfma_f32_16x16x32_bf16 v[44:47], v[172:175], v[180:183], v[44:47]
	v_mfma_f32_16x16x32_bf16 v[36:39], v[164:167], v[188:191], v[36:39]
	v_mfma_f32_16x16x32_bf16 v[28:31], v[172:175], v[188:191], v[28:31]
	v_mfma_f32_16x16x32_bf16 v[20:23], v[164:167], v[196:199], v[20:23]
	v_mfma_f32_16x16x32_bf16 v[12:15], v[172:175], v[196:199], v[12:15]
	v_mfma_f32_16x16x32_bf16 v[4:7], v[164:167], v[206:209], v[4:7]
	v_mfma_f32_16x16x32_bf16 v[0:3], v[172:175], v[206:209], v[0:3]
	v_mfma_f32_16x16x32_bf16 v[52:55], v[168:171], v[184:187], v[52:55]
	v_mfma_f32_16x16x32_bf16 v[44:47], v[176:179], v[184:187], v[44:47]
	v_mfma_f32_16x16x32_bf16 v[36:39], v[168:171], v[192:195], v[36:39]
	v_mfma_f32_16x16x32_bf16 v[28:31], v[176:179], v[192:195], v[28:31]
	v_mfma_f32_16x16x32_bf16 v[20:23], v[168:171], v[202:205], v[20:23]
	v_mfma_f32_16x16x32_bf16 v[12:15], v[176:179], v[202:205], v[12:15]
	v_mfma_f32_16x16x32_bf16 v[4:7], v[168:171], v[210:213], v[4:7]
	v_mfma_f32_16x16x32_bf16 v[0:3], v[176:179], v[210:213], v[0:3]
	s_barrier
	s_add_i32 s78, s78, 2
	s_add_u32 s52, s52, 0x100
	s_addc_u32 s53, s53, 0
	s_add_u32 s76, s76, 0x100
	s_addc_u32 s77, s77, 0
	s_cmp_gt_u32 s78, 41
	s_cbranch_scc0 .LBB0_1018
	s_setprio 0
	s_and_b64 vcc, exec, s[12:13]
	s_cbranch_vccz .LBB0_1021
	s_barrier

.LBB0_1154:
	s_ashr_i32 s15, s14, 31
	s_lshl_b64 s[18:19], s[14:15], 19
	s_add_u32 s18, s17, s18
	s_addc_u32 s19, s52, s19
	s_and_b64 s[20:21], s[2:3], exec
	s_cselect_b32 s15, s19, s35
	s_cselect_b32 s70, s18, s34
	s_ashr_i32 s13, s12, 31
	s_lshl_b64 s[20:21], s[12:13], 19
	s_add_u32 s20, s53, s20
	s_addc_u32 s21, s54, s21
	s_and_b64 s[50:51], s[2:3], exec
	s_cselect_b32 s13, s21, s45
	s_cselect_b32 s71, s20, s44
	s_add_u32 s34, s34, 0x40080
	s_addc_u32 s35, s35, 0
	s_add_u32 s72, s44, 0x100
	s_addc_u32 s73, s45, 0
	s_mov_b32 s74, -2
	v_mov_b64_e32 v[0:1], 0
	v_mov_b64_e32 v[2:3], 0
	v_mov_b64_e32 v[4:5], 0
	v_mov_b64_e32 v[6:7], 0
	v_mov_b64_e32 v[8:9], 0
	v_mov_b64_e32 v[10:11], 0
	v_mov_b64_e32 v[12:13], 0
	v_mov_b64_e32 v[14:15], 0
	v_mov_b64_e32 v[16:17], 0
	v_mov_b64_e32 v[18:19], 0
	v_mov_b64_e32 v[20:21], 0
	v_mov_b64_e32 v[22:23], 0
	v_mov_b64_e32 v[24:25], 0
	v_mov_b64_e32 v[26:27], 0
	v_mov_b64_e32 v[28:29], 0
	v_mov_b64_e32 v[30:31], 0
	v_mov_b64_e32 v[32:33], 0
	v_mov_b64_e32 v[34:35], 0
	v_mov_b64_e32 v[36:37], 0
	v_mov_b64_e32 v[38:39], 0
	v_mov_b64_e32 v[40:41], 0
	v_mov_b64_e32 v[42:43], 0
	v_mov_b64_e32 v[44:45], 0
	v_mov_b64_e32 v[46:47], 0
	v_mov_b64_e32 v[48:49], 0
	v_mov_b64_e32 v[50:51], 0
	v_mov_b64_e32 v[52:53], 0
	v_mov_b64_e32 v[54:55], 0
	v_mov_b64_e32 v[56:57], 0
	v_mov_b64_e32 v[58:59], 0
	v_mov_b64_e32 v[60:61], 0
	v_mov_b64_e32 v[62:63], 0
	v_mov_b64_e32 v[64:65], 0
	v_mov_b64_e32 v[66:67], 0
	v_mov_b64_e32 v[68:69], 0
	v_mov_b64_e32 v[70:71], 0
	v_mov_b64_e32 v[72:73], 0
	v_mov_b64_e32 v[74:75], 0
	v_mov_b64_e32 v[76:77], 0
	v_mov_b64_e32 v[78:79], 0
	v_mov_b64_e32 v[80:81], 0
	v_mov_b64_e32 v[82:83], 0
	v_mov_b64_e32 v[84:85], 0
	v_mov_b64_e32 v[86:87], 0
	v_mov_b64_e32 v[88:89], 0
	v_mov_b64_e32 v[90:91], 0
	v_mov_b64_e32 v[92:93], 0
	v_mov_b64_e32 v[94:95], 0
	v_mov_b64_e32 v[96:97], 0
	v_mov_b64_e32 v[98:99], 0
	v_mov_b64_e32 v[100:101], 0
	v_mov_b64_e32 v[102:103], 0
	v_mov_b64_e32 v[104:105], 0
	v_mov_b64_e32 v[106:107], 0
	v_mov_b64_e32 v[108:109], 0
	v_mov_b64_e32 v[110:111], 0
	v_mov_b64_e32 v[112:113], 0
	v_mov_b64_e32 v[114:115], 0
	v_mov_b64_e32 v[116:117], 0
	v_mov_b64_e32 v[118:119], 0
	v_mov_b64_e32 v[120:121], 0
	v_mov_b64_e32 v[122:123], 0
	v_mov_b64_e32 v[124:125], 0
	v_mov_b64_e32 v[126:127], 0
	v_lshrrev_b32_e32 v253, 8, v200
	s_nop 0
	v_readfirstlane_b32 s98, v253
	s_cmp_lg_u32 s98, 0
	s_cbranch_scc0 .Lgp_1155
	s_setprio 1
.Lgp_1155:
.LBB0_1155:
	ds_read_b128 v[144:147], v151
	ds_read_b128 v[154:157], v151 offset:1024
	ds_read_b128 v[158:161], v151 offset:2048
	ds_read_b128 v[162:165], v151 offset:3072
	ds_read_b128 v[166:169], v152
	ds_read_b128 v[170:173], v152 offset:1024
	ds_read_b128 v[174:177], v152 offset:2048
	ds_read_b128 v[178:181], v152 offset:3072
	s_add_u32 s44, s34, 0xfffc0080
	s_addc_u32 s45, s35, -1
	s_cmp_eq_u32 s74, 12
	s_cselect_b32 s51, s15, s45
	s_cselect_b32 s50, s70, s44
	s_cselect_b32 s45, s13, s73
	s_cselect_b32 s44, s71, s72
	v_lshl_add_u64 v[198:199], s[34:35], 0, v[136:137]
	s_add_i32 m0, s58, 0xc000
	ds_read_b128 v[182:185], v153
	ds_read_b128 v[186:189], v153 offset:1024
	ds_read_b128 v[190:193], v153 offset:2048
	ds_read_b128 v[194:197], v153 offset:3072
	ds_read_b128 v[202:205], v153 offset:4096
	ds_read_b128 v[206:209], v153 offset:5120
	ds_read_b128 v[210:213], v153 offset:6144
	ds_read_b128 v[214:217], v153 offset:7168
	global_load_lds_dwordx4 v[198:199], off
	v_lshl_add_u64 v[198:199], s[34:35], 0, v[138:139]
	s_add_i32 m0, s58, 0xe000
	s_nop 0
	global_load_lds_dwordx4 v[198:199], off
	s_waitcnt vmcnt(8)
	s_waitcnt lgkmcnt(0)
	s_barrier
	s_waitcnt lgkmcnt(0)
	v_mfma_f32_16x16x32_bf16 v[124:127], v[144:147], v[182:185], v[124:127]
	v_mfma_f32_16x16x32_bf16 v[120:123], v[158:161], v[182:185], v[120:123]
	v_mfma_f32_16x16x32_bf16 v[116:119], v[144:147], v[190:193], v[116:119]
	v_mfma_f32_16x16x32_bf16 v[108:111], v[158:161], v[190:193], v[108:111]
	v_mfma_f32_16x16x32_bf16 v[100:103], v[144:147], v[202:205], v[100:103]
	v_mfma_f32_16x16x32_bf16 v[92:95], v[158:161], v[202:205], v[92:95]
	v_mfma_f32_16x16x32_bf16 v[84:87], v[144:147], v[210:213], v[84:87]
	v_mfma_f32_16x16x32_bf16 v[76:79], v[158:161], v[210:213], v[76:79]
	v_mfma_f32_16x16x32_bf16 v[124:127], v[154:157], v[186:189], v[124:127]
	v_mfma_f32_16x16x32_bf16 v[120:123], v[162:165], v[186:189], v[120:123]
	v_mfma_f32_16x16x32_bf16 v[116:119], v[154:157], v[194:197], v[116:119]
	v_mfma_f32_16x16x32_bf16 v[108:111], v[162:165], v[194:197], v[108:111]
	v_mfma_f32_16x16x32_bf16 v[100:103], v[154:157], v[206:209], v[100:103]
	v_mfma_f32_16x16x32_bf16 v[92:95], v[162:165], v[206:209], v[92:95]
	v_mfma_f32_16x16x32_bf16 v[84:87], v[154:157], v[214:217], v[84:87]
	v_mfma_f32_16x16x32_bf16 v[76:79], v[162:165], v[214:217], v[76:79]
	v_mfma_f32_16x16x32_bf16 v[112:115], v[166:169], v[182:185], v[112:115]
	v_mfma_f32_16x16x32_bf16 v[104:107], v[174:177], v[182:185], v[104:107]
	v_mfma_f32_16x16x32_bf16 v[96:99], v[166:169], v[190:193], v[96:99]
	v_mfma_f32_16x16x32_bf16 v[88:91], v[174:177], v[190:193], v[88:91]
	v_mfma_f32_16x16x32_bf16 v[80:83], v[166:169], v[202:205], v[80:83]
	v_mfma_f32_16x16x32_bf16 v[72:75], v[174:177], v[202:205], v[72:75]
	v_mfma_f32_16x16x32_bf16 v[68:71], v[166:169], v[210:213], v[68:71]
	v_mfma_f32_16x16x32_bf16 v[64:67], v[174:177], v[210:213], v[64:67]
	v_mfma_f32_16x16x32_bf16 v[112:115], v[170:173], v[186:189], v[112:115]
	v_mfma_f32_16x16x32_bf16 v[104:107], v[178:181], v[186:189], v[104:107]
	v_mfma_f32_16x16x32_bf16 v[96:99], v[170:173], v[194:197], v[96:99]
	v_mfma_f32_16x16x32_bf16 v[88:91], v[178:181], v[194:197], v[88:91]
	v_mfma_f32_16x16x32_bf16 v[80:83], v[170:173], v[206:209], v[80:83]
	v_mfma_f32_16x16x32_bf16 v[72:75], v[178:181], v[206:209], v[72:75]
	v_mfma_f32_16x16x32_bf16 v[68:71], v[170:173], v[214:217], v[68:71]
	v_mfma_f32_16x16x32_bf16 v[64:67], v[178:181], v[214:217], v[64:67]
	s_barrier
	s_add_i32 s75, s65, s55
	v_lshl_add_u64 v[198:199], s[44:45], 0, v[132:133]
	s_mov_b32 m0, s75
	ds_read_b128 v[182:185], v153 offset:16384
	ds_read_b128 v[186:189], v153 offset:17408
	ds_read_b128 v[190:193], v153 offset:18432
	ds_read_b128 v[194:197], v153 offset:19456
	ds_read_b128 v[202:205], v153 offset:20480
	ds_read_b128 v[206:209], v153 offset:21504
	ds_read_b128 v[210:213], v153 offset:22528
	ds_read_b128 v[214:217], v153 offset:23552
	global_load_lds_dwordx4 v[198:199], off
	s_add_i32 m0, s75, 0x2000
	s_add_u32 s76, s44, 0x40000
	v_lshl_add_u64 v[218:219], s[44:45], 0, v[128:129]
	s_addc_u32 s77, s45, 0
	s_add_i32 s75, s66, s55
	global_load_lds_dwordx4 v[218:219], off
	v_lshl_add_u64 v[220:221], s[76:77], 0, v[132:133]
	s_mov_b32 m0, s75
	v_lshl_add_u64 v[222:223], s[50:51], 0, v[130:131]
	global_load_lds_dwordx4 v[220:221], off
	v_lshl_add_u64 v[220:221], s[76:77], 0, v[128:129]
	s_add_i32 m0, s75, 0x2000
	s_nop 0
	global_load_lds_dwordx4 v[220:221], off
	v_lshl_add_u64 v[220:221], s[50:51], 0, v[134:135]
	s_mov_b32 m0, s58
	s_nop 0
	global_load_lds_dwordx4 v[220:221], off
	s_mov_b32 m0, s59
	s_nop 0
	global_load_lds_dwordx4 v[222:223], off
	s_waitcnt vmcnt(8)
	s_waitcnt lgkmcnt(0)
	s_barrier
	s_waitcnt lgkmcnt(0)
	v_mfma_f32_16x16x32_bf16 v[60:63], v[144:147], v[182:185], v[60:63]
	v_mfma_f32_16x16x32_bf16 v[56:59], v[158:161], v[182:185], v[56:59]
	v_mfma_f32_16x16x32_bf16 v[52:55], v[144:147], v[190:193], v[52:55]
	v_mfma_f32_16x16x32_bf16 v[44:47], v[158:161], v[190:193], v[44:47]
	v_mfma_f32_16x16x32_bf16 v[36:39], v[144:147], v[202:205], v[36:39]
	v_mfma_f32_16x16x32_bf16 v[28:31], v[158:161], v[202:205], v[28:31]
	v_mfma_f32_16x16x32_bf16 v[20:23], v[144:147], v[210:213], v[20:23]
	v_mfma_f32_16x16x32_bf16 v[12:15], v[158:161], v[210:213], v[12:15]
	v_mfma_f32_16x16x32_bf16 v[60:63], v[154:157], v[186:189], v[60:63]
	v_mfma_f32_16x16x32_bf16 v[56:59], v[162:165], v[186:189], v[56:59]
	v_mfma_f32_16x16x32_bf16 v[52:55], v[154:157], v[194:197], v[52:55]
	v_mfma_f32_16x16x32_bf16 v[44:47], v[162:165], v[194:197], v[44:47]
	v_mfma_f32_16x16x32_bf16 v[36:39], v[154:157], v[206:209], v[36:39]
	v_mfma_f32_16x16x32_bf16 v[28:31], v[162:165], v[206:209], v[28:31]
	v_mfma_f32_16x16x32_bf16 v[20:23], v[154:157], v[214:217], v[20:23]
	v_mfma_f32_16x16x32_bf16 v[12:15], v[162:165], v[214:217], v[12:15]
	v_mfma_f32_16x16x32_bf16 v[48:51], v[166:169], v[182:185], v[48:51]
	v_mfma_f32_16x16x32_bf16 v[40:43], v[174:177], v[182:185], v[40:43]
	v_mfma_f32_16x16x32_bf16 v[32:35], v[166:169], v[190:193], v[32:35]
	v_mfma_f32_16x16x32_bf16 v[24:27], v[174:177], v[190:193], v[24:27]
	v_mfma_f32_16x16x32_bf16 v[16:19], v[166:169], v[202:205], v[16:19]
	v_mfma_f32_16x16x32_bf16 v[8:11], v[174:177], v[202:205], v[8:11]
	v_mfma_f32_16x16x32_bf16 v[4:7], v[166:169], v[210:213], v[4:7]
	v_mfma_f32_16x16x32_bf16 v[0:3], v[174:177], v[210:213], v[0:3]
	v_mfma_f32_16x16x32_bf16 v[48:51], v[170:173], v[186:189], v[48:51]
	v_mfma_f32_16x16x32_bf16 v[40:43], v[178:181], v[186:189], v[40:43]
	v_mfma_f32_16x16x32_bf16 v[32:35], v[170:173], v[194:197], v[32:35]
	v_mfma_f32_16x16x32_bf16 v[24:27], v[178:181], v[194:197], v[24:27]
	v_mfma_f32_16x16x32_bf16 v[16:19], v[170:173], v[206:209], v[16:19]
	v_mfma_f32_16x16x32_bf16 v[8:11], v[178:181], v[206:209], v[8:11]
	v_mfma_f32_16x16x32_bf16 v[4:7], v[170:173], v[214:217], v[4:7]
	v_mfma_f32_16x16x32_bf16 v[0:3], v[178:181], v[214:217], v[0:3]
	s_barrier
	s_add_i32 s75, 0, 0x18000
	s_add_i32 s76, 0, 0x1c000
	v_add_u32_e32 v162, s75, v149
	v_add_u32_e32 v178, s76, v149
	ds_read_b128 v[144:147], v162
	ds_read_b128 v[154:157], v162 offset:1024
	ds_read_b128 v[158:161], v162 offset:2048
	ds_read_b128 v[162:165], v162 offset:3072
	ds_read_b128 v[166:169], v178
	ds_read_b128 v[170:173], v178 offset:1024
	ds_read_b128 v[174:177], v178 offset:2048
	ds_read_b128 v[178:181], v178 offset:3072
	s_add_u32 s50, s50, 0x40000
	s_addc_u32 s51, s51, 0
	s_mov_b32 m0, s60
	v_lshl_add_u64 v[224:225], s[50:51], 0, v[134:135]
	ds_read_b128 v[182:185], v153 offset:32768
	ds_read_b128 v[186:189], v153 offset:33792
	ds_read_b128 v[190:193], v153 offset:34816
	ds_read_b128 v[194:197], v153 offset:35840
	ds_read_b128 v[202:205], v153 offset:36864
	ds_read_b128 v[206:209], v153 offset:37888
	ds_read_b128 v[210:213], v153 offset:38912
	ds_read_b128 v[214:217], v153 offset:39936
	global_load_lds_dwordx4 v[224:225], off
	v_lshl_add_u64 v[224:225], s[50:51], 0, v[130:131]
	s_mov_b32 m0, s61
	s_nop 0
	global_load_lds_dwordx4 v[224:225], off
	s_waitcnt vmcnt(8)
	s_waitcnt lgkmcnt(0)
	s_barrier
	s_waitcnt lgkmcnt(0)
	v_mfma_f32_16x16x32_bf16 v[124:127], v[144:147], v[182:185], v[124:127]
	v_mfma_f32_16x16x32_bf16 v[120:123], v[158:161], v[182:185], v[120:123]
	v_mfma_f32_16x16x32_bf16 v[116:119], v[144:147], v[190:193], v[116:119]
	v_mfma_f32_16x16x32_bf16 v[108:111], v[158:161], v[190:193], v[108:111]
	v_mfma_f32_16x16x32_bf16 v[100:103], v[144:147], v[202:205], v[100:103]
	v_mfma_f32_16x16x32_bf16 v[92:95], v[158:161], v[202:205], v[92:95]
	v_mfma_f32_16x16x32_bf16 v[84:87], v[144:147], v[210:213], v[84:87]
	v_mfma_f32_16x16x32_bf16 v[76:79], v[158:161], v[210:213], v[76:79]
	v_mfma_f32_16x16x32_bf16 v[124:127], v[154:157], v[186:189], v[124:127]
	v_mfma_f32_16x16x32_bf16 v[120:123], v[162:165], v[186:189], v[120:123]
	v_mfma_f32_16x16x32_bf16 v[116:119], v[154:157], v[194:197], v[116:119]
	v_mfma_f32_16x16x32_bf16 v[108:111], v[162:165], v[194:197], v[108:111]
	v_mfma_f32_16x16x32_bf16 v[100:103], v[154:157], v[206:209], v[100:103]
	v_mfma_f32_16x16x32_bf16 v[92:95], v[162:165], v[206:209], v[92:95]
	v_mfma_f32_16x16x32_bf16 v[84:87], v[154:157], v[214:217], v[84:87]
	v_mfma_f32_16x16x32_bf16 v[76:79], v[162:165], v[214:217], v[76:79]
	v_mfma_f32_16x16x32_bf16 v[112:115], v[166:169], v[182:185], v[112:115]
	v_mfma_f32_16x16x32_bf16 v[104:107], v[174:177], v[182:185], v[104:107]
	v_mfma_f32_16x16x32_bf16 v[96:99], v[166:169], v[190:193], v[96:99]
	v_mfma_f32_16x16x32_bf16 v[88:91], v[174:177], v[190:193], v[88:91]
	v_mfma_f32_16x16x32_bf16 v[80:83], v[166:169], v[202:205], v[80:83]
	v_mfma_f32_16x16x32_bf16 v[72:75], v[174:177], v[202:205], v[72:75]
	v_mfma_f32_16x16x32_bf16 v[68:71], v[166:169], v[210:213], v[68:71]
	v_mfma_f32_16x16x32_bf16 v[64:67], v[174:177], v[210:213], v[64:67]
	v_mfma_f32_16x16x32_bf16 v[112:115], v[170:173], v[186:189], v[112:115]
	v_mfma_f32_16x16x32_bf16 v[104:107], v[178:181], v[186:189], v[104:107]
	v_mfma_f32_16x16x32_bf16 v[96:99], v[170:173], v[194:197], v[96:99]
	v_mfma_f32_16x16x32_bf16 v[88:91], v[178:181], v[194:197], v[88:91]
	v_mfma_f32_16x16x32_bf16 v[80:83], v[170:173], v[206:209], v[80:83]
	v_mfma_f32_16x16x32_bf16 v[72:75], v[178:181], v[206:209], v[72:75]
	v_mfma_f32_16x16x32_bf16 v[68:71], v[170:173], v[214:217], v[68:71]
	v_mfma_f32_16x16x32_bf16 v[64:67], v[178:181], v[214:217], v[64:67]
	s_barrier
	s_add_i32 s50, s75, s55
	v_lshl_add_u64 v[198:199], v[198:199], 0, s[8:9]
	s_mov_b32 m0, s50
	ds_read_b128 v[182:185], v153 offset:49152
	ds_read_b128 v[186:189], v153 offset:50176
	ds_read_b128 v[190:193], v153 offset:51200
	ds_read_b128 v[194:197], v153 offset:52224
	ds_read_b128 v[202:205], v153 offset:53248
	ds_read_b128 v[206:209], v153 offset:54272
	ds_read_b128 v[210:213], v153 offset:55296
	ds_read_b128 v[214:217], v153 offset:56320
	global_load_lds_dwordx4 v[198:199], off
	s_add_i32 m0, s50, 0x2000
	s_add_u32 s44, s44, 0x40080
	v_lshl_add_u64 v[198:199], v[218:219], 0, s[8:9]
	s_addc_u32 s45, s45, 0
	s_add_i32 s50, s76, s55
	global_load_lds_dwordx4 v[198:199], off
	v_lshl_add_u64 v[198:199], s[44:45], 0, v[132:133]
	s_mov_b32 m0, s50
	s_nop 0
	global_load_lds_dwordx4 v[198:199], off
	v_lshl_add_u64 v[198:199], s[44:45], 0, v[128:129]
	s_add_i32 m0, s50, 0x2000
	s_nop 0
	global_load_lds_dwordx4 v[198:199], off
	v_lshl_add_u64 v[198:199], v[220:221], 0, s[8:9]
	s_mov_b32 m0, s63
	s_nop 0
	global_load_lds_dwordx4 v[198:199], off
	v_lshl_add_u64 v[198:199], v[222:223], 0, s[8:9]
	s_mov_b32 m0, s64
	s_nop 0
	global_load_lds_dwordx4 v[198:199], off
	s_waitcnt vmcnt(8)
	s_waitcnt lgkmcnt(0)
	s_barrier
	s_waitcnt lgkmcnt(0)
	v_mfma_f32_16x16x32_bf16 v[60:63], v[144:147], v[182:185], v[60:63]
	v_mfma_f32_16x16x32_bf16 v[56:59], v[158:161], v[182:185], v[56:59]
	v_mfma_f32_16x16x32_bf16 v[52:55], v[144:147], v[190:193], v[52:55]
	v_mfma_f32_16x16x32_bf16 v[44:47], v[158:161], v[190:193], v[44:47]
	v_mfma_f32_16x16x32_bf16 v[36:39], v[144:147], v[202:205], v[36:39]
	v_mfma_f32_16x16x32_bf16 v[28:31], v[158:161], v[202:205], v[28:31]
	v_mfma_f32_16x16x32_bf16 v[20:23], v[144:147], v[210:213], v[20:23]
	v_mfma_f32_16x16x32_bf16 v[12:15], v[158:161], v[210:213], v[12:15]
	v_mfma_f32_16x16x32_bf16 v[60:63], v[154:157], v[186:189], v[60:63]
	v_mfma_f32_16x16x32_bf16 v[56:59], v[162:165], v[186:189], v[56:59]
	v_mfma_f32_16x16x32_bf16 v[52:55], v[154:157], v[194:197], v[52:55]
	v_mfma_f32_16x16x32_bf16 v[44:47], v[162:165], v[194:197], v[44:47]
	v_mfma_f32_16x16x32_bf16 v[36:39], v[154:157], v[206:209], v[36:39]
	v_mfma_f32_16x16x32_bf16 v[28:31], v[162:165], v[206:209], v[28:31]
	v_mfma_f32_16x16x32_bf16 v[20:23], v[154:157], v[214:217], v[20:23]
	v_mfma_f32_16x16x32_bf16 v[12:15], v[162:165], v[214:217], v[12:15]
	v_mfma_f32_16x16x32_bf16 v[48:51], v[166:169], v[182:185], v[48:51]
	v_mfma_f32_16x16x32_bf16 v[40:43], v[174:177], v[182:185], v[40:43]
	v_mfma_f32_16x16x32_bf16 v[32:35], v[166:169], v[190:193], v[32:35]
	v_mfma_f32_16x16x32_bf16 v[24:27], v[174:177], v[190:193], v[24:27]
	v_mfma_f32_16x16x32_bf16 v[16:19], v[166:169], v[202:205], v[16:19]
	v_mfma_f32_16x16x32_bf16 v[8:11], v[174:177], v[202:205], v[8:11]
	v_mfma_f32_16x16x32_bf16 v[4:7], v[166:169], v[210:213], v[4:7]
	v_mfma_f32_16x16x32_bf16 v[0:3], v[174:177], v[210:213], v[0:3]
	v_mfma_f32_16x16x32_bf16 v[48:51], v[170:173], v[186:189], v[48:51]
	v_mfma_f32_16x16x32_bf16 v[40:43], v[178:181], v[186:189], v[40:43]
	v_mfma_f32_16x16x32_bf16 v[32:35], v[170:173], v[194:197], v[32:35]
	v_mfma_f32_16x16x32_bf16 v[24:27], v[178:181], v[194:197], v[24:27]
	v_mfma_f32_16x16x32_bf16 v[16:19], v[170:173], v[206:209], v[16:19]
	v_mfma_f32_16x16x32_bf16 v[8:11], v[178:181], v[206:209], v[8:11]
	v_mfma_f32_16x16x32_bf16 v[4:7], v[170:173], v[214:217], v[4:7]
	v_mfma_f32_16x16x32_bf16 v[0:3], v[178:181], v[214:217], v[0:3]
	s_barrier
	s_add_i32 s74, s74, 2
	s_add_u32 s34, s34, 0x100
	s_addc_u32 s35, s35, 0
	s_add_u32 s72, s72, 0x100
	s_addc_u32 s73, s73, 0
	s_cmp_gt_u32 s74, 13
	s_cbranch_scc0 .LBB0_1155
	s_setprio 0
	s_and_b64 vcc, exec, s[10:11]
	s_cbranch_vccz .LBB0_1158
	s_barrier

.LBB0_1414:
	s_ashr_i32 s51, s50, 31
	s_lshl_b64 s[52:53], s[50:51], 19
	s_add_u32 s52, s13, s52
	s_addc_u32 s53, s17, s53
	s_and_b64 s[54:55], s[2:3], exec
	s_cselect_b32 s51, s53, s57
	s_cselect_b32 s76, s52, s56
	s_ashr_i32 s45, s44, 31
	s_lshl_b64 s[54:55], s[44:45], 19
	s_add_u32 s54, s62, s54
	s_addc_u32 s55, s63, s55
	s_and_b64 s[60:61], s[2:3], exec
	s_cselect_b32 s45, s55, s59
	s_cselect_b32 s77, s54, s58
	s_add_u32 s56, s56, 0x40080
	s_addc_u32 s57, s57, 0
	s_add_u32 s78, s58, 0x100
	s_addc_u32 s79, s59, 0
	s_mov_b32 s80, -2
	v_mov_b64_e32 v[0:1], 0
	v_mov_b64_e32 v[2:3], 0
	v_mov_b64_e32 v[4:5], 0
	v_mov_b64_e32 v[6:7], 0
	v_mov_b64_e32 v[8:9], 0
	v_mov_b64_e32 v[10:11], 0
	v_mov_b64_e32 v[12:13], 0
	v_mov_b64_e32 v[14:15], 0
	v_mov_b64_e32 v[16:17], 0
	v_mov_b64_e32 v[18:19], 0
	v_mov_b64_e32 v[20:21], 0
	v_mov_b64_e32 v[22:23], 0
	v_mov_b64_e32 v[24:25], 0
	v_mov_b64_e32 v[26:27], 0
	v_mov_b64_e32 v[28:29], 0
	v_mov_b64_e32 v[30:31], 0
	v_mov_b64_e32 v[32:33], 0
	v_mov_b64_e32 v[34:35], 0
	v_mov_b64_e32 v[36:37], 0
	v_mov_b64_e32 v[38:39], 0
	v_mov_b64_e32 v[40:41], 0
	v_mov_b64_e32 v[42:43], 0
	v_mov_b64_e32 v[44:45], 0
	v_mov_b64_e32 v[46:47], 0
	v_mov_b64_e32 v[48:49], 0
	v_mov_b64_e32 v[50:51], 0
	v_mov_b64_e32 v[52:53], 0
	v_mov_b64_e32 v[54:55], 0
	v_mov_b64_e32 v[56:57], 0
	v_mov_b64_e32 v[58:59], 0
	v_mov_b64_e32 v[60:61], 0
	v_mov_b64_e32 v[62:63], 0
	v_mov_b64_e32 v[64:65], 0
	v_mov_b64_e32 v[66:67], 0
	v_mov_b64_e32 v[68:69], 0
	v_mov_b64_e32 v[70:71], 0
	v_mov_b64_e32 v[72:73], 0
	v_mov_b64_e32 v[74:75], 0
	v_mov_b64_e32 v[76:77], 0
	v_mov_b64_e32 v[78:79], 0
	v_mov_b64_e32 v[80:81], 0
	v_mov_b64_e32 v[82:83], 0
	v_mov_b64_e32 v[84:85], 0
	v_mov_b64_e32 v[86:87], 0
	v_mov_b64_e32 v[88:89], 0
	v_mov_b64_e32 v[90:91], 0
	v_mov_b64_e32 v[92:93], 0
	v_mov_b64_e32 v[94:95], 0
	v_mov_b64_e32 v[96:97], 0
	v_mov_b64_e32 v[98:99], 0
	v_mov_b64_e32 v[100:101], 0
	v_mov_b64_e32 v[102:103], 0
	v_mov_b64_e32 v[104:105], 0
	v_mov_b64_e32 v[106:107], 0
	v_mov_b64_e32 v[108:109], 0
	v_mov_b64_e32 v[110:111], 0
	v_mov_b64_e32 v[112:113], 0
	v_mov_b64_e32 v[114:115], 0
	v_mov_b64_e32 v[116:117], 0
	v_mov_b64_e32 v[118:119], 0
	v_mov_b64_e32 v[120:121], 0
	v_mov_b64_e32 v[122:123], 0
	v_mov_b64_e32 v[124:125], 0
	v_mov_b64_e32 v[126:127], 0
	s_waitcnt vmcnt(0)
	v_lshrrev_b32_e32 v253, 8, v200
	s_nop 0
	v_readfirstlane_b32 s98, v253
	s_cmp_lg_u32 s98, 0
	s_cbranch_scc0 .Lgp_1415
	s_setprio 1
.Lgp_1415:
.LBB0_1415:
	ds_read_b128 v[140:143], v149
	ds_read_b128 v[152:155], v149 offset:1024
	ds_read_b128 v[156:159], v149 offset:2048
	ds_read_b128 v[160:163], v149 offset:3072
	ds_read_b128 v[164:167], v150
	ds_read_b128 v[168:171], v150 offset:1024
	ds_read_b128 v[172:175], v150 offset:2048
	ds_read_b128 v[176:179], v150 offset:3072
	s_add_u32 s58, s56, 0xfffc0080
	s_addc_u32 s59, s57, -1
	s_cmp_eq_u32 s80, 12
	s_cselect_b32 s61, s51, s59
	s_cselect_b32 s60, s76, s58
	s_cselect_b32 s59, s45, s79
	s_cselect_b32 s58, s77, s78
	v_lshl_add_u64 v[144:145], s[56:57], 0, v[132:133]
	s_add_i32 m0, s65, 0xc000
	ds_read_b128 v[180:183], v151
	ds_read_b128 v[184:187], v151 offset:1024
	ds_read_b128 v[188:191], v151 offset:2048
	ds_read_b128 v[192:195], v151 offset:3072
	ds_read_b128 v[196:199], v151 offset:4096
	ds_read_b128 v[202:205], v151 offset:5120
	ds_read_b128 v[206:209], v151 offset:6144
	ds_read_b128 v[210:213], v151 offset:7168
	global_load_lds_dwordx4 v[144:145], off
	v_lshl_add_u64 v[144:145], s[56:57], 0, v[134:135]
	s_add_i32 m0, s65, 0xe000
	s_nop 0
	global_load_lds_dwordx4 v[144:145], off
	s_waitcnt vmcnt(8)
	s_waitcnt lgkmcnt(0)
	s_barrier
	s_waitcnt lgkmcnt(0)
	v_mfma_f32_16x16x32_bf16 v[124:127], v[140:143], v[180:183], v[124:127]
	v_mfma_f32_16x16x32_bf16 v[120:123], v[156:159], v[180:183], v[120:123]
	v_mfma_f32_16x16x32_bf16 v[112:115], v[140:143], v[188:191], v[112:115]
	v_mfma_f32_16x16x32_bf16 v[104:107], v[156:159], v[188:191], v[104:107]
	v_mfma_f32_16x16x32_bf16 v[96:99], v[140:143], v[196:199], v[96:99]
	v_mfma_f32_16x16x32_bf16 v[88:91], v[156:159], v[196:199], v[88:91]
	v_mfma_f32_16x16x32_bf16 v[80:83], v[140:143], v[206:209], v[80:83]
	v_mfma_f32_16x16x32_bf16 v[72:75], v[156:159], v[206:209], v[72:75]
	v_mfma_f32_16x16x32_bf16 v[124:127], v[152:155], v[184:187], v[124:127]
	v_mfma_f32_16x16x32_bf16 v[120:123], v[160:163], v[184:187], v[120:123]
	v_mfma_f32_16x16x32_bf16 v[112:115], v[152:155], v[192:195], v[112:115]
	v_mfma_f32_16x16x32_bf16 v[104:107], v[160:163], v[192:195], v[104:107]
	v_mfma_f32_16x16x32_bf16 v[96:99], v[152:155], v[202:205], v[96:99]
	v_mfma_f32_16x16x32_bf16 v[88:91], v[160:163], v[202:205], v[88:91]
	v_mfma_f32_16x16x32_bf16 v[80:83], v[152:155], v[210:213], v[80:83]
	v_mfma_f32_16x16x32_bf16 v[72:75], v[160:163], v[210:213], v[72:75]
	v_mfma_f32_16x16x32_bf16 v[116:119], v[164:167], v[180:183], v[116:119]
	v_mfma_f32_16x16x32_bf16 v[108:111], v[172:175], v[180:183], v[108:111]
	v_mfma_f32_16x16x32_bf16 v[100:103], v[164:167], v[188:191], v[100:103]
	v_mfma_f32_16x16x32_bf16 v[92:95], v[172:175], v[188:191], v[92:95]
	v_mfma_f32_16x16x32_bf16 v[84:87], v[164:167], v[196:199], v[84:87]
	v_mfma_f32_16x16x32_bf16 v[76:79], v[172:175], v[196:199], v[76:79]
	v_mfma_f32_16x16x32_bf16 v[68:71], v[164:167], v[206:209], v[68:71]
	v_mfma_f32_16x16x32_bf16 v[64:67], v[172:175], v[206:209], v[64:67]
	v_mfma_f32_16x16x32_bf16 v[116:119], v[168:171], v[184:187], v[116:119]
	v_mfma_f32_16x16x32_bf16 v[108:111], v[176:179], v[184:187], v[108:111]
	v_mfma_f32_16x16x32_bf16 v[100:103], v[168:171], v[192:195], v[100:103]
	v_mfma_f32_16x16x32_bf16 v[92:95], v[176:179], v[192:195], v[92:95]
	v_mfma_f32_16x16x32_bf16 v[84:87], v[168:171], v[202:205], v[84:87]
	v_mfma_f32_16x16x32_bf16 v[76:79], v[176:179], v[202:205], v[76:79]
	v_mfma_f32_16x16x32_bf16 v[68:71], v[168:171], v[210:213], v[68:71]
	v_mfma_f32_16x16x32_bf16 v[64:67], v[176:179], v[210:213], v[64:67]
	s_barrier
	s_add_i32 s81, s74, s64
	v_lshl_add_u64 v[144:145], s[58:59], 0, v[130:131]
	s_mov_b32 m0, s81
	ds_read_b128 v[180:183], v151 offset:16384
	ds_read_b128 v[184:187], v151 offset:17408
	ds_read_b128 v[188:191], v151 offset:18432
	ds_read_b128 v[192:195], v151 offset:19456
	ds_read_b128 v[196:199], v151 offset:20480
	ds_read_b128 v[202:205], v151 offset:21504
	ds_read_b128 v[206:209], v151 offset:22528
	ds_read_b128 v[210:213], v151 offset:23552
	global_load_lds_dwordx4 v[144:145], off
	s_add_i32 m0, s81, 0x2000
	s_add_u32 s82, s58, 0x40000
	v_lshl_add_u64 v[214:215], s[58:59], 0, v[128:129]
	s_addc_u32 s83, s59, 0
	s_add_i32 s81, s75, s64
	global_load_lds_dwordx4 v[214:215], off
	v_lshl_add_u64 v[216:217], s[82:83], 0, v[130:131]
	s_mov_b32 m0, s81
	v_lshl_add_u64 v[218:219], s[60:61], 0, v[128:129]
	global_load_lds_dwordx4 v[216:217], off
	v_lshl_add_u64 v[216:217], s[82:83], 0, v[128:129]
	s_add_i32 m0, s81, 0x2000
	s_nop 0
	global_load_lds_dwordx4 v[216:217], off
	v_lshl_add_u64 v[216:217], s[60:61], 0, v[130:131]
	s_mov_b32 m0, s65
	s_nop 0
	global_load_lds_dwordx4 v[216:217], off
	s_mov_b32 m0, s66
	s_nop 0
	global_load_lds_dwordx4 v[218:219], off
	s_waitcnt vmcnt(8)
	s_waitcnt lgkmcnt(0)
	s_barrier
	s_waitcnt lgkmcnt(0)
	v_mfma_f32_16x16x32_bf16 v[60:63], v[140:143], v[180:183], v[60:63]
	v_mfma_f32_16x16x32_bf16 v[56:59], v[156:159], v[180:183], v[56:59]
	v_mfma_f32_16x16x32_bf16 v[48:51], v[140:143], v[188:191], v[48:51]
	v_mfma_f32_16x16x32_bf16 v[40:43], v[156:159], v[188:191], v[40:43]
	v_mfma_f32_16x16x32_bf16 v[32:35], v[140:143], v[196:199], v[32:35]
	v_mfma_f32_16x16x32_bf16 v[24:27], v[156:159], v[196:199], v[24:27]
	v_mfma_f32_16x16x32_bf16 v[16:19], v[140:143], v[206:209], v[16:19]
	v_mfma_f32_16x16x32_bf16 v[8:11], v[156:159], v[206:209], v[8:11]
	v_mfma_f32_16x16x32_bf16 v[60:63], v[152:155], v[184:187], v[60:63]
	v_mfma_f32_16x16x32_bf16 v[56:59], v[160:163], v[184:187], v[56:59]
	v_mfma_f32_16x16x32_bf16 v[48:51], v[152:155], v[192:195], v[48:51]
	v_mfma_f32_16x16x32_bf16 v[40:43], v[160:163], v[192:195], v[40:43]
	v_mfma_f32_16x16x32_bf16 v[32:35], v[152:155], v[202:205], v[32:35]
	v_mfma_f32_16x16x32_bf16 v[24:27], v[160:163], v[202:205], v[24:27]
	v_mfma_f32_16x16x32_bf16 v[16:19], v[152:155], v[210:213], v[16:19]
	v_mfma_f32_16x16x32_bf16 v[8:11], v[160:163], v[210:213], v[8:11]
	v_mfma_f32_16x16x32_bf16 v[52:55], v[164:167], v[180:183], v[52:55]
	v_mfma_f32_16x16x32_bf16 v[44:47], v[172:175], v[180:183], v[44:47]
	v_mfma_f32_16x16x32_bf16 v[36:39], v[164:167], v[188:191], v[36:39]
	v_mfma_f32_16x16x32_bf16 v[28:31], v[172:175], v[188:191], v[28:31]
	v_mfma_f32_16x16x32_bf16 v[20:23], v[164:167], v[196:199], v[20:23]
	v_mfma_f32_16x16x32_bf16 v[12:15], v[172:175], v[196:199], v[12:15]
	v_mfma_f32_16x16x32_bf16 v[4:7], v[164:167], v[206:209], v[4:7]
	v_mfma_f32_16x16x32_bf16 v[0:3], v[172:175], v[206:209], v[0:3]
	v_mfma_f32_16x16x32_bf16 v[52:55], v[168:171], v[184:187], v[52:55]
	v_mfma_f32_16x16x32_bf16 v[44:47], v[176:179], v[184:187], v[44:47]
	v_mfma_f32_16x16x32_bf16 v[36:39], v[168:171], v[192:195], v[36:39]
	v_mfma_f32_16x16x32_bf16 v[28:31], v[176:179], v[192:195], v[28:31]
	v_mfma_f32_16x16x32_bf16 v[20:23], v[168:171], v[202:205], v[20:23]
	v_mfma_f32_16x16x32_bf16 v[12:15], v[176:179], v[202:205], v[12:15]
	v_mfma_f32_16x16x32_bf16 v[4:7], v[168:171], v[210:213], v[4:7]
	v_mfma_f32_16x16x32_bf16 v[0:3], v[176:179], v[210:213], v[0:3]
	s_barrier
	s_add_i32 s81, 0, 0x18000
	s_add_i32 s82, 0, 0x1c000
	v_add_u32_e32 v160, s81, v147
	v_add_u32_e32 v176, s82, v147
	ds_read_b128 v[140:143], v160
	ds_read_b128 v[152:155], v160 offset:1024
	ds_read_b128 v[156:159], v160 offset:2048
	ds_read_b128 v[160:163], v160 offset:3072
	ds_read_b128 v[164:167], v176
	ds_read_b128 v[168:171], v176 offset:1024
	ds_read_b128 v[172:175], v176 offset:2048
	ds_read_b128 v[176:179], v176 offset:3072
	s_add_u32 s60, s60, 0x40000
	s_addc_u32 s61, s61, 0
	s_mov_b32 m0, s67
	v_lshl_add_u64 v[220:221], s[60:61], 0, v[130:131]
	ds_read_b128 v[180:183], v151 offset:32768
	ds_read_b128 v[184:187], v151 offset:33792
	ds_read_b128 v[188:191], v151 offset:34816
	ds_read_b128 v[192:195], v151 offset:35840
	ds_read_b128 v[196:199], v151 offset:36864
	ds_read_b128 v[202:205], v151 offset:37888
	ds_read_b128 v[206:209], v151 offset:38912
	ds_read_b128 v[210:213], v151 offset:39936
	global_load_lds_dwordx4 v[220:221], off
	v_lshl_add_u64 v[220:221], s[60:61], 0, v[128:129]
	s_mov_b32 m0, s68
	s_nop 0
	global_load_lds_dwordx4 v[220:221], off
	s_waitcnt vmcnt(8)
	s_waitcnt lgkmcnt(0)
	s_barrier
	s_waitcnt lgkmcnt(0)
	v_mfma_f32_16x16x32_bf16 v[124:127], v[140:143], v[180:183], v[124:127]
	v_mfma_f32_16x16x32_bf16 v[120:123], v[156:159], v[180:183], v[120:123]
	v_mfma_f32_16x16x32_bf16 v[112:115], v[140:143], v[188:191], v[112:115]
	v_mfma_f32_16x16x32_bf16 v[104:107], v[156:159], v[188:191], v[104:107]
	v_mfma_f32_16x16x32_bf16 v[96:99], v[140:143], v[196:199], v[96:99]
	v_mfma_f32_16x16x32_bf16 v[88:91], v[156:159], v[196:199], v[88:91]
	v_mfma_f32_16x16x32_bf16 v[80:83], v[140:143], v[206:209], v[80:83]
	v_mfma_f32_16x16x32_bf16 v[72:75], v[156:159], v[206:209], v[72:75]
	v_mfma_f32_16x16x32_bf16 v[124:127], v[152:155], v[184:187], v[124:127]
	v_mfma_f32_16x16x32_bf16 v[120:123], v[160:163], v[184:187], v[120:123]
	v_mfma_f32_16x16x32_bf16 v[112:115], v[152:155], v[192:195], v[112:115]
	v_mfma_f32_16x16x32_bf16 v[104:107], v[160:163], v[192:195], v[104:107]
	v_mfma_f32_16x16x32_bf16 v[96:99], v[152:155], v[202:205], v[96:99]
	v_mfma_f32_16x16x32_bf16 v[88:91], v[160:163], v[202:205], v[88:91]
	v_mfma_f32_16x16x32_bf16 v[80:83], v[152:155], v[210:213], v[80:83]
	v_mfma_f32_16x16x32_bf16 v[72:75], v[160:163], v[210:213], v[72:75]
	v_mfma_f32_16x16x32_bf16 v[116:119], v[164:167], v[180:183], v[116:119]
	v_mfma_f32_16x16x32_bf16 v[108:111], v[172:175], v[180:183], v[108:111]
	v_mfma_f32_16x16x32_bf16 v[100:103], v[164:167], v[188:191], v[100:103]
	v_mfma_f32_16x16x32_bf16 v[92:95], v[172:175], v[188:191], v[92:95]
	v_mfma_f32_16x16x32_bf16 v[84:87], v[164:167], v[196:199], v[84:87]
	v_mfma_f32_16x16x32_bf16 v[76:79], v[172:175], v[196:199], v[76:79]
	v_mfma_f32_16x16x32_bf16 v[68:71], v[164:167], v[206:209], v[68:71]
	v_mfma_f32_16x16x32_bf16 v[64:67], v[172:175], v[206:209], v[64:67]
	v_mfma_f32_16x16x32_bf16 v[116:119], v[168:171], v[184:187], v[116:119]
	v_mfma_f32_16x16x32_bf16 v[108:111], v[176:179], v[184:187], v[108:111]
	v_mfma_f32_16x16x32_bf16 v[100:103], v[168:171], v[192:195], v[100:103]
	v_mfma_f32_16x16x32_bf16 v[92:95], v[176:179], v[192:195], v[92:95]
	v_mfma_f32_16x16x32_bf16 v[84:87], v[168:171], v[202:205], v[84:87]
	v_mfma_f32_16x16x32_bf16 v[76:79], v[176:179], v[202:205], v[76:79]
	v_mfma_f32_16x16x32_bf16 v[68:71], v[168:171], v[210:213], v[68:71]
	v_mfma_f32_16x16x32_bf16 v[64:67], v[176:179], v[210:213], v[64:67]
	s_barrier
	s_add_i32 s60, s81, s64
	v_lshl_add_u64 v[144:145], v[144:145], 0, s[8:9]
	s_mov_b32 m0, s60
	ds_read_b128 v[180:183], v151 offset:49152
	ds_read_b128 v[184:187], v151 offset:50176
	ds_read_b128 v[188:191], v151 offset:51200
	ds_read_b128 v[192:195], v151 offset:52224
	ds_read_b128 v[196:199], v151 offset:53248
	ds_read_b128 v[202:205], v151 offset:54272
	ds_read_b128 v[206:209], v151 offset:55296
	ds_read_b128 v[210:213], v151 offset:56320
	global_load_lds_dwordx4 v[144:145], off
	s_add_i32 m0, s60, 0x2000
	s_add_u32 s58, s58, 0x40080
	v_lshl_add_u64 v[144:145], v[214:215], 0, s[8:9]
	s_addc_u32 s59, s59, 0
	s_add_i32 s60, s82, s64
	global_load_lds_dwordx4 v[144:145], off
	v_lshl_add_u64 v[144:145], s[58:59], 0, v[130:131]
	s_mov_b32 m0, s60
	s_nop 0
	global_load_lds_dwordx4 v[144:145], off
	v_lshl_add_u64 v[144:145], s[58:59], 0, v[128:129]
	s_add_i32 m0, s60, 0x2000
	s_nop 0
	global_load_lds_dwordx4 v[144:145], off
	v_lshl_add_u64 v[144:145], v[216:217], 0, s[8:9]
	s_mov_b32 m0, s70
	s_nop 0
	global_load_lds_dwordx4 v[144:145], off
	v_lshl_add_u64 v[144:145], v[218:219], 0, s[8:9]
	s_mov_b32 m0, s71
	s_nop 0
	global_load_lds_dwordx4 v[144:145], off
	s_waitcnt vmcnt(8)
	s_waitcnt lgkmcnt(0)
	s_barrier
	s_waitcnt lgkmcnt(0)
	v_mfma_f32_16x16x32_bf16 v[60:63], v[140:143], v[180:183], v[60:63]
	v_mfma_f32_16x16x32_bf16 v[56:59], v[156:159], v[180:183], v[56:59]
	v_mfma_f32_16x16x32_bf16 v[48:51], v[140:143], v[188:191], v[48:51]
	v_mfma_f32_16x16x32_bf16 v[40:43], v[156:159], v[188:191], v[40:43]
	v_mfma_f32_16x16x32_bf16 v[32:35], v[140:143], v[196:199], v[32:35]
	v_mfma_f32_16x16x32_bf16 v[24:27], v[156:159], v[196:199], v[24:27]
	v_mfma_f32_16x16x32_bf16 v[16:19], v[140:143], v[206:209], v[16:19]
	v_mfma_f32_16x16x32_bf16 v[8:11], v[156:159], v[206:209], v[8:11]
	v_mfma_f32_16x16x32_bf16 v[60:63], v[152:155], v[184:187], v[60:63]
	v_mfma_f32_16x16x32_bf16 v[56:59], v[160:163], v[184:187], v[56:59]
	v_mfma_f32_16x16x32_bf16 v[48:51], v[152:155], v[192:195], v[48:51]
	v_mfma_f32_16x16x32_bf16 v[40:43], v[160:163], v[192:195], v[40:43]
	v_mfma_f32_16x16x32_bf16 v[32:35], v[152:155], v[202:205], v[32:35]
	v_mfma_f32_16x16x32_bf16 v[24:27], v[160:163], v[202:205], v[24:27]
	v_mfma_f32_16x16x32_bf16 v[16:19], v[152:155], v[210:213], v[16:19]
	v_mfma_f32_16x16x32_bf16 v[8:11], v[160:163], v[210:213], v[8:11]
	v_mfma_f32_16x16x32_bf16 v[52:55], v[164:167], v[180:183], v[52:55]
	v_mfma_f32_16x16x32_bf16 v[44:47], v[172:175], v[180:183], v[44:47]
	v_mfma_f32_16x16x32_bf16 v[36:39], v[164:167], v[188:191], v[36:39]
	v_mfma_f32_16x16x32_bf16 v[28:31], v[172:175], v[188:191], v[28:31]
	v_mfma_f32_16x16x32_bf16 v[20:23], v[164:167], v[196:199], v[20:23]
	v_mfma_f32_16x16x32_bf16 v[12:15], v[172:175], v[196:199], v[12:15]
	v_mfma_f32_16x16x32_bf16 v[4:7], v[164:167], v[206:209], v[4:7]
	v_mfma_f32_16x16x32_bf16 v[0:3], v[172:175], v[206:209], v[0:3]
	v_mfma_f32_16x16x32_bf16 v[52:55], v[168:171], v[184:187], v[52:55]
	v_mfma_f32_16x16x32_bf16 v[44:47], v[176:179], v[184:187], v[44:47]
	v_mfma_f32_16x16x32_bf16 v[36:39], v[168:171], v[192:195], v[36:39]
	v_mfma_f32_16x16x32_bf16 v[28:31], v[176:179], v[192:195], v[28:31]
	v_mfma_f32_16x16x32_bf16 v[20:23], v[168:171], v[202:205], v[20:23]
	v_mfma_f32_16x16x32_bf16 v[12:15], v[176:179], v[202:205], v[12:15]
	v_mfma_f32_16x16x32_bf16 v[4:7], v[168:171], v[210:213], v[4:7]
	v_mfma_f32_16x16x32_bf16 v[0:3], v[176:179], v[210:213], v[0:3]
	s_barrier
	s_add_i32 s80, s80, 2
	s_add_u32 s56, s56, 0x100
	s_addc_u32 s57, s57, 0
	s_add_u32 s78, s78, 0x100
	s_addc_u32 s79, s79, 0
	s_cmp_gt_u32 s80, 13
	s_cbranch_scc0 .LBB0_1415
	s_setprio 0
	s_and_b64 vcc, exec, s[10:11]
	s_cbranch_vccz .LBB0_1418
	s_barrier

.LBB0_1551:
	s_ashr_i32 s55, s54, 31
	s_lshl_b64 s[56:57], s[54:55], 19
	s_add_u32 s56, s17, s56
	s_addc_u32 s57, s66, s57
	s_and_b64 s[58:59], s[6:7], exec
	s_cselect_b32 s55, s57, s61
	s_cselect_b32 s84, s56, s60
	s_ashr_i32 s53, s52, 31
	s_lshl_b64 s[58:59], s[52:53], 19
	s_add_u32 s58, s67, s58
	s_addc_u32 s59, s68, s59
	s_and_b64 s[64:65], s[6:7], exec
	s_cselect_b32 s53, s59, s63
	s_cselect_b32 s85, s58, s62
	s_add_u32 s60, s60, 0x40080
	s_addc_u32 s61, s61, 0
	s_add_u32 s86, s62, 0x100
	s_addc_u32 s87, s63, 0
	s_mov_b32 s88, -2
	v_mov_b64_e32 v[0:1], 0
	v_mov_b64_e32 v[2:3], 0
	v_mov_b64_e32 v[4:5], 0
	v_mov_b64_e32 v[6:7], 0
	v_mov_b64_e32 v[8:9], 0
	v_mov_b64_e32 v[10:11], 0
	v_mov_b64_e32 v[12:13], 0
	v_mov_b64_e32 v[14:15], 0
	v_mov_b64_e32 v[16:17], 0
	v_mov_b64_e32 v[18:19], 0
	v_mov_b64_e32 v[20:21], 0
	v_mov_b64_e32 v[22:23], 0
	v_mov_b64_e32 v[24:25], 0
	v_mov_b64_e32 v[26:27], 0
	v_mov_b64_e32 v[28:29], 0
	v_mov_b64_e32 v[30:31], 0
	v_mov_b64_e32 v[32:33], 0
	v_mov_b64_e32 v[34:35], 0
	v_mov_b64_e32 v[36:37], 0
	v_mov_b64_e32 v[38:39], 0
	v_mov_b64_e32 v[40:41], 0
	v_mov_b64_e32 v[42:43], 0
	v_mov_b64_e32 v[44:45], 0
	v_mov_b64_e32 v[46:47], 0
	v_mov_b64_e32 v[48:49], 0
	v_mov_b64_e32 v[50:51], 0
	v_mov_b64_e32 v[52:53], 0
	v_mov_b64_e32 v[54:55], 0
	v_mov_b64_e32 v[56:57], 0
	v_mov_b64_e32 v[58:59], 0
	v_mov_b64_e32 v[60:61], 0
	v_mov_b64_e32 v[62:63], 0
	v_mov_b64_e32 v[96:97], 0
	v_mov_b64_e32 v[98:99], 0
	v_mov_b64_e32 v[100:101], 0
	v_mov_b64_e32 v[102:103], 0
	v_mov_b64_e32 v[104:105], 0
	v_mov_b64_e32 v[106:107], 0
	v_mov_b64_e32 v[108:109], 0
	v_mov_b64_e32 v[110:111], 0
	v_mov_b64_e32 v[112:113], 0
	v_mov_b64_e32 v[114:115], 0
	v_mov_b64_e32 v[116:117], 0
	v_mov_b64_e32 v[118:119], 0
	v_mov_b64_e32 v[120:121], 0
	v_mov_b64_e32 v[122:123], 0
	v_mov_b64_e32 v[124:125], 0
	v_mov_b64_e32 v[126:127], 0
	v_mov_b64_e32 v[128:129], 0
	v_mov_b64_e32 v[130:131], 0
	v_mov_b64_e32 v[132:133], 0
	v_mov_b64_e32 v[134:135], 0
	v_mov_b64_e32 v[136:137], 0
	v_mov_b64_e32 v[138:139], 0
	v_mov_b64_e32 v[140:141], 0
	v_mov_b64_e32 v[142:143], 0
	v_mov_b64_e32 v[144:145], 0
	v_mov_b64_e32 v[146:147], 0
	v_mov_b64_e32 v[148:149], 0
	v_mov_b64_e32 v[150:151], 0
	v_mov_b64_e32 v[152:153], 0
	v_mov_b64_e32 v[154:155], 0
	v_mov_b64_e32 v[156:157], 0
	v_mov_b64_e32 v[158:159], 0
	v_lshrrev_b32_e32 v253, 8, v200
	s_nop 0
	v_readfirstlane_b32 s98, v253
	s_cmp_lg_u32 s98, 0
	s_cbranch_scc0 .Lgp_1552
	s_setprio 1
.Lgp_1552:
.LBB0_1552:
	ds_read_b128 v[64:67], v203
	ds_read_b128 v[68:71], v203 offset:1024
	ds_read_b128 v[72:75], v203 offset:2048
	ds_read_b128 v[76:79], v203 offset:3072
	ds_read_b128 v[80:83], v204
	ds_read_b128 v[84:87], v204 offset:1024
	ds_read_b128 v[88:91], v204 offset:2048
	ds_read_b128 v[92:95], v204 offset:3072
	s_add_u32 s62, s60, 0xfffc0080
	s_addc_u32 s63, s61, -1
	s_cmp_eq_u32 s88, 12
	s_cselect_b32 s65, s55, s63
	s_cselect_b32 s64, s84, s62
	s_cselect_b32 s63, s53, s87
	s_cselect_b32 s62, s85, s86
	v_lshl_add_u64 v[220:221], s[60:61], 0, v[172:173]
	s_add_i32 m0, s71, 0xc000
	ds_read_b128 v[180:183], v205
	ds_read_b128 v[184:187], v205 offset:1024
	ds_read_b128 v[188:191], v205 offset:2048
	ds_read_b128 v[192:195], v205 offset:3072
	ds_read_b128 v[196:199], v205 offset:4096
	ds_read_b128 v[208:211], v205 offset:5120
	ds_read_b128 v[212:215], v205 offset:6144
	ds_read_b128 v[216:219], v205 offset:7168
	global_load_lds_dwordx4 v[220:221], off
	v_lshl_add_u64 v[220:221], s[60:61], 0, v[174:175]
	s_add_i32 m0, s71, 0xe000
	s_nop 0
	global_load_lds_dwordx4 v[220:221], off
	s_waitcnt vmcnt(8)
	s_waitcnt lgkmcnt(0)
	s_barrier
	s_waitcnt lgkmcnt(0)
	v_mfma_f32_16x16x32_bf16 v[148:151], v[64:67], v[180:183], v[148:151]
	v_mfma_f32_16x16x32_bf16 v[144:147], v[72:75], v[180:183], v[144:147]
	v_mfma_f32_16x16x32_bf16 v[132:135], v[64:67], v[188:191], v[132:135]
	v_mfma_f32_16x16x32_bf16 v[128:131], v[72:75], v[188:191], v[128:131]
	v_mfma_f32_16x16x32_bf16 v[116:119], v[64:67], v[196:199], v[116:119]
	v_mfma_f32_16x16x32_bf16 v[112:115], v[72:75], v[196:199], v[112:115]
	v_mfma_f32_16x16x32_bf16 v[104:107], v[64:67], v[212:215], v[104:107]
	v_mfma_f32_16x16x32_bf16 v[100:103], v[72:75], v[212:215], v[100:103]
	v_mfma_f32_16x16x32_bf16 v[148:151], v[68:71], v[184:187], v[148:151]
	v_mfma_f32_16x16x32_bf16 v[144:147], v[76:79], v[184:187], v[144:147]
	v_mfma_f32_16x16x32_bf16 v[132:135], v[68:71], v[192:195], v[132:135]
	v_mfma_f32_16x16x32_bf16 v[128:131], v[76:79], v[192:195], v[128:131]
	v_mfma_f32_16x16x32_bf16 v[116:119], v[68:71], v[208:211], v[116:119]
	v_mfma_f32_16x16x32_bf16 v[112:115], v[76:79], v[208:211], v[112:115]
	v_mfma_f32_16x16x32_bf16 v[104:107], v[68:71], v[216:219], v[104:107]
	v_mfma_f32_16x16x32_bf16 v[100:103], v[76:79], v[216:219], v[100:103]
	v_mfma_f32_16x16x32_bf16 v[152:155], v[80:83], v[180:183], v[152:155]
	v_mfma_f32_16x16x32_bf16 v[156:159], v[88:91], v[180:183], v[156:159]
	v_mfma_f32_16x16x32_bf16 v[136:139], v[80:83], v[188:191], v[136:139]
	v_mfma_f32_16x16x32_bf16 v[140:143], v[88:91], v[188:191], v[140:143]
	v_mfma_f32_16x16x32_bf16 v[120:123], v[80:83], v[196:199], v[120:123]
	v_mfma_f32_16x16x32_bf16 v[124:127], v[88:91], v[196:199], v[124:127]
	v_mfma_f32_16x16x32_bf16 v[96:99], v[80:83], v[212:215], v[96:99]
	v_mfma_f32_16x16x32_bf16 v[108:111], v[88:91], v[212:215], v[108:111]
	v_mfma_f32_16x16x32_bf16 v[152:155], v[84:87], v[184:187], v[152:155]
	v_mfma_f32_16x16x32_bf16 v[156:159], v[92:95], v[184:187], v[156:159]
	v_mfma_f32_16x16x32_bf16 v[136:139], v[84:87], v[192:195], v[136:139]
	v_mfma_f32_16x16x32_bf16 v[140:143], v[92:95], v[192:195], v[140:143]
	v_mfma_f32_16x16x32_bf16 v[120:123], v[84:87], v[208:211], v[120:123]
	v_mfma_f32_16x16x32_bf16 v[124:127], v[92:95], v[208:211], v[124:127]
	v_mfma_f32_16x16x32_bf16 v[96:99], v[84:87], v[216:219], v[96:99]
	v_mfma_f32_16x16x32_bf16 v[108:111], v[92:95], v[216:219], v[108:111]
	s_barrier
	s_add_i32 s89, s80, s70
	v_lshl_add_u64 v[220:221], s[62:63], 0, v[164:165]
	s_mov_b32 m0, s89
	ds_read_b128 v[180:183], v205 offset:16384
	ds_read_b128 v[184:187], v205 offset:17408
	ds_read_b128 v[188:191], v205 offset:18432
	ds_read_b128 v[192:195], v205 offset:19456
	ds_read_b128 v[196:199], v205 offset:20480
	ds_read_b128 v[208:211], v205 offset:21504
	ds_read_b128 v[212:215], v205 offset:22528
	ds_read_b128 v[216:219], v205 offset:23552
	global_load_lds_dwordx4 v[220:221], off
	s_add_i32 m0, s89, 0x2000
	s_add_u32 s90, s62, 0x40000
	v_lshl_add_u64 v[222:223], s[62:63], 0, v[160:161]
	s_addc_u32 s91, s63, 0
	s_add_i32 s89, s81, s70
	global_load_lds_dwordx4 v[222:223], off
	v_lshl_add_u64 v[224:225], s[90:91], 0, v[164:165]
	s_mov_b32 m0, s89
	v_lshl_add_u64 v[226:227], s[64:65], 0, v[162:163]
	global_load_lds_dwordx4 v[224:225], off
	v_lshl_add_u64 v[224:225], s[90:91], 0, v[160:161]
	s_add_i32 m0, s89, 0x2000
	s_nop 0
	global_load_lds_dwordx4 v[224:225], off
	v_lshl_add_u64 v[224:225], s[64:65], 0, v[166:167]
	s_mov_b32 m0, s71
	s_nop 0
	global_load_lds_dwordx4 v[224:225], off
	s_mov_b32 m0, s72
	s_nop 0
	global_load_lds_dwordx4 v[226:227], off
	s_waitcnt vmcnt(8)
	s_waitcnt lgkmcnt(0)
	s_barrier
	s_waitcnt lgkmcnt(0)
	v_mfma_f32_16x16x32_bf16 v[52:55], v[64:67], v[180:183], v[52:55]
	v_mfma_f32_16x16x32_bf16 v[48:51], v[72:75], v[180:183], v[48:51]
	v_mfma_f32_16x16x32_bf16 v[36:39], v[64:67], v[188:191], v[36:39]
	v_mfma_f32_16x16x32_bf16 v[32:35], v[72:75], v[188:191], v[32:35]
	v_mfma_f32_16x16x32_bf16 v[20:23], v[64:67], v[196:199], v[20:23]
	v_mfma_f32_16x16x32_bf16 v[16:19], v[72:75], v[196:199], v[16:19]
	v_mfma_f32_16x16x32_bf16 v[8:11], v[64:67], v[212:215], v[8:11]
	v_mfma_f32_16x16x32_bf16 v[4:7], v[72:75], v[212:215], v[4:7]
	v_mfma_f32_16x16x32_bf16 v[52:55], v[68:71], v[184:187], v[52:55]
	v_mfma_f32_16x16x32_bf16 v[48:51], v[76:79], v[184:187], v[48:51]
	v_mfma_f32_16x16x32_bf16 v[36:39], v[68:71], v[192:195], v[36:39]
	v_mfma_f32_16x16x32_bf16 v[32:35], v[76:79], v[192:195], v[32:35]
	v_mfma_f32_16x16x32_bf16 v[20:23], v[68:71], v[208:211], v[20:23]
	v_mfma_f32_16x16x32_bf16 v[16:19], v[76:79], v[208:211], v[16:19]
	v_mfma_f32_16x16x32_bf16 v[8:11], v[68:71], v[216:219], v[8:11]
	v_mfma_f32_16x16x32_bf16 v[4:7], v[76:79], v[216:219], v[4:7]
	v_mfma_f32_16x16x32_bf16 v[56:59], v[80:83], v[180:183], v[56:59]
	v_mfma_f32_16x16x32_bf16 v[60:63], v[88:91], v[180:183], v[60:63]
	v_mfma_f32_16x16x32_bf16 v[40:43], v[80:83], v[188:191], v[40:43]
	v_mfma_f32_16x16x32_bf16 v[44:47], v[88:91], v[188:191], v[44:47]
	v_mfma_f32_16x16x32_bf16 v[24:27], v[80:83], v[196:199], v[24:27]
	v_mfma_f32_16x16x32_bf16 v[28:31], v[88:91], v[196:199], v[28:31]
	v_mfma_f32_16x16x32_bf16 v[0:3], v[80:83], v[212:215], v[0:3]
	v_mfma_f32_16x16x32_bf16 v[12:15], v[88:91], v[212:215], v[12:15]
	v_mfma_f32_16x16x32_bf16 v[56:59], v[84:87], v[184:187], v[56:59]
	v_mfma_f32_16x16x32_bf16 v[60:63], v[92:95], v[184:187], v[60:63]
	v_mfma_f32_16x16x32_bf16 v[40:43], v[84:87], v[192:195], v[40:43]
	v_mfma_f32_16x16x32_bf16 v[44:47], v[92:95], v[192:195], v[44:47]
	v_mfma_f32_16x16x32_bf16 v[24:27], v[84:87], v[208:211], v[24:27]
	v_mfma_f32_16x16x32_bf16 v[28:31], v[92:95], v[208:211], v[28:31]
	v_mfma_f32_16x16x32_bf16 v[0:3], v[84:87], v[216:219], v[0:3]
	v_mfma_f32_16x16x32_bf16 v[12:15], v[92:95], v[216:219], v[12:15]
	s_barrier
	s_add_i32 s89, 0, 0x18000
	s_add_i32 s90, 0, 0x1c000
	v_add_u32_e32 v76, s89, v201
	v_add_u32_e32 v92, s90, v201
	ds_read_b128 v[64:67], v76
	ds_read_b128 v[68:71], v76 offset:1024
	ds_read_b128 v[72:75], v76 offset:2048
	ds_read_b128 v[76:79], v76 offset:3072
	ds_read_b128 v[80:83], v92
	ds_read_b128 v[84:87], v92 offset:1024
	ds_read_b128 v[88:91], v92 offset:2048
	ds_read_b128 v[92:95], v92 offset:3072
	s_add_u32 s64, s64, 0x40000
	s_addc_u32 s65, s65, 0
	s_mov_b32 m0, s73
	v_lshl_add_u64 v[228:229], s[64:65], 0, v[166:167]
	ds_read_b128 v[180:183], v205 offset:32768
	ds_read_b128 v[184:187], v205 offset:33792
	ds_read_b128 v[188:191], v205 offset:34816
	ds_read_b128 v[192:195], v205 offset:35840
	ds_read_b128 v[196:199], v205 offset:36864
	ds_read_b128 v[208:211], v205 offset:37888
	ds_read_b128 v[212:215], v205 offset:38912
	ds_read_b128 v[216:219], v205 offset:39936
	global_load_lds_dwordx4 v[228:229], off
	v_lshl_add_u64 v[228:229], s[64:65], 0, v[162:163]
	s_mov_b32 m0, s74
	s_nop 0
	global_load_lds_dwordx4 v[228:229], off
	s_waitcnt vmcnt(8)
	s_waitcnt lgkmcnt(0)
	s_barrier
	s_waitcnt lgkmcnt(0)
	v_mfma_f32_16x16x32_bf16 v[148:151], v[64:67], v[180:183], v[148:151]
	v_mfma_f32_16x16x32_bf16 v[144:147], v[72:75], v[180:183], v[144:147]
	v_mfma_f32_16x16x32_bf16 v[132:135], v[64:67], v[188:191], v[132:135]
	v_mfma_f32_16x16x32_bf16 v[128:131], v[72:75], v[188:191], v[128:131]
	v_mfma_f32_16x16x32_bf16 v[116:119], v[64:67], v[196:199], v[116:119]
	v_mfma_f32_16x16x32_bf16 v[112:115], v[72:75], v[196:199], v[112:115]
	v_mfma_f32_16x16x32_bf16 v[104:107], v[64:67], v[212:215], v[104:107]
	v_mfma_f32_16x16x32_bf16 v[100:103], v[72:75], v[212:215], v[100:103]
	v_mfma_f32_16x16x32_bf16 v[148:151], v[68:71], v[184:187], v[148:151]
	v_mfma_f32_16x16x32_bf16 v[144:147], v[76:79], v[184:187], v[144:147]
	v_mfma_f32_16x16x32_bf16 v[132:135], v[68:71], v[192:195], v[132:135]
	v_mfma_f32_16x16x32_bf16 v[128:131], v[76:79], v[192:195], v[128:131]
	v_mfma_f32_16x16x32_bf16 v[116:119], v[68:71], v[208:211], v[116:119]
	v_mfma_f32_16x16x32_bf16 v[112:115], v[76:79], v[208:211], v[112:115]
	v_mfma_f32_16x16x32_bf16 v[104:107], v[68:71], v[216:219], v[104:107]
	v_mfma_f32_16x16x32_bf16 v[100:103], v[76:79], v[216:219], v[100:103]
	v_mfma_f32_16x16x32_bf16 v[152:155], v[80:83], v[180:183], v[152:155]
	v_mfma_f32_16x16x32_bf16 v[156:159], v[88:91], v[180:183], v[156:159]
	v_mfma_f32_16x16x32_bf16 v[136:139], v[80:83], v[188:191], v[136:139]
	v_mfma_f32_16x16x32_bf16 v[140:143], v[88:91], v[188:191], v[140:143]
	v_mfma_f32_16x16x32_bf16 v[120:123], v[80:83], v[196:199], v[120:123]
	v_mfma_f32_16x16x32_bf16 v[124:127], v[88:91], v[196:199], v[124:127]
	v_mfma_f32_16x16x32_bf16 v[96:99], v[80:83], v[212:215], v[96:99]
	v_mfma_f32_16x16x32_bf16 v[108:111], v[88:91], v[212:215], v[108:111]
	v_mfma_f32_16x16x32_bf16 v[152:155], v[84:87], v[184:187], v[152:155]
	v_mfma_f32_16x16x32_bf16 v[156:159], v[92:95], v[184:187], v[156:159]
	v_mfma_f32_16x16x32_bf16 v[136:139], v[84:87], v[192:195], v[136:139]
	v_mfma_f32_16x16x32_bf16 v[140:143], v[92:95], v[192:195], v[140:143]
	v_mfma_f32_16x16x32_bf16 v[120:123], v[84:87], v[208:211], v[120:123]
	v_mfma_f32_16x16x32_bf16 v[124:127], v[92:95], v[208:211], v[124:127]
	v_mfma_f32_16x16x32_bf16 v[96:99], v[84:87], v[216:219], v[96:99]
	v_mfma_f32_16x16x32_bf16 v[108:111], v[92:95], v[216:219], v[108:111]
	s_barrier
	s_add_i32 s64, s89, s70
	v_lshl_add_u64 v[220:221], v[220:221], 0, s[36:37]
	s_mov_b32 m0, s64
	ds_read_b128 v[180:183], v205 offset:49152
	ds_read_b128 v[184:187], v205 offset:50176
	ds_read_b128 v[188:191], v205 offset:51200
	ds_read_b128 v[192:195], v205 offset:52224
	ds_read_b128 v[196:199], v205 offset:53248
	ds_read_b128 v[208:211], v205 offset:54272
	ds_read_b128 v[212:215], v205 offset:55296
	ds_read_b128 v[216:219], v205 offset:56320
	global_load_lds_dwordx4 v[220:221], off
	s_add_i32 m0, s64, 0x2000
	s_add_u32 s62, s62, 0x40080
	v_lshl_add_u64 v[220:221], v[222:223], 0, s[36:37]
	s_addc_u32 s63, s63, 0
	s_add_i32 s64, s90, s70
	global_load_lds_dwordx4 v[220:221], off
	v_lshl_add_u64 v[220:221], s[62:63], 0, v[164:165]
	s_mov_b32 m0, s64
	s_nop 0
	global_load_lds_dwordx4 v[220:221], off
	v_lshl_add_u64 v[220:221], s[62:63], 0, v[160:161]
	s_add_i32 m0, s64, 0x2000
	s_nop 0
	global_load_lds_dwordx4 v[220:221], off
	v_lshl_add_u64 v[220:221], v[224:225], 0, s[36:37]
	s_mov_b32 m0, s76
	s_nop 0
	global_load_lds_dwordx4 v[220:221], off
	v_lshl_add_u64 v[220:221], v[226:227], 0, s[36:37]
	s_mov_b32 m0, s77
	s_nop 0
	global_load_lds_dwordx4 v[220:221], off
	s_waitcnt vmcnt(8)
	s_waitcnt lgkmcnt(0)
	s_barrier
	s_waitcnt lgkmcnt(0)
	v_mfma_f32_16x16x32_bf16 v[52:55], v[64:67], v[180:183], v[52:55]
	v_mfma_f32_16x16x32_bf16 v[48:51], v[72:75], v[180:183], v[48:51]
	v_mfma_f32_16x16x32_bf16 v[36:39], v[64:67], v[188:191], v[36:39]
	v_mfma_f32_16x16x32_bf16 v[32:35], v[72:75], v[188:191], v[32:35]
	v_mfma_f32_16x16x32_bf16 v[20:23], v[64:67], v[196:199], v[20:23]
	v_mfma_f32_16x16x32_bf16 v[16:19], v[72:75], v[196:199], v[16:19]
	v_mfma_f32_16x16x32_bf16 v[8:11], v[64:67], v[212:215], v[8:11]
	v_mfma_f32_16x16x32_bf16 v[4:7], v[72:75], v[212:215], v[4:7]
	v_mfma_f32_16x16x32_bf16 v[52:55], v[68:71], v[184:187], v[52:55]
	v_mfma_f32_16x16x32_bf16 v[48:51], v[76:79], v[184:187], v[48:51]
	v_mfma_f32_16x16x32_bf16 v[36:39], v[68:71], v[192:195], v[36:39]
	v_mfma_f32_16x16x32_bf16 v[32:35], v[76:79], v[192:195], v[32:35]
	v_mfma_f32_16x16x32_bf16 v[20:23], v[68:71], v[208:211], v[20:23]
	v_mfma_f32_16x16x32_bf16 v[16:19], v[76:79], v[208:211], v[16:19]
	v_mfma_f32_16x16x32_bf16 v[8:11], v[68:71], v[216:219], v[8:11]
	v_mfma_f32_16x16x32_bf16 v[4:7], v[76:79], v[216:219], v[4:7]
	v_mfma_f32_16x16x32_bf16 v[56:59], v[80:83], v[180:183], v[56:59]
	v_mfma_f32_16x16x32_bf16 v[60:63], v[88:91], v[180:183], v[60:63]
	v_mfma_f32_16x16x32_bf16 v[40:43], v[80:83], v[188:191], v[40:43]
	v_mfma_f32_16x16x32_bf16 v[44:47], v[88:91], v[188:191], v[44:47]
	v_mfma_f32_16x16x32_bf16 v[24:27], v[80:83], v[196:199], v[24:27]
	v_mfma_f32_16x16x32_bf16 v[28:31], v[88:91], v[196:199], v[28:31]
	v_mfma_f32_16x16x32_bf16 v[0:3], v[80:83], v[212:215], v[0:3]
	v_mfma_f32_16x16x32_bf16 v[12:15], v[88:91], v[212:215], v[12:15]
	v_mfma_f32_16x16x32_bf16 v[56:59], v[84:87], v[184:187], v[56:59]
	v_mfma_f32_16x16x32_bf16 v[60:63], v[92:95], v[184:187], v[60:63]
	v_mfma_f32_16x16x32_bf16 v[40:43], v[84:87], v[192:195], v[40:43]
	v_mfma_f32_16x16x32_bf16 v[44:47], v[92:95], v[192:195], v[44:47]
	v_mfma_f32_16x16x32_bf16 v[24:27], v[84:87], v[208:211], v[24:27]
	v_mfma_f32_16x16x32_bf16 v[28:31], v[92:95], v[208:211], v[28:31]
	v_mfma_f32_16x16x32_bf16 v[0:3], v[84:87], v[216:219], v[0:3]
	v_mfma_f32_16x16x32_bf16 v[12:15], v[92:95], v[216:219], v[12:15]
	s_barrier
	s_add_i32 s88, s88, 2
	s_add_u32 s60, s60, 0x100
	s_addc_u32 s61, s61, 0
	s_add_u32 s86, s86, 0x100
	s_addc_u32 s87, s87, 0
	s_cmp_gt_u32 s88, 13
	s_cbranch_scc0 .LBB0_1552
	s_setprio 0
	s_and_b64 vcc, exec, s[38:39]
	s_cbranch_vccz .LBB0_1555
	s_barrier

.LBB0_1703:
	s_add_u32 s44, s44, 0xb0080
	s_addc_u32 s45, s45, 0
	s_add_u32 s66, s46, 0x100
	s_addc_u32 s67, s47, 0
	s_mov_b32 s68, -2
	v_mov_b64_e32 v[0:1], 0
	v_mov_b64_e32 v[2:3], 0
	v_mov_b64_e32 v[4:5], 0
	v_mov_b64_e32 v[6:7], 0
	v_mov_b64_e32 v[8:9], 0
	v_mov_b64_e32 v[10:11], 0
	v_mov_b64_e32 v[12:13], 0
	v_mov_b64_e32 v[14:15], 0
	v_mov_b64_e32 v[16:17], 0
	v_mov_b64_e32 v[18:19], 0
	v_mov_b64_e32 v[20:21], 0
	v_mov_b64_e32 v[22:23], 0
	v_mov_b64_e32 v[24:25], 0
	v_mov_b64_e32 v[26:27], 0
	v_mov_b64_e32 v[28:29], 0
	v_mov_b64_e32 v[30:31], 0
	v_mov_b64_e32 v[32:33], 0
	v_mov_b64_e32 v[34:35], 0
	v_mov_b64_e32 v[36:37], 0
	v_mov_b64_e32 v[38:39], 0
	v_mov_b64_e32 v[40:41], 0
	v_mov_b64_e32 v[42:43], 0
	v_mov_b64_e32 v[44:45], 0
	v_mov_b64_e32 v[46:47], 0
	v_mov_b64_e32 v[48:49], 0
	v_mov_b64_e32 v[50:51], 0
	v_mov_b64_e32 v[52:53], 0
	v_mov_b64_e32 v[54:55], 0
	v_mov_b64_e32 v[56:57], 0
	v_mov_b64_e32 v[58:59], 0
	v_mov_b64_e32 v[60:61], 0
	v_mov_b64_e32 v[62:63], 0
	v_mov_b64_e32 v[64:65], 0
	v_mov_b64_e32 v[66:67], 0
	v_mov_b64_e32 v[68:69], 0
	v_mov_b64_e32 v[70:71], 0
	v_mov_b64_e32 v[72:73], 0
	v_mov_b64_e32 v[74:75], 0
	v_mov_b64_e32 v[76:77], 0
	v_mov_b64_e32 v[78:79], 0
	v_mov_b64_e32 v[80:81], 0
	v_mov_b64_e32 v[82:83], 0
	v_mov_b64_e32 v[84:85], 0
	v_mov_b64_e32 v[86:87], 0
	v_mov_b64_e32 v[88:89], 0
	v_mov_b64_e32 v[90:91], 0
	v_mov_b64_e32 v[92:93], 0
	v_mov_b64_e32 v[94:95], 0
	v_mov_b64_e32 v[96:97], 0
	v_mov_b64_e32 v[98:99], 0
	v_mov_b64_e32 v[100:101], 0
	v_mov_b64_e32 v[102:103], 0
	v_mov_b64_e32 v[104:105], 0
	v_mov_b64_e32 v[106:107], 0
	v_mov_b64_e32 v[108:109], 0
	v_mov_b64_e32 v[110:111], 0
	v_mov_b64_e32 v[112:113], 0
	v_mov_b64_e32 v[114:115], 0
	v_mov_b64_e32 v[116:117], 0
	v_mov_b64_e32 v[118:119], 0
	v_mov_b64_e32 v[120:121], 0
	v_mov_b64_e32 v[122:123], 0
	v_mov_b64_e32 v[124:125], 0
	v_mov_b64_e32 v[126:127], 0
	s_waitcnt vmcnt(0)
	v_lshrrev_b32_e32 v253, 8, v200
	s_nop 0
	v_readfirstlane_b32 s98, v253
	s_cmp_lg_u32 s98, 0
	s_cbranch_scc0 .Lgp_1704
	s_setprio 1
.Lgp_1704:
.LBB0_1704:
	ds_read_b128 v[140:143], v149
	ds_read_b128 v[152:155], v149 offset:1024
	ds_read_b128 v[156:159], v149 offset:2048
	ds_read_b128 v[160:163], v149 offset:3072
	ds_read_b128 v[164:167], v150
	ds_read_b128 v[168:171], v150 offset:1024
	ds_read_b128 v[172:175], v150 offset:2048
	ds_read_b128 v[176:179], v150 offset:3072
	s_add_u32 s46, s44, 0xfff50080
	s_addc_u32 s47, s45, -1
	s_cmp_eq_u32 s68, 40
	s_cselect_b32 s49, s5, s47
	s_cselect_b32 s48, s4, s46
	s_cselect_b32 s47, s39, s67
	s_cselect_b32 s46, s38, s66
	v_lshl_add_u64 v[144:145], s[44:45], 0, v[132:133]
	s_add_i32 m0, s53, 0xc000
	ds_read_b128 v[180:183], v151
	ds_read_b128 v[184:187], v151 offset:1024
	ds_read_b128 v[188:191], v151 offset:2048
	ds_read_b128 v[192:195], v151 offset:3072
	ds_read_b128 v[196:199], v151 offset:4096
	ds_read_b128 v[202:205], v151 offset:5120
	ds_read_b128 v[206:209], v151 offset:6144
	ds_read_b128 v[210:213], v151 offset:7168
	global_load_lds_dwordx4 v[144:145], off
	v_lshl_add_u64 v[144:145], s[44:45], 0, v[134:135]
	s_add_i32 m0, s53, 0xe000
	s_nop 0
	global_load_lds_dwordx4 v[144:145], off
	s_waitcnt vmcnt(8)
	s_waitcnt lgkmcnt(0)
	s_barrier
	s_waitcnt lgkmcnt(0)
	v_mfma_f32_16x16x32_bf16 v[124:127], v[140:143], v[180:183], v[124:127]
	v_mfma_f32_16x16x32_bf16 v[120:123], v[156:159], v[180:183], v[120:123]
	v_mfma_f32_16x16x32_bf16 v[112:115], v[140:143], v[188:191], v[112:115]
	v_mfma_f32_16x16x32_bf16 v[104:107], v[156:159], v[188:191], v[104:107]
	v_mfma_f32_16x16x32_bf16 v[96:99], v[140:143], v[196:199], v[96:99]
	v_mfma_f32_16x16x32_bf16 v[88:91], v[156:159], v[196:199], v[88:91]
	v_mfma_f32_16x16x32_bf16 v[80:83], v[140:143], v[206:209], v[80:83]
	v_mfma_f32_16x16x32_bf16 v[72:75], v[156:159], v[206:209], v[72:75]
	v_mfma_f32_16x16x32_bf16 v[124:127], v[152:155], v[184:187], v[124:127]
	v_mfma_f32_16x16x32_bf16 v[120:123], v[160:163], v[184:187], v[120:123]
	v_mfma_f32_16x16x32_bf16 v[112:115], v[152:155], v[192:195], v[112:115]
	v_mfma_f32_16x16x32_bf16 v[104:107], v[160:163], v[192:195], v[104:107]
	v_mfma_f32_16x16x32_bf16 v[96:99], v[152:155], v[202:205], v[96:99]
	v_mfma_f32_16x16x32_bf16 v[88:91], v[160:163], v[202:205], v[88:91]
	v_mfma_f32_16x16x32_bf16 v[80:83], v[152:155], v[210:213], v[80:83]
	v_mfma_f32_16x16x32_bf16 v[72:75], v[160:163], v[210:213], v[72:75]
	v_mfma_f32_16x16x32_bf16 v[116:119], v[164:167], v[180:183], v[116:119]
	v_mfma_f32_16x16x32_bf16 v[108:111], v[172:175], v[180:183], v[108:111]
	v_mfma_f32_16x16x32_bf16 v[100:103], v[164:167], v[188:191], v[100:103]
	v_mfma_f32_16x16x32_bf16 v[92:95], v[172:175], v[188:191], v[92:95]
	v_mfma_f32_16x16x32_bf16 v[84:87], v[164:167], v[196:199], v[84:87]
	v_mfma_f32_16x16x32_bf16 v[76:79], v[172:175], v[196:199], v[76:79]
	v_mfma_f32_16x16x32_bf16 v[68:71], v[164:167], v[206:209], v[68:71]
	v_mfma_f32_16x16x32_bf16 v[64:67], v[172:175], v[206:209], v[64:67]
	v_mfma_f32_16x16x32_bf16 v[116:119], v[168:171], v[184:187], v[116:119]
	v_mfma_f32_16x16x32_bf16 v[108:111], v[176:179], v[184:187], v[108:111]
	v_mfma_f32_16x16x32_bf16 v[100:103], v[168:171], v[192:195], v[100:103]
	v_mfma_f32_16x16x32_bf16 v[92:95], v[176:179], v[192:195], v[92:95]
	v_mfma_f32_16x16x32_bf16 v[84:87], v[168:171], v[202:205], v[84:87]
	v_mfma_f32_16x16x32_bf16 v[76:79], v[176:179], v[202:205], v[76:79]
	v_mfma_f32_16x16x32_bf16 v[68:71], v[168:171], v[210:213], v[68:71]
	v_mfma_f32_16x16x32_bf16 v[64:67], v[176:179], v[210:213], v[64:67]
	s_barrier
	s_add_i32 s69, s62, s52
	v_lshl_add_u64 v[144:145], s[46:47], 0, v[130:131]
	s_mov_b32 m0, s69
	ds_read_b128 v[180:183], v151 offset:16384
	ds_read_b128 v[184:187], v151 offset:17408
	ds_read_b128 v[188:191], v151 offset:18432
	ds_read_b128 v[192:195], v151 offset:19456
	ds_read_b128 v[196:199], v151 offset:20480
	ds_read_b128 v[202:205], v151 offset:21504
	ds_read_b128 v[206:209], v151 offset:22528
	ds_read_b128 v[210:213], v151 offset:23552
	global_load_lds_dwordx4 v[144:145], off
	s_add_i32 m0, s69, 0x2000
	s_add_u32 s70, s46, 0xb0000
	v_lshl_add_u64 v[214:215], s[46:47], 0, v[128:129]
	s_addc_u32 s71, s47, 0
	s_add_i32 s69, s63, s52
	global_load_lds_dwordx4 v[214:215], off
	v_lshl_add_u64 v[216:217], s[70:71], 0, v[130:131]
	s_mov_b32 m0, s69
	v_lshl_add_u64 v[218:219], s[48:49], 0, v[128:129]
	global_load_lds_dwordx4 v[216:217], off
	v_lshl_add_u64 v[216:217], s[70:71], 0, v[128:129]
	s_add_i32 m0, s69, 0x2000
	s_nop 0
	global_load_lds_dwordx4 v[216:217], off
	v_lshl_add_u64 v[216:217], s[48:49], 0, v[130:131]
	s_mov_b32 m0, s53
	s_nop 0
	global_load_lds_dwordx4 v[216:217], off
	s_mov_b32 m0, s54
	s_nop 0
	global_load_lds_dwordx4 v[218:219], off
	s_waitcnt vmcnt(8)
	s_waitcnt lgkmcnt(0)
	s_barrier
	s_waitcnt lgkmcnt(0)
	v_mfma_f32_16x16x32_bf16 v[60:63], v[140:143], v[180:183], v[60:63]
	v_mfma_f32_16x16x32_bf16 v[56:59], v[156:159], v[180:183], v[56:59]
	v_mfma_f32_16x16x32_bf16 v[48:51], v[140:143], v[188:191], v[48:51]
	v_mfma_f32_16x16x32_bf16 v[40:43], v[156:159], v[188:191], v[40:43]
	v_mfma_f32_16x16x32_bf16 v[32:35], v[140:143], v[196:199], v[32:35]
	v_mfma_f32_16x16x32_bf16 v[24:27], v[156:159], v[196:199], v[24:27]
	v_mfma_f32_16x16x32_bf16 v[16:19], v[140:143], v[206:209], v[16:19]
	v_mfma_f32_16x16x32_bf16 v[8:11], v[156:159], v[206:209], v[8:11]
	v_mfma_f32_16x16x32_bf16 v[60:63], v[152:155], v[184:187], v[60:63]
	v_mfma_f32_16x16x32_bf16 v[56:59], v[160:163], v[184:187], v[56:59]
	v_mfma_f32_16x16x32_bf16 v[48:51], v[152:155], v[192:195], v[48:51]
	v_mfma_f32_16x16x32_bf16 v[40:43], v[160:163], v[192:195], v[40:43]
	v_mfma_f32_16x16x32_bf16 v[32:35], v[152:155], v[202:205], v[32:35]
	v_mfma_f32_16x16x32_bf16 v[24:27], v[160:163], v[202:205], v[24:27]
	v_mfma_f32_16x16x32_bf16 v[16:19], v[152:155], v[210:213], v[16:19]
	v_mfma_f32_16x16x32_bf16 v[8:11], v[160:163], v[210:213], v[8:11]
	v_mfma_f32_16x16x32_bf16 v[52:55], v[164:167], v[180:183], v[52:55]
	v_mfma_f32_16x16x32_bf16 v[44:47], v[172:175], v[180:183], v[44:47]
	v_mfma_f32_16x16x32_bf16 v[36:39], v[164:167], v[188:191], v[36:39]
	v_mfma_f32_16x16x32_bf16 v[28:31], v[172:175], v[188:191], v[28:31]
	v_mfma_f32_16x16x32_bf16 v[20:23], v[164:167], v[196:199], v[20:23]
	v_mfma_f32_16x16x32_bf16 v[12:15], v[172:175], v[196:199], v[12:15]
	v_mfma_f32_16x16x32_bf16 v[4:7], v[164:167], v[206:209], v[4:7]
	v_mfma_f32_16x16x32_bf16 v[0:3], v[172:175], v[206:209], v[0:3]
	v_mfma_f32_16x16x32_bf16 v[52:55], v[168:171], v[184:187], v[52:55]
	v_mfma_f32_16x16x32_bf16 v[44:47], v[176:179], v[184:187], v[44:47]
	v_mfma_f32_16x16x32_bf16 v[36:39], v[168:171], v[192:195], v[36:39]
	v_mfma_f32_16x16x32_bf16 v[28:31], v[176:179], v[192:195], v[28:31]
	v_mfma_f32_16x16x32_bf16 v[20:23], v[168:171], v[202:205], v[20:23]
	v_mfma_f32_16x16x32_bf16 v[12:15], v[176:179], v[202:205], v[12:15]
	v_mfma_f32_16x16x32_bf16 v[4:7], v[168:171], v[210:213], v[4:7]
	v_mfma_f32_16x16x32_bf16 v[0:3], v[176:179], v[210:213], v[0:3]
	s_barrier
	s_add_i32 s69, 0, 0x18000
	s_add_i32 s70, 0, 0x1c000
	v_add_u32_e32 v160, s69, v147
	v_add_u32_e32 v176, s70, v147
	ds_read_b128 v[140:143], v160
	ds_read_b128 v[152:155], v160 offset:1024
	ds_read_b128 v[156:159], v160 offset:2048
	ds_read_b128 v[160:163], v160 offset:3072
	ds_read_b128 v[164:167], v176
	ds_read_b128 v[168:171], v176 offset:1024
	ds_read_b128 v[172:175], v176 offset:2048
	ds_read_b128 v[176:179], v176 offset:3072
	s_add_u32 s48, s48, 0xb0000
	s_addc_u32 s49, s49, 0
	s_mov_b32 m0, s55
	v_lshl_add_u64 v[220:221], s[48:49], 0, v[130:131]
	ds_read_b128 v[180:183], v151 offset:32768
	ds_read_b128 v[184:187], v151 offset:33792
	ds_read_b128 v[188:191], v151 offset:34816
	ds_read_b128 v[192:195], v151 offset:35840
	ds_read_b128 v[196:199], v151 offset:36864
	ds_read_b128 v[202:205], v151 offset:37888
	ds_read_b128 v[206:209], v151 offset:38912
	ds_read_b128 v[210:213], v151 offset:39936
	global_load_lds_dwordx4 v[220:221], off
	v_lshl_add_u64 v[220:221], s[48:49], 0, v[128:129]
	s_mov_b32 m0, s56
	s_nop 0
	global_load_lds_dwordx4 v[220:221], off
	s_waitcnt vmcnt(8)
	s_waitcnt lgkmcnt(0)
	s_barrier
	s_waitcnt lgkmcnt(0)
	v_mfma_f32_16x16x32_bf16 v[124:127], v[140:143], v[180:183], v[124:127]
	v_mfma_f32_16x16x32_bf16 v[120:123], v[156:159], v[180:183], v[120:123]
	v_mfma_f32_16x16x32_bf16 v[112:115], v[140:143], v[188:191], v[112:115]
	v_mfma_f32_16x16x32_bf16 v[104:107], v[156:159], v[188:191], v[104:107]
	v_mfma_f32_16x16x32_bf16 v[96:99], v[140:143], v[196:199], v[96:99]
	v_mfma_f32_16x16x32_bf16 v[88:91], v[156:159], v[196:199], v[88:91]
	v_mfma_f32_16x16x32_bf16 v[80:83], v[140:143], v[206:209], v[80:83]
	v_mfma_f32_16x16x32_bf16 v[72:75], v[156:159], v[206:209], v[72:75]
	v_mfma_f32_16x16x32_bf16 v[124:127], v[152:155], v[184:187], v[124:127]
	v_mfma_f32_16x16x32_bf16 v[120:123], v[160:163], v[184:187], v[120:123]
	v_mfma_f32_16x16x32_bf16 v[112:115], v[152:155], v[192:195], v[112:115]
	v_mfma_f32_16x16x32_bf16 v[104:107], v[160:163], v[192:195], v[104:107]
	v_mfma_f32_16x16x32_bf16 v[96:99], v[152:155], v[202:205], v[96:99]
	v_mfma_f32_16x16x32_bf16 v[88:91], v[160:163], v[202:205], v[88:91]
	v_mfma_f32_16x16x32_bf16 v[80:83], v[152:155], v[210:213], v[80:83]
	v_mfma_f32_16x16x32_bf16 v[72:75], v[160:163], v[210:213], v[72:75]
	v_mfma_f32_16x16x32_bf16 v[116:119], v[164:167], v[180:183], v[116:119]
	v_mfma_f32_16x16x32_bf16 v[108:111], v[172:175], v[180:183], v[108:111]
	v_mfma_f32_16x16x32_bf16 v[100:103], v[164:167], v[188:191], v[100:103]
	v_mfma_f32_16x16x32_bf16 v[92:95], v[172:175], v[188:191], v[92:95]
	v_mfma_f32_16x16x32_bf16 v[84:87], v[164:167], v[196:199], v[84:87]
	v_mfma_f32_16x16x32_bf16 v[76:79], v[172:175], v[196:199], v[76:79]
	v_mfma_f32_16x16x32_bf16 v[68:71], v[164:167], v[206:209], v[68:71]
	v_mfma_f32_16x16x32_bf16 v[64:67], v[172:175], v[206:209], v[64:67]
	v_mfma_f32_16x16x32_bf16 v[116:119], v[168:171], v[184:187], v[116:119]
	v_mfma_f32_16x16x32_bf16 v[108:111], v[176:179], v[184:187], v[108:111]
	v_mfma_f32_16x16x32_bf16 v[100:103], v[168:171], v[192:195], v[100:103]
	v_mfma_f32_16x16x32_bf16 v[92:95], v[176:179], v[192:195], v[92:95]
	v_mfma_f32_16x16x32_bf16 v[84:87], v[168:171], v[202:205], v[84:87]
	v_mfma_f32_16x16x32_bf16 v[76:79], v[176:179], v[202:205], v[76:79]
	v_mfma_f32_16x16x32_bf16 v[68:71], v[168:171], v[210:213], v[68:71]
	v_mfma_f32_16x16x32_bf16 v[64:67], v[176:179], v[210:213], v[64:67]
	s_barrier
	s_add_i32 s48, s69, s52
	v_lshl_add_u64 v[144:145], v[144:145], 0, s[10:11]
	s_mov_b32 m0, s48
	ds_read_b128 v[180:183], v151 offset:49152
	ds_read_b128 v[184:187], v151 offset:50176
	ds_read_b128 v[188:191], v151 offset:51200
	ds_read_b128 v[192:195], v151 offset:52224
	ds_read_b128 v[196:199], v151 offset:53248
	ds_read_b128 v[202:205], v151 offset:54272
	ds_read_b128 v[206:209], v151 offset:55296
	ds_read_b128 v[210:213], v151 offset:56320
	global_load_lds_dwordx4 v[144:145], off
	s_add_i32 m0, s48, 0x2000
	s_add_u32 s46, s46, 0xb0080
	v_lshl_add_u64 v[144:145], v[214:215], 0, s[10:11]
	s_addc_u32 s47, s47, 0
	s_add_i32 s48, s70, s52
	global_load_lds_dwordx4 v[144:145], off
	v_lshl_add_u64 v[144:145], s[46:47], 0, v[130:131]
	s_mov_b32 m0, s48
	s_nop 0
	global_load_lds_dwordx4 v[144:145], off
	v_lshl_add_u64 v[144:145], s[46:47], 0, v[128:129]
	s_add_i32 m0, s48, 0x2000
	s_nop 0
	global_load_lds_dwordx4 v[144:145], off
	v_lshl_add_u64 v[144:145], v[216:217], 0, s[10:11]
	s_mov_b32 m0, s58
	s_nop 0
	global_load_lds_dwordx4 v[144:145], off
	v_lshl_add_u64 v[144:145], v[218:219], 0, s[10:11]
	s_mov_b32 m0, s59
	s_nop 0
	global_load_lds_dwordx4 v[144:145], off
	s_waitcnt vmcnt(8)
	s_waitcnt lgkmcnt(0)
	s_barrier
	s_waitcnt lgkmcnt(0)
	v_mfma_f32_16x16x32_bf16 v[60:63], v[140:143], v[180:183], v[60:63]
	v_mfma_f32_16x16x32_bf16 v[56:59], v[156:159], v[180:183], v[56:59]
	v_mfma_f32_16x16x32_bf16 v[48:51], v[140:143], v[188:191], v[48:51]
	v_mfma_f32_16x16x32_bf16 v[40:43], v[156:159], v[188:191], v[40:43]
	v_mfma_f32_16x16x32_bf16 v[32:35], v[140:143], v[196:199], v[32:35]
	v_mfma_f32_16x16x32_bf16 v[24:27], v[156:159], v[196:199], v[24:27]
	v_mfma_f32_16x16x32_bf16 v[16:19], v[140:143], v[206:209], v[16:19]
	v_mfma_f32_16x16x32_bf16 v[8:11], v[156:159], v[206:209], v[8:11]
	v_mfma_f32_16x16x32_bf16 v[60:63], v[152:155], v[184:187], v[60:63]
	v_mfma_f32_16x16x32_bf16 v[56:59], v[160:163], v[184:187], v[56:59]
	v_mfma_f32_16x16x32_bf16 v[48:51], v[152:155], v[192:195], v[48:51]
	v_mfma_f32_16x16x32_bf16 v[40:43], v[160:163], v[192:195], v[40:43]
	v_mfma_f32_16x16x32_bf16 v[32:35], v[152:155], v[202:205], v[32:35]
	v_mfma_f32_16x16x32_bf16 v[24:27], v[160:163], v[202:205], v[24:27]
	v_mfma_f32_16x16x32_bf16 v[16:19], v[152:155], v[210:213], v[16:19]
	v_mfma_f32_16x16x32_bf16 v[8:11], v[160:163], v[210:213], v[8:11]
	v_mfma_f32_16x16x32_bf16 v[52:55], v[164:167], v[180:183], v[52:55]
	v_mfma_f32_16x16x32_bf16 v[44:47], v[172:175], v[180:183], v[44:47]
	v_mfma_f32_16x16x32_bf16 v[36:39], v[164:167], v[188:191], v[36:39]
	v_mfma_f32_16x16x32_bf16 v[28:31], v[172:175], v[188:191], v[28:31]
	v_mfma_f32_16x16x32_bf16 v[20:23], v[164:167], v[196:199], v[20:23]
	v_mfma_f32_16x16x32_bf16 v[12:15], v[172:175], v[196:199], v[12:15]
	v_mfma_f32_16x16x32_bf16 v[4:7], v[164:167], v[206:209], v[4:7]
	v_mfma_f32_16x16x32_bf16 v[0:3], v[172:175], v[206:209], v[0:3]
	v_mfma_f32_16x16x32_bf16 v[52:55], v[168:171], v[184:187], v[52:55]
	v_mfma_f32_16x16x32_bf16 v[44:47], v[176:179], v[184:187], v[44:47]
	v_mfma_f32_16x16x32_bf16 v[36:39], v[168:171], v[192:195], v[36:39]
	v_mfma_f32_16x16x32_bf16 v[28:31], v[176:179], v[192:195], v[28:31]
	v_mfma_f32_16x16x32_bf16 v[20:23], v[168:171], v[202:205], v[20:23]
	v_mfma_f32_16x16x32_bf16 v[12:15], v[176:179], v[202:205], v[12:15]
	v_mfma_f32_16x16x32_bf16 v[4:7], v[168:171], v[210:213], v[4:7]
	v_mfma_f32_16x16x32_bf16 v[0:3], v[176:179], v[210:213], v[0:3]
	s_barrier
	s_add_i32 s68, s68, 2
	s_add_u32 s44, s44, 0x100
	s_addc_u32 s45, s45, 0
	s_add_u32 s66, s66, 0x100
	s_addc_u32 s67, s67, 0
	s_cmp_gt_u32 s68, 41
	s_cbranch_scc0 .LBB0_1704
	s_setprio 0
	s_and_b64 vcc, exec, s[12:13]
	s_cbranch_vccz .LBB0_1707
	s_barrier

	.amdhsa_kernel _Z9yoco_mega6Params
		.amdhsa_group_segment_fixed_size 0
		.amdhsa_private_segment_fixed_size 0
		.amdhsa_kernarg_size 472
		.amdhsa_user_sgpr_count 2
		.amdhsa_user_sgpr_dispatch_ptr 0
		.amdhsa_user_sgpr_queue_ptr 0
		.amdhsa_user_sgpr_kernarg_segment_ptr 1
		.amdhsa_user_sgpr_dispatch_id 0
		.amdhsa_user_sgpr_kernarg_preload_length 0
		.amdhsa_user_sgpr_kernarg_preload_offset 0
		.amdhsa_user_sgpr_private_segment_size 0
		.amdhsa_uses_dynamic_stack 0
		.amdhsa_enable_private_segment 0
		.amdhsa_system_sgpr_workgroup_id_x 1
		.amdhsa_system_sgpr_workgroup_id_y 0
		.amdhsa_system_sgpr_workgroup_id_z 0
		.amdhsa_system_sgpr_workgroup_info 0
		.amdhsa_system_vgpr_workitem_id 2
		.amdhsa_next_free_vgpr 255
		.amdhsa_next_free_sgpr 102
		.amdhsa_accum_offset 256
		.amdhsa_reserve_vcc 1
		.amdhsa_float_round_mode_32 0
		.amdhsa_float_round_mode_16_64 0
		.amdhsa_float_denorm_mode_32 3
		.amdhsa_float_denorm_mode_16_64 3
		.amdhsa_dx10_clamp 1
		.amdhsa_ieee_mode 1
		.amdhsa_fp16_overflow 0
		.amdhsa_tg_split 0
		.amdhsa_exception_fp_ieee_invalid_op 0
		.amdhsa_exception_fp_denorm_src 0
		.amdhsa_exception_fp_ieee_div_zero 0
		.amdhsa_exception_fp_ieee_overflow 0
		.amdhsa_exception_fp_ieee_underflow 0
		.amdhsa_exception_fp_ieee_inexact 0
		.amdhsa_exception_int_div_zero 0
	.end_amdhsa_kernel

amdhsa.kernels:
  - .agpr_count:     0
    .args:
      - .offset:         0
        .size:           216
        .value_kind:     by_value
      - .offset:         216
        .size:           4
        .value_kind:     hidden_block_count_x
      - .offset:         220
        .size:           4
        .value_kind:     hidden_block_count_y
      - .offset:         224
        .size:           4
        .value_kind:     hidden_block_count_z
      - .offset:         228
        .size:           2
        .value_kind:     hidden_group_size_x
      - .offset:         230
        .size:           2
        .value_kind:     hidden_group_size_y
      - .offset:         232
        .size:           2
        .value_kind:     hidden_group_size_z
      - .offset:         234
        .size:           2
        .value_kind:     hidden_remainder_x
      - .offset:         236
        .size:           2
        .value_kind:     hidden_remainder_y
      - .offset:         238
        .size:           2
        .value_kind:     hidden_remainder_z
      - .offset:         256
        .size:           8
        .value_kind:     hidden_global_offset_x
      - .offset:         264
        .size:           8
        .value_kind:     hidden_global_offset_y
      - .offset:         272
        .size:           8
        .value_kind:     hidden_global_offset_z
      - .offset:         280
        .size:           2
        .value_kind:     hidden_grid_dims
      - .offset:         304
        .size:           8
        .value_kind:     hidden_multigrid_sync_arg
      - .offset:         336
        .size:           4
        .value_kind:     hidden_dynamic_lds_size
    .group_segment_fixed_size: 0
    .kernarg_segment_align: 8
    .kernarg_segment_size: 472
    .language:       OpenCL C
    .language_version:
      - 2
      - 0
    .max_flat_workgroup_size: 512
    .name:           _Z9yoco_mega6Params
    .private_segment_fixed_size: 0
    .sgpr_count:     108
    .sgpr_spill_count: 5
    .symbol:         _Z9yoco_mega6Params.kd
    .uniform_work_group_size: 1
    .uses_dynamic_stack: false
    .vgpr_count:     255
    .vgpr_spill_count: 0
    .wavefront_size: 64
